# mixer prompt jobs: closing barrier moved behind the next job's first load block
# speedup vs baseline: 1.0045x; 1.0045x over previous
.LBB0_301:
	s_and_b64 vcc, exec, s[16:17]
	s_cbranch_vccz .LBB0_356
	s_mul_hi_i32 s16, s25, 0x2aaaaaab
	s_lshr_b32 s17, s16, 31
	s_ashr_i32 s16, s16, 4
	s_add_i32 s16, s16, s17
	s_mul_i32 s17, s16, 0x60
	s_sub_i32 s17, s25, s17
	s_mul_i32 s25, s17, 43
	s_sext_i32_i16 s26, s25
	s_ashr_i32 s26, s26, 9
	s_bfe_u32 s25, s25, 0x1000f
	s_add_i32 s25, s26, s25
	s_sext_i32_i16 s27, s25
	s_mul_i32 s25, s25, 12
	s_sub_i32 s17, s17, s25
	s_bfe_i32 s26, s17, 0x80000
	s_lshl_b32 s68, s27, 11
	s_lshl_b32 s16, s16, 7
	s_add_i32 s68, s68, s16
	s_sext_i32_i16 s16, s26
	s_sext_i32_i8 s25, s17
	s_cmp_gt_i32 s16, 3
	s_mov_b64 s[16:17], -1
	s_cbranch_scc0 .LBB0_342
	s_add_i32 s16, s25, -4
	s_lshl_b32 s27, s16, 7
	v_readlane_b32 s28, v253, 44
	v_mbcnt_lo_u32_b32 v101, -1, 0
	v_mbcnt_hi_u32_b32 v101, -1, v101
	s_add_i32 s17, s27, s28
	v_and_b32_e32 v105, 15, v101
	v_or_b32_e32 v160, s17, v105
	v_lshl_add_u64 v[0:1], v[160:161], 2, s[72:73]
	s_add_i32 s16, s16, s60
	v_add_co_u32_e32 v2, vcc, 0x1000, v0
	s_ashr_i32 s17, s16, 31
	s_nop 0
	v_addc_co_u32_e32 v3, vcc, 0, v1, vcc
	s_lshl_b64 s[16:17], s[16:17], 7
	v_lshlrev_b32_e32 v33, 3, v101
	global_load_dword v102, v[0:1], off
	global_load_dword v104, v[2:3], off
	v_add_co_u32_e32 v0, vcc, 0x2000, v0
	s_add_u32 s16, s16, s28
	v_and_b32_e32 v107, 0x78, v33
	v_addc_co_u32_e32 v1, vcc, 0, v1, vcc
	s_addc_u32 s17, s17, 0
	v_or_b32_e32 v60, s27, v107
	v_mov_b32_e32 v61, v161
	global_load_dword v100, v[0:1], off
	v_or_b32_e32 v0, s16, v105
	v_mov_b32_e32 v1, s17
	v_readlane_b32 s16, v253, 46
	v_lshlrev_b64 v[48:49], 2, v[60:61]
	v_lshlrev_b64 v[0:1], 8, v[0:1]
	v_readlane_b32 s17, v253, 47
	v_ashrrev_i32_e32 v103, 4, v101
	v_add_u32_e32 v32, s3, v101
	v_lshl_add_u64 v[50:51], s[30:31], 0, v[48:49]
	s_mov_b64 s[28:29], 0x1000
	v_lshl_add_u64 v[2:3], s[16:17], 0, v[0:1]
	v_lshlrev_b32_e32 v4, 3, v103
	v_readlane_b32 s16, v253, 48
	v_ashrrev_i32_e32 v106, 2, v32
	v_lshl_add_u64 v[32:33], v[50:51], 0, s[28:29]
	s_movk_i32 s28, 0x2000
	v_ashrrev_i32_e32 v5, 31, v4
	v_readlane_b32 s17, v253, 49
	v_add_co_u32_e32 v34, vcc, s28, v50
	s_mov_b64 s[28:29], 0x2000
	v_lshlrev_b64 v[4:5], 1, v[4:5]
	v_lshl_add_u64 v[0:1], s[16:17], 0, v[0:1]
	v_lshl_add_u64 v[36:37], v[50:51], 0, s[28:29]
	s_mov_b64 s[28:29], 0x3000
	v_lshl_add_u64 v[2:3], v[2:3], 0, v[4:5]
	v_lshl_add_u64 v[4:5], v[0:1], 0, v[4:5]
	v_addc_co_u32_e32 v35, vcc, 0, v51, vcc
	v_lshl_add_u64 v[52:53], v[50:51], 0, s[28:29]
	s_movk_i32 s28, 0x3000
	global_load_dwordx4 v[24:27], v[2:3], off
	global_load_dwordx4 v[28:31], v[4:5], off
	global_load_dwordx4 v[16:19], v[2:3], off offset:64
	global_load_dwordx4 v[20:23], v[4:5], off offset:64
	global_load_dwordx4 v[8:11], v[2:3], off offset:128
	global_load_dwordx4 v[12:15], v[4:5], off offset:128
	s_nop 0
	global_load_dwordx4 v[0:3], v[2:3], off offset:192
	s_nop 0
	global_load_dwordx4 v[4:7], v[4:5], off offset:192
	s_nop 0
	global_load_dwordx4 v[40:43], v[50:51], off offset:16
	global_load_dwordx4 v[44:47], v[50:51], off
	v_add_co_u32_e32 v50, vcc, s28, v50
	global_load_dwordx4 v[80:83], v[34:35], off offset:-4096
	global_load_dwordx4 v[68:71], v[32:33], off offset:16
	v_addc_co_u32_e32 v51, vcc, 0, v51, vcc
	global_load_dwordx4 v[32:35], v[34:35], off
	s_nop 0
	global_load_dwordx4 v[36:39], v[36:37], off offset:16
	s_nop 0
	global_load_dwordx4 v[64:67], v[50:51], off
	global_load_dwordx4 v[56:59], v[52:53], off offset:16
	v_lshl_add_u64 v[52:53], s[64:65], 0, v[48:49]
	global_load_dwordx4 v[48:51], v[52:53], off offset:16
	s_nop 0
	global_load_dwordx4 v[52:55], v[52:53], off
	s_ashr_i32 s16, s68, 31
	s_lshr_b32 s16, s16, 21
	s_add_i32 s27, s68, s16
	s_ashr_i32 s38, s27, 11
	s_ashr_i32 s39, s38, 31
	s_lshl_b64 s[16:17], s[38:39], 24
	s_add_u32 s16, s0, s16
	s_addc_u32 s17, s1, s17
	s_and_b32 s27, s27, 0xfffff800
	v_and_b32_e32 v108, -4, v106
	s_sub_i32 s27, s68, s27
	v_add_u32_e32 v109, s27, v108
	v_max_i32_e32 v61, 3, v109
	v_add_u32_e32 v62, -3, v61
	v_mov_b32_e32 v63, v161
	v_lshlrev_b64 v[62:63], 13, v[62:63]
	v_lshl_add_u64 v[62:63], s[16:17], 0, v[62:63]
	v_lshlrev_b32_e32 v60, 1, v60
	v_mov_b32_e32 v61, v161
	v_lshl_add_u64 v[62:63], v[62:63], 0, v[60:61]
	global_load_dwordx4 v[92:95], v[62:63], off offset:2048
	v_max_i32_e32 v62, 2, v109
	v_add_u32_e32 v62, -2, v62
	v_mov_b32_e32 v63, v161
	v_lshlrev_b64 v[62:63], 13, v[62:63]
	v_lshl_add_u64 v[62:63], s[16:17], 0, v[62:63]
	v_lshl_add_u64 v[62:63], v[62:63], 0, v[60:61]
	global_load_dwordx4 v[96:99], v[62:63], off offset:2048
	v_max_i32_e32 v62, 1, v109
	v_add_u32_e32 v62, -1, v62
	v_mov_b32_e32 v63, v161
	v_lshlrev_b64 v[62:63], 13, v[62:63]
	v_lshl_add_u64 v[62:63], s[16:17], 0, v[62:63]
	v_lshl_add_u64 v[62:63], v[62:63], 0, v[60:61]
	global_load_dwordx4 v[84:87], v[62:63], off offset:2048
	v_max_i32_e32 v62, 0, v109
	v_mov_b32_e32 v63, v161
	v_lshlrev_b64 v[62:63], 13, v[62:63]
	v_lshl_add_u64 v[62:63], s[16:17], 0, v[62:63]
	v_lshl_add_u64 v[62:63], v[62:63], 0, v[60:61]
	global_load_dwordx4 v[88:91], v[62:63], off offset:2048
	v_max_i32_e32 v62, -1, v109
	v_add_u32_e32 v62, 1, v62
	v_mov_b32_e32 v63, v161
	v_lshlrev_b64 v[62:63], 13, v[62:63]
	v_lshl_add_u64 v[62:63], s[16:17], 0, v[62:63]
	v_lshl_add_u64 v[62:63], v[62:63], 0, v[60:61]
	global_load_dwordx4 v[72:75], v[62:63], off offset:2048
	v_max_i32_e32 v62, -2, v109
	v_add_u32_e32 v62, 2, v62
	v_mov_b32_e32 v63, v161
	v_lshlrev_b64 v[62:63], 13, v[62:63]
	v_lshl_add_u64 v[62:63], s[16:17], 0, v[62:63]
	v_lshl_add_u64 v[62:63], v[62:63], 0, v[60:61]
	global_load_dwordx4 v[76:79], v[62:63], off offset:2048
	v_max_i32_e32 v62, -3, v109
	v_add_u32_e32 v62, 3, v62
	v_mov_b32_e32 v63, v161
	v_lshlrev_b64 v[62:63], 13, v[62:63]
	v_lshl_add_u64 v[62:63], s[16:17], 0, v[62:63]
	v_lshl_add_u64 v[60:61], v[62:63], 0, v[60:61]
	global_load_dwordx4 v[60:63], v[60:61], off offset:2048
	v_cmp_lt_i32_e32 vcc, 2, v109
	s_barrier
	s_waitcnt vmcnt(0)
	s_movk_i32 s28, 0x110
	v_cmp_gt_i32_e64 s[36:37], 2, v103
	v_cndmask_b32_e32 v120, 0, v95, vcc
	v_cndmask_b32_e32 v116, 0, v94, vcc
	v_cndmask_b32_e32 v112, 0, v93, vcc
	v_cndmask_b32_e32 v110, 0, v92, vcc
	v_cmp_lt_i32_e32 vcc, 1, v109
	v_lshlrev_b32_e32 v95, 16, v110
	v_lshlrev_b32_e32 v111, 16, v112
	v_cndmask_b32_e32 v118, 0, v98, vcc
	v_cndmask_b32_e32 v98, 0, v96, vcc
	v_cndmask_b32_e32 v114, 0, v97, vcc
	v_lshlrev_b32_e32 v94, 16, v98
	v_mov_b32_e32 v96, v80
	v_mov_b32_e32 v97, v44
	v_pk_mul_f32 v[92:93], v[96:97], v[94:95]
	v_cndmask_b32_e32 v122, 0, v99, vcc
	v_add_f32_e32 v44, v52, v93
	v_add_f32_e32 v95, v92, v44
	v_and_b32_e32 v99, 0xffff0000, v110
	v_and_b32_e32 v98, 0xffff0000, v98
	v_mov_b32_e32 v44, v81
	v_pk_mul_f32 v[80:81], v[44:45], v[98:99]
	v_lshlrev_b32_e32 v110, 16, v114
	v_add_f32_e32 v81, v53, v81
	v_mov_b32_e32 v92, v82
	v_mov_b32_e32 v93, v46
	v_add_f32_e32 v123, v80, v81
	v_pk_mul_f32 v[80:81], v[92:93], v[110:111]
	v_and_b32_e32 v113, 0xffff0000, v112
	v_add_f32_e32 v46, v54, v81
	v_add_f32_e32 v111, v80, v46
	v_and_b32_e32 v112, 0xffff0000, v114
	v_mov_b32_e32 v46, v83
	v_pk_mul_f32 v[80:81], v[46:47], v[112:113]
	v_lshlrev_b32_e32 v114, 16, v118
	v_add_f32_e32 v81, v55, v81
	v_lshlrev_b32_e32 v115, 16, v116
	v_mov_b32_e32 v82, v68
	v_mov_b32_e32 v83, v40
	v_add_f32_e32 v124, v80, v81
	v_pk_mul_f32 v[80:81], v[82:83], v[114:115]
	v_and_b32_e32 v117, 0xffff0000, v116
	v_add_f32_e32 v40, v48, v81
	v_add_f32_e32 v115, v80, v40
	v_and_b32_e32 v116, 0xffff0000, v118
	v_mov_b32_e32 v40, v69
	v_pk_mul_f32 v[68:69], v[40:41], v[116:117]
	v_lshlrev_b32_e32 v118, 16, v122
	v_add_f32_e32 v69, v49, v69
	v_lshlrev_b32_e32 v119, 16, v120
	v_mov_b32_e32 v80, v70
	v_mov_b32_e32 v81, v42
	v_add_f32_e32 v125, v68, v69
	v_pk_mul_f32 v[68:69], v[80:81], v[118:119]
	v_and_b32_e32 v121, 0xffff0000, v120
	v_add_f32_e32 v42, v50, v69
	v_add_f32_e32 v119, v68, v42
	v_and_b32_e32 v120, 0xffff0000, v122
	v_mov_b32_e32 v42, v71
	v_cmp_lt_i32_e32 vcc, 0, v109
	v_pk_mul_f32 v[68:69], v[42:43], v[120:121]
	v_cmp_gt_i32_e64 s[34:35], 1, v103
	v_cndmask_b32_e32 v126, 0, v87, vcc
	v_cndmask_b32_e32 v127, 0, v86, vcc
	v_cndmask_b32_e32 v128, 0, v85, vcc
	v_cndmask_b32_e32 v129, 0, v84, vcc
	v_cmp_lt_i32_e32 vcc, -1, v109
	v_add_f32_e32 v69, v51, v69
	v_add_f32_e32 v122, v68, v69
	v_cndmask_b32_e32 v88, 0, v88, vcc
	v_lshlrev_b32_e32 v71, 16, v129
	v_lshlrev_b32_e32 v70, 16, v88
	v_mov_b32_e32 v68, v64
	v_mov_b32_e32 v69, v32
	v_pk_mul_f32 v[84:85], v[68:69], v[70:71]
	v_pk_mov_b32 v[86:87], v[70:71], v[94:95] op_sel:[1,0]
	v_add_f32_e32 v32, v85, v95
	v_pk_mul_f32 v[86:87], v[96:97], v[86:87]
	v_add_f32_e32 v134, v84, v32
	v_add_f32_e32 v64, v52, v87
	v_and_b32_e32 v85, 0xffff0000, v129
	v_and_b32_e32 v84, 0xffff0000, v88
	v_add_f32_e32 v133, v86, v64
	v_mov_b32_e32 v32, v65
	v_pk_mov_b32 v[86:87], v[84:85], v[98:99] op_sel:[1,0]
	v_pk_mul_f32 v[64:65], v[32:33], v[84:85]
	v_pk_mul_f32 v[86:87], v[44:45], v[86:87]
	v_cndmask_b32_e32 v132, 0, v89, vcc
	v_add_f32_e32 v65, v65, v123
	v_add_f32_e32 v87, v53, v87
	v_add_f32_e32 v123, v86, v87
	v_add_f32_e32 v129, v64, v65
	v_lshlrev_b32_e32 v87, 16, v128
	v_lshlrev_b32_e32 v86, 16, v132
	v_mov_b32_e32 v64, v66
	v_mov_b32_e32 v65, v34
	v_cndmask_b32_e32 v130, 0, v91, vcc
	v_cndmask_b32_e32 v131, 0, v90, vcc
	v_pk_mul_f32 v[88:89], v[64:65], v[86:87]
	v_pk_mov_b32 v[90:91], v[86:87], v[110:111] op_sel:[1,0]
	v_add_f32_e32 v34, v89, v111
	v_pk_mul_f32 v[90:91], v[92:93], v[90:91]
	v_add_f32_e32 v136, v88, v34
	v_add_f32_e32 v66, v54, v91
	v_and_b32_e32 v89, 0xffff0000, v128
	v_and_b32_e32 v88, 0xffff0000, v132
	v_add_f32_e32 v135, v90, v66
	v_mov_b32_e32 v34, v67
	v_pk_mov_b32 v[90:91], v[88:89], v[112:113] op_sel:[1,0]
	v_pk_mul_f32 v[66:67], v[34:35], v[88:89]
	v_pk_mul_f32 v[90:91], v[46:47], v[90:91]
	v_add_f32_e32 v67, v67, v124
	v_add_f32_e32 v91, v55, v91
	v_add_f32_e32 v124, v90, v91
	v_add_f32_e32 v128, v66, v67
	v_lshlrev_b32_e32 v67, 16, v127
	v_lshlrev_b32_e32 v66, 16, v131
	v_mov_b32_e32 v90, v56
	v_mov_b32_e32 v91, v36
	v_pk_mul_f32 v[94:95], v[90:91], v[66:67]
	v_pk_mov_b32 v[98:99], v[66:67], v[114:115] op_sel:[1,0]
	v_add_f32_e32 v36, v95, v115
	v_pk_mul_f32 v[98:99], v[82:83], v[98:99]
	v_add_f32_e32 v115, v94, v36
	v_add_f32_e32 v56, v48, v99
	v_and_b32_e32 v95, 0xffff0000, v127
	v_and_b32_e32 v94, 0xffff0000, v131
	v_add_f32_e32 v114, v98, v56
	v_mov_b32_e32 v36, v57
	v_pk_mov_b32 v[98:99], v[94:95], v[116:117] op_sel:[1,0]
	v_pk_mul_f32 v[56:57], v[36:37], v[94:95]
	v_pk_mul_f32 v[98:99], v[40:41], v[98:99]
	v_add_f32_e32 v57, v57, v125
	v_add_f32_e32 v99, v49, v99
	v_add_f32_e32 v116, v98, v99
	v_add_f32_e32 v117, v56, v57
	v_lshlrev_b32_e32 v57, 16, v126
	v_lshlrev_b32_e32 v56, 16, v130
	v_mov_b32_e32 v98, v58
	v_mov_b32_e32 v99, v38
	v_pk_mul_f32 v[110:111], v[98:99], v[56:57]
	v_pk_mov_b32 v[112:113], v[56:57], v[118:119] op_sel:[1,0]
	v_add_f32_e32 v38, v111, v119
	v_pk_mul_f32 v[112:113], v[80:81], v[112:113]
	v_add_f32_e32 v119, v110, v38
	v_add_f32_e32 v58, v50, v113
	v_and_b32_e32 v111, 0xffff0000, v126
	v_and_b32_e32 v110, 0xffff0000, v130
	v_add_f32_e32 v118, v112, v58
	v_mov_b32_e32 v38, v59
	v_pk_mov_b32 v[112:113], v[110:111], v[120:121] op_sel:[1,0]
	v_pk_mul_f32 v[58:59], v[38:39], v[110:111]
	v_pk_mul_f32 v[112:113], v[42:43], v[112:113]
	v_add_f32_e32 v59, v59, v122
	v_add_f32_e32 v113, v51, v113
	v_add_f32_e32 v112, v112, v113
	v_add_f32_e32 v113, v58, v59
	v_pk_mul_f32 v[58:59], v[96:97], v[70:71]
	v_cmp_lt_i32_e32 vcc, -2, v109
	v_add_f32_e32 v59, v52, v59
	v_add_f32_e32 v120, v58, v59
	v_pk_mul_f32 v[58:59], v[44:45], v[84:85]
	v_cndmask_b32_e32 v132, 0, v75, vcc
	v_add_f32_e32 v59, v53, v59
	v_add_f32_e32 v121, v58, v59
	v_pk_mul_f32 v[58:59], v[92:93], v[86:87]
	v_cndmask_b32_e32 v137, 0, v74, vcc
	v_add_f32_e32 v59, v54, v59
	v_add_f32_e32 v122, v58, v59
	v_pk_mul_f32 v[58:59], v[46:47], v[88:89]
	v_cndmask_b32_e32 v138, 0, v73, vcc
	v_add_f32_e32 v59, v55, v59
	v_add_f32_e32 v125, v58, v59
	v_pk_mul_f32 v[58:59], v[82:83], v[66:67]
	v_cndmask_b32_e32 v74, 0, v72, vcc
	v_add_f32_e32 v59, v48, v59
	v_add_f32_e32 v126, v58, v59
	v_pk_mul_f32 v[58:59], v[40:41], v[94:95]
	v_cmp_lt_i32_e32 vcc, -3, v109
	v_add_f32_e32 v59, v49, v59
	v_add_f32_e32 v127, v58, v59
	v_pk_mul_f32 v[58:59], v[80:81], v[56:57]
	v_cndmask_b32_e32 v75, 0, v76, vcc
	v_add_f32_e32 v59, v50, v59
	v_add_f32_e32 v130, v58, v59
	v_pk_mul_f32 v[58:59], v[42:43], v[110:111]
	v_cndmask_b32_e32 v77, 0, v77, vcc
	v_add_f32_e32 v59, v51, v59
	v_add_f32_e32 v131, v58, v59
	v_lshlrev_b32_e32 v59, 16, v74
	v_lshlrev_b32_e32 v58, 16, v75
	v_pk_mov_b32 v[70:71], v[58:59], v[70:71] op_sel:[1,0]
	v_cndmask_b32_e32 v78, 0, v78, vcc
	v_pk_mul_f32 v[72:73], v[68:69], v[70:71]
	v_pk_mul_f32 v[70:71], v[96:97], v[70:71]
	v_add_f32_e32 v73, v73, v133
	v_add_f32_e32 v76, v72, v73
	v_pk_mul_f32 v[72:73], v[68:69], v[58:59]
	v_add_f32_e32 v52, v52, v71
	v_add_f32_e32 v59, v73, v120
	v_add_f32_e32 v96, v70, v52
	v_and_b32_e32 v71, 0xffff0000, v74
	v_and_b32_e32 v70, 0xffff0000, v75
	v_add_f32_e32 v59, v72, v59
	v_pk_mov_b32 v[72:73], v[70:71], v[84:85] op_sel:[1,0]
	v_cndmask_b32_e32 v79, 0, v79, vcc
	v_pk_mul_f32 v[74:75], v[32:33], v[72:73]
	v_pk_mul_f32 v[44:45], v[44:45], v[72:73]
	v_add_f32_e32 v52, v75, v123
	v_add_f32_e32 v84, v74, v52
	v_pk_mul_f32 v[74:75], v[32:33], v[70:71]
	v_add_f32_e32 v45, v53, v45
	v_add_f32_e32 v52, v75, v121
	v_add_f32_e32 v71, v44, v45
	v_lshlrev_b32_e32 v45, 16, v138
	v_lshlrev_b32_e32 v44, 16, v77
	v_add_f32_e32 v85, v74, v52
	v_pk_mov_b32 v[52:53], v[44:45], v[86:87] op_sel:[1,0]
	v_cmp_lt_i32_e32 vcc, -4, v109
	v_pk_mul_f32 v[72:73], v[64:65], v[52:53]
	v_pk_mul_f32 v[52:53], v[92:93], v[52:53]
	v_add_f32_e32 v73, v73, v135
	v_add_f32_e32 v86, v72, v73
	v_pk_mul_f32 v[72:73], v[64:65], v[44:45]
	v_add_f32_e32 v53, v54, v53
	v_add_f32_e32 v45, v73, v122
	v_add_f32_e32 v87, v52, v53
	v_and_b32_e32 v53, 0xffff0000, v138
	v_and_b32_e32 v52, 0xffff0000, v77
	v_add_f32_e32 v45, v72, v45
	v_pk_mov_b32 v[72:73], v[52:53], v[88:89] op_sel:[1,0]
	v_cndmask_b32_e32 v61, 0, v61, vcc
	v_pk_mul_f32 v[46:47], v[46:47], v[72:73]
	v_pk_mul_f32 v[74:75], v[34:35], v[72:73]
	v_add_f32_e32 v47, v55, v47
	v_add_f32_e32 v54, v75, v124
	v_add_f32_e32 v88, v46, v47
	v_lshlrev_b32_e32 v47, 16, v137
	v_lshlrev_b32_e32 v46, 16, v78
	v_add_f32_e32 v77, v74, v54
	v_pk_mov_b32 v[54:55], v[46:47], v[66:67] op_sel:[1,0]
	v_pk_mul_f32 v[74:75], v[34:35], v[52:53]
	v_pk_mul_f32 v[66:67], v[90:91], v[54:55]
	v_pk_mul_f32 v[54:55], v[82:83], v[54:55]
	v_add_f32_e32 v67, v67, v114
	v_add_f32_e32 v89, v66, v67
	v_pk_mul_f32 v[66:67], v[90:91], v[46:47]
	v_add_f32_e32 v48, v48, v55
	v_add_f32_e32 v47, v67, v126
	v_add_f32_e32 v82, v54, v48
	v_and_b32_e32 v55, 0xffff0000, v137
	v_and_b32_e32 v54, 0xffff0000, v78
	v_add_f32_e32 v47, v66, v47
	v_pk_mov_b32 v[66:67], v[54:55], v[94:95] op_sel:[1,0]
	v_add_f32_e32 v53, v75, v125
	v_pk_mul_f32 v[72:73], v[36:37], v[66:67]
	v_pk_mul_f32 v[40:41], v[40:41], v[66:67]
	v_add_f32_e32 v48, v73, v116
	v_add_f32_e32 v78, v72, v48
	v_pk_mul_f32 v[72:73], v[36:37], v[54:55]
	v_add_f32_e32 v41, v49, v41
	v_add_f32_e32 v48, v73, v127
	v_add_f32_e32 v55, v40, v41
	v_lshlrev_b32_e32 v41, 16, v132
	v_lshlrev_b32_e32 v40, 16, v79
	v_add_f32_e32 v83, v72, v48
	v_pk_mov_b32 v[48:49], v[40:41], v[56:57] op_sel:[1,0]
	v_add_f32_e32 v53, v74, v53
	v_pk_mul_f32 v[56:57], v[98:99], v[48:49]
	v_pk_mul_f32 v[48:49], v[80:81], v[48:49]
	v_add_f32_e32 v57, v57, v118
	v_add_f32_e32 v92, v56, v57
	v_pk_mul_f32 v[56:57], v[98:99], v[40:41]
	v_add_f32_e32 v49, v50, v49
	v_add_f32_e32 v41, v57, v130
	v_add_f32_e32 v80, v48, v49
	v_and_b32_e32 v49, 0xffff0000, v132
	v_and_b32_e32 v48, 0xffff0000, v79
	v_add_f32_e32 v41, v56, v41
	v_pk_mov_b32 v[56:57], v[48:49], v[110:111] op_sel:[1,0]
	v_mov_b32_e32 v75, v48
	v_pk_mul_f32 v[66:67], v[38:39], v[56:57]
	v_pk_mul_f32 v[42:43], v[42:43], v[56:57]
	v_add_f32_e32 v50, v67, v112
	v_add_f32_e32 v79, v66, v50
	v_pk_mul_f32 v[66:67], v[38:39], v[48:49]
	v_cndmask_b32_e32 v57, 0, v62, vcc
	v_add_f32_e32 v49, v67, v131
	v_add_f32_e32 v43, v51, v43
	v_add_f32_e32 v49, v66, v49
	v_cndmask_b32_e32 v51, 0, v63, vcc
	v_cndmask_b32_e32 v50, 0, v60, vcc
	v_and_b32_e32 v66, 0xffff0000, v57
	v_mov_b32_e32 v67, v54
	v_add_f32_e32 v43, v42, v43
	v_lshlrev_b32_e32 v42, 16, v50
	v_and_b32_e32 v50, 0xffff0000, v50
	v_lshlrev_b32_e32 v56, 16, v61
	v_and_b32_e32 v60, 0xffff0000, v61
	v_lshlrev_b32_e32 v72, 16, v51
	v_and_b32_e32 v74, 0xffff0000, v51
	v_pk_mul_f32 v[36:37], v[36:37], v[66:67]
	v_mov_b32_e32 v61, v52
	v_mov_b32_e32 v51, v70
	v_lshlrev_b32_e32 v62, 16, v57
	v_pk_mul_f32 v[38:39], v[38:39], v[74:75]
	v_add_f32_e32 v37, v37, v55
	v_mov_b32_e32 v63, v46
	v_pk_mul_f32 v[34:35], v[34:35], v[60:61]
	v_pk_mul_f32 v[32:33], v[32:33], v[50:51]
	v_add_f32_e32 v39, v39, v43
	v_mov_b32_e32 v73, v40
	v_add_f32_e32 v54, v36, v37
	v_pk_mul_f32 v[36:37], v[90:91], v[62:63]
	v_add_f32_e32 v35, v35, v88
	v_mov_b32_e32 v57, v44
	v_add_f32_e32 v33, v33, v71
	v_mov_b32_e32 v43, v58
	v_add_f32_e32 v48, v38, v39
	v_pk_mul_f32 v[38:39], v[98:99], v[72:73]
	v_add_f32_e32 v37, v37, v82
	v_add_f32_e32 v46, v34, v35
	v_pk_mul_f32 v[34:35], v[64:65], v[56:57]
	v_add_f32_e32 v50, v32, v33
	v_pk_mul_f32 v[32:33], v[68:69], v[42:43]
	v_add_f32_e32 v39, v39, v80
	v_add_f32_e32 v37, v36, v37
	v_add_f32_e32 v35, v35, v87
	v_add_f32_e32 v33, v33, v96
	v_lshl_add_u32 v36, v107, 1, 0
	v_add_f32_e32 v40, v38, v39
	v_add_f32_e32 v44, v34, v35
	v_add_f32_e32 v42, v32, v33
	v_cvt_pk_bf16_f32 v32, v134, v129
	v_cvt_pk_bf16_f32 v33, v136, v128
	v_cvt_pk_bf16_f32 v34, v115, v117
	v_mad_u64_u32 v[38:39], s[16:17], v108, s28, v[36:37]
	v_cvt_pk_bf16_f32 v35, v119, v113
	ds_write_b128 v38, v[32:35]
	v_cvt_pk_bf16_f32 v32, v76, v84
	v_cvt_pk_bf16_f32 v33, v86, v77
	v_cvt_pk_bf16_f32 v34, v89, v78
	v_cvt_pk_bf16_f32 v35, v92, v79
	ds_write_b128 v38, v[32:35] offset:272
	v_cvt_pk_bf16_f32 v32, v59, v85
	v_cvt_pk_bf16_f32 v33, v45, v53
	v_cvt_pk_bf16_f32 v34, v47, v83
	v_cvt_pk_bf16_f32 v35, v41, v49
	ds_write_b128 v38, v[32:35] offset:544
	v_cvt_pk_bf16_f32 v32, v42, v50
	v_cvt_pk_bf16_f32 v33, v44, v46
	v_cvt_pk_bf16_f32 v34, v37, v54
	v_or_b32_e32 v37, 3, v106
	v_mad_u64_u32 v[36:37], s[16:17], v37, s28, v[36:37]
	v_cvt_pk_bf16_f32 v35, v40, v48
	ds_write_b128 v36, v[32:35]
	v_and_b32_e32 v32, -16, v101
	v_mul_u32_u24_e32 v33, 0x110, v105
	v_add3_u32 v114, 0, v32, v33
	s_waitcnt lgkmcnt(0)
	s_barrier
	ds_read_b128 v[32:35], v114
	ds_read_b128 v[40:43], v114 offset:4352
	ds_read_b128 v[48:51], v114 offset:8704
	ds_read_b128 v[56:59], v114 offset:13056
	ds_read_b128 v[64:67], v114 offset:17408
	ds_read_b128 v[72:75], v114 offset:21760
	ds_read_b128 v[80:83], v114 offset:26112
	ds_read_b128 v[88:91], v114 offset:30464
	s_waitcnt lgkmcnt(7)
	v_mfma_f32_16x16x32_bf16 v[36:39], v[32:35], v[24:27], 0
	s_movk_i32 s16, 0x440
	v_mfma_f32_16x16x32_bf16 v[32:35], v[32:35], v[28:31], 0
	s_waitcnt lgkmcnt(6)
	v_mfma_f32_16x16x32_bf16 v[44:47], v[40:43], v[24:27], 0
	v_mfma_f32_16x16x32_bf16 v[40:43], v[40:43], v[28:31], 0
	s_waitcnt lgkmcnt(5)
	v_mfma_f32_16x16x32_bf16 v[52:55], v[48:51], v[24:27], 0
	v_mfma_f32_16x16x32_bf16 v[48:51], v[48:51], v[28:31], 0
	s_waitcnt lgkmcnt(4)
	v_mfma_f32_16x16x32_bf16 v[60:63], v[56:59], v[24:27], 0
	v_mfma_f32_16x16x32_bf16 v[56:59], v[56:59], v[28:31], 0
	s_waitcnt lgkmcnt(3)
	v_mfma_f32_16x16x32_bf16 v[68:71], v[64:67], v[24:27], 0
	v_mfma_f32_16x16x32_bf16 v[64:67], v[64:67], v[28:31], 0
	s_waitcnt lgkmcnt(2)
	v_mfma_f32_16x16x32_bf16 v[76:79], v[72:75], v[24:27], 0
	v_mfma_f32_16x16x32_bf16 v[72:75], v[72:75], v[28:31], 0
	s_waitcnt lgkmcnt(1)
	v_mfma_f32_16x16x32_bf16 v[84:87], v[80:83], v[24:27], 0
	v_mfma_f32_16x16x32_bf16 v[80:83], v[80:83], v[28:31], 0
	s_waitcnt lgkmcnt(0)
	v_mfma_f32_16x16x32_bf16 v[24:27], v[88:91], v[24:27], 0
	v_mfma_f32_16x16x32_bf16 v[28:31], v[88:91], v[28:31], 0
	ds_read_b128 v[88:91], v114 offset:64
	s_waitcnt lgkmcnt(0)
	v_mfma_f32_16x16x32_bf16 v[36:39], v[88:91], v[16:19], v[36:39]
	v_mfma_f32_16x16x32_bf16 v[32:35], v[88:91], v[20:23], v[32:35]
	ds_read_b128 v[88:91], v114 offset:4416
	s_waitcnt lgkmcnt(0)
	v_mfma_f32_16x16x32_bf16 v[44:47], v[88:91], v[16:19], v[44:47]
	v_mfma_f32_16x16x32_bf16 v[40:43], v[88:91], v[20:23], v[40:43]
	ds_read_b128 v[88:91], v114 offset:8768
	s_waitcnt lgkmcnt(0)
	v_mfma_f32_16x16x32_bf16 v[52:55], v[88:91], v[16:19], v[52:55]
	v_mfma_f32_16x16x32_bf16 v[48:51], v[88:91], v[20:23], v[48:51]
	ds_read_b128 v[88:91], v114 offset:13120
	s_waitcnt lgkmcnt(0)
	v_mfma_f32_16x16x32_bf16 v[60:63], v[88:91], v[16:19], v[60:63]
	v_mfma_f32_16x16x32_bf16 v[56:59], v[88:91], v[20:23], v[56:59]
	ds_read_b128 v[88:91], v114 offset:17472
	s_waitcnt lgkmcnt(0)
	v_mfma_f32_16x16x32_bf16 v[68:71], v[88:91], v[16:19], v[68:71]
	v_mfma_f32_16x16x32_bf16 v[64:67], v[88:91], v[20:23], v[64:67]
	ds_read_b128 v[88:91], v114 offset:21824
	s_waitcnt lgkmcnt(0)
	v_mfma_f32_16x16x32_bf16 v[76:79], v[88:91], v[16:19], v[76:79]
	v_mfma_f32_16x16x32_bf16 v[72:75], v[88:91], v[20:23], v[72:75]
	ds_read_b128 v[88:91], v114 offset:26176
	s_waitcnt lgkmcnt(0)
	v_mfma_f32_16x16x32_bf16 v[84:87], v[88:91], v[16:19], v[84:87]
	v_mfma_f32_16x16x32_bf16 v[80:83], v[88:91], v[20:23], v[80:83]
	ds_read_b128 v[88:91], v114 offset:30528
	s_waitcnt lgkmcnt(0)
	v_mfma_f32_16x16x32_bf16 v[16:19], v[88:91], v[16:19], v[24:27]
	s_nop 2
	ds_read_b128 v[24:27], v114 offset:128
	v_mfma_f32_16x16x32_bf16 v[20:23], v[88:91], v[20:23], v[28:31]
	s_waitcnt lgkmcnt(0)
	v_mfma_f32_16x16x32_bf16 v[28:31], v[24:27], v[8:11], v[36:39]
	v_mfma_f32_16x16x32_bf16 v[24:27], v[24:27], v[12:15], v[32:35]
	s_nop 2
	ds_read_b128 v[32:35], v114 offset:4480
	s_waitcnt lgkmcnt(0)
	v_mfma_f32_16x16x32_bf16 v[36:39], v[32:35], v[8:11], v[44:47]
	v_mfma_f32_16x16x32_bf16 v[32:35], v[32:35], v[12:15], v[40:43]
	s_nop 2
	ds_read_b128 v[40:43], v114 offset:8832
	s_waitcnt lgkmcnt(0)
	v_mfma_f32_16x16x32_bf16 v[44:47], v[40:43], v[8:11], v[52:55]
	v_mfma_f32_16x16x32_bf16 v[88:91], v[40:43], v[12:15], v[48:51]
	ds_read_b128 v[40:43], v114 offset:13184
	s_waitcnt lgkmcnt(0)
	v_mfma_f32_16x16x32_bf16 v[92:95], v[40:43], v[8:11], v[60:63]
	v_mfma_f32_16x16x32_bf16 v[96:99], v[40:43], v[12:15], v[56:59]
	ds_read_b128 v[40:43], v114 offset:17536
	s_waitcnt lgkmcnt(0)
	v_mfma_f32_16x16x32_bf16 v[68:71], v[40:43], v[8:11], v[68:71]
	v_mfma_f32_16x16x32_bf16 v[64:67], v[40:43], v[12:15], v[64:67]
	ds_read_b128 v[40:43], v114 offset:21888
	s_waitcnt lgkmcnt(0)
	v_mfma_f32_16x16x32_bf16 v[76:79], v[40:43], v[8:11], v[76:79]
	v_mfma_f32_16x16x32_bf16 v[72:75], v[40:43], v[12:15], v[72:75]
	ds_read_b128 v[40:43], v114 offset:26240
	s_waitcnt lgkmcnt(0)
	v_mfma_f32_16x16x32_bf16 v[84:87], v[40:43], v[8:11], v[84:87]
	v_mfma_f32_16x16x32_bf16 v[80:83], v[40:43], v[12:15], v[80:83]
	ds_read_b128 v[40:43], v114 offset:30592
	s_waitcnt lgkmcnt(0)
	v_mfma_f32_16x16x32_bf16 v[106:109], v[40:43], v[8:11], v[16:19]
	ds_read_b128 v[8:11], v114 offset:192
	v_mfma_f32_16x16x32_bf16 v[110:113], v[40:43], v[12:15], v[20:23]
	ds_read_b128 v[12:15], v114 offset:26304
	s_waitcnt lgkmcnt(1)
	v_mfma_f32_16x16x32_bf16 v[56:59], v[8:11], v[0:3], v[28:31]
	v_mfma_f32_16x16x32_bf16 v[60:63], v[8:11], v[4:7], v[24:27]
	ds_read_b128 v[8:11], v114 offset:4544
	s_nop 5
	v_pk_add_f32 v[56:57], v[102:103], v[56:57] op_sel_hi:[0,1]
	v_exp_f32_e32 v56, v56
	s_waitcnt lgkmcnt(0)
	v_mfma_f32_16x16x32_bf16 v[48:51], v[8:11], v[0:3], v[36:39]
	v_exp_f32_e32 v57, v57
	v_pk_add_f32 v[60:61], v[104:105], v[60:61] op_sel_hi:[0,1]
	v_pk_add_f32 v[58:59], v[102:103], v[58:59] op_sel_hi:[0,1]
	v_mfma_f32_16x16x32_bf16 v[52:55], v[8:11], v[4:7], v[32:35]
	ds_read_b128 v[8:11], v114 offset:8896
	v_pk_add_f32 v[56:57], v[56:57], 1.0 op_sel_hi:[1,0]
	v_exp_f32_e32 v60, v60
	s_waitcnt lgkmcnt(0)
	v_mfma_f32_16x16x32_bf16 v[40:43], v[8:11], v[0:3], v[44:47]
	v_rcp_f32_e32 v56, v56
	v_rcp_f32_e32 v57, v57
	v_exp_f32_e32 v61, v61
	v_mfma_f32_16x16x32_bf16 v[44:47], v[8:11], v[4:7], v[88:91]
	ds_read_b128 v[8:11], v114 offset:13248
	v_pk_mul_f32 v[56:57], v[100:101], v[56:57] op_sel_hi:[0,1]
	v_exp_f32_e32 v56, v56
	s_waitcnt lgkmcnt(0)
	v_mfma_f32_16x16x32_bf16 v[32:35], v[8:11], v[0:3], v[92:95]
	v_exp_f32_e32 v57, v57
	v_exp_f32_e32 v58, v58
	v_exp_f32_e32 v59, v59
	v_mfma_f32_16x16x32_bf16 v[36:39], v[8:11], v[4:7], v[96:99]
	ds_read_b128 v[8:11], v114 offset:17600
	v_pk_add_f32 v[60:61], v[60:61], 1.0 op_sel_hi:[1,0]
	v_pk_add_f32 v[62:63], v[104:105], v[62:63] op_sel_hi:[0,1]
	s_waitcnt lgkmcnt(0)
	v_mfma_f32_16x16x32_bf16 v[24:27], v[8:11], v[0:3], v[68:71]
	s_nop 2
	v_fma_f32 v68, -v56, v56, 1.0
	v_fma_f32 v69, -v57, v57, 1.0
	v_pk_add_f32 v[58:59], v[58:59], 1.0 op_sel_hi:[1,0]
	v_max_f32_e32 v68, 0x2b8cbccc, v68
	v_mfma_f32_16x16x32_bf16 v[28:31], v[8:11], v[4:7], v[64:67]
	ds_read_b128 v[8:11], v114 offset:21952
	v_rcp_f32_e32 v60, v60
	v_rcp_f32_e32 v61, v61
	ds_read_b128 v[64:67], v114 offset:30656
	s_waitcnt lgkmcnt(1)
	v_mfma_f32_16x16x32_bf16 v[16:19], v[8:11], v[0:3], v[76:79]
	v_sqrt_f32_e32 v68, v68
	v_max_f32_e32 v69, 0x2b8cbccc, v69
	v_exp_f32_e32 v62, v62
	v_mfma_f32_16x16x32_bf16 v[20:23], v[8:11], v[4:7], v[72:75]
	v_exp_f32_e32 v63, v63
	v_rcp_f32_e32 v58, v58
	v_rcp_f32_e32 v59, v59
	v_mfma_f32_16x16x32_bf16 v[8:11], v[12:15], v[0:3], v[84:87]
	v_add_f32_e64 v48, v102, v48
	v_add_f32_e64 v49, v102, v49
	v_sqrt_f32_e32 v69, v69
	v_exp_f32_e32 v48, v48
	v_mfma_f32_16x16x32_bf16 v[12:15], v[12:15], v[4:7], v[80:83]
	v_exp_f32_e32 v49, v49
	v_pk_add_f32 v[62:63], v[62:63], 1.0 op_sel_hi:[1,0]
	v_pk_mul_f32 v[58:59], v[100:101], v[58:59] op_sel_hi:[0,1]
	s_waitcnt lgkmcnt(0)
	v_mfma_f32_16x16x32_bf16 v[0:3], v[64:67], v[0:3], v[106:109]
	v_add_f32_e64 v48, v48, 1.0
	v_add_f32_e64 v49, v49, 1.0
	v_pk_add_f32 v[52:53], v[104:105], v[52:53] op_sel_hi:[0,1]
	v_rcp_f32_e32 v48, v48
	v_mfma_f32_16x16x32_bf16 v[4:7], v[64:67], v[4:7], v[110:113]
	v_lshlrev_b32_e32 v64, 2, v103
	v_sub_u32_e32 v67, 0, v64
	v_mul_lo_u32 v64, v103, s16
	v_lshlrev_b32_e32 v65, 1, v105
	v_readlane_b32 s16, v254, 52
	v_cmp_ne_u32_e32 vcc, s27, v67
	v_rcp_f32_e32 v49, v49
	v_add3_u32 v66, s16, v64, v65
	ds_read_u16 v64, v66
	ds_read_u16 v65, v66 offset:272
	v_cndmask_b32_e32 v68, 1.0, v68, vcc
	v_pk_mul_f32 v[48:49], v[100:101], v[48:49] op_sel_hi:[0,1]
	v_exp_f32_e32 v48, v48
	s_waitcnt lgkmcnt(1)
	v_lshlrev_b32_e32 v64, 16, v64
	s_waitcnt lgkmcnt(0)
	v_lshlrev_b32_e32 v65, 16, v65
	v_pk_mul_f32 v[60:61], v[60:61], v[64:65]
	ds_read_u16 v64, v66 offset:544
	ds_read_u16 v65, v66 offset:816
	v_pk_mul_f32 v[60:61], v[68:69], v[60:61]
	v_rcp_f32_e32 v68, v62
	v_rcp_f32_e32 v69, v63
	v_exp_f32_e32 v62, v58
	v_exp_f32_e32 v63, v59
	v_exp_f32_e32 v49, v49
	v_pk_add_f32 v[50:51], v[102:103], v[50:51] op_sel_hi:[0,1]
	v_exp_f32_e32 v52, v52
	v_pk_fma_f32 v[58:59], v[62:63], v[62:63], 1.0 op_sel_hi:[1,1,0] neg_lo:[1,0,0] neg_hi:[1,0,0]
	v_exp_f32_e32 v53, v53
	v_max_f32_e32 v58, 0x2b8cbccc, v58
	v_max_f32_e32 v59, 0x2b8cbccc, v59
	v_sqrt_f32_e32 v58, v58
	v_sqrt_f32_e32 v59, v59
	v_exp_f32_e32 v50, v50
	v_exp_f32_e32 v51, v51
	s_waitcnt lgkmcnt(1)
	v_lshlrev_b32_e32 v64, 16, v64
	s_waitcnt lgkmcnt(0)
	v_lshlrev_b32_e32 v65, 16, v65
	v_pk_mul_f32 v[64:65], v[68:69], v[64:65]
	v_pk_fma_f32 v[68:69], v[48:49], v[48:49], 1.0 op_sel_hi:[1,1,0] neg_lo:[1,0,0] neg_hi:[1,0,0]
	v_pk_mul_f32 v[58:59], v[58:59], v[64:65]
	ds_read_u16 v64, v66 offset:4352
	ds_read_u16 v65, v66 offset:4624
	v_pk_add_f32 v[52:53], v[52:53], 1.0 op_sel_hi:[1,0]
	v_max_f32_e32 v67, 0x2b8cbccc, v68
	v_pk_add_f32 v[54:55], v[104:105], v[54:55] op_sel_hi:[0,1]
	v_pk_add_f32 v[50:51], v[50:51], 1.0 op_sel_hi:[1,0]
	v_rcp_f32_e32 v52, v52
	v_rcp_f32_e32 v53, v53
	v_sqrt_f32_e32 v68, v67
	v_max_f32_e32 v67, 0x2b8cbccc, v69
	v_exp_f32_e32 v54, v54
	v_exp_f32_e32 v55, v55
	v_rcp_f32_e32 v50, v50
	v_rcp_f32_e32 v51, v51
	v_pk_add_f32 v[40:41], v[102:103], v[40:41] op_sel_hi:[0,1]
	v_sqrt_f32_e32 v69, v67
	v_exp_f32_e32 v40, v40
	v_exp_f32_e32 v41, v41
	s_waitcnt lgkmcnt(1)
	v_lshlrev_b32_e32 v64, 16, v64
	s_waitcnt lgkmcnt(0)
	v_lshlrev_b32_e32 v65, 16, v65
	v_pk_mul_f32 v[52:53], v[52:53], v[64:65]
	v_pk_add_f32 v[54:55], v[54:55], 1.0 op_sel_hi:[1,0]
	v_pk_mul_f32 v[50:51], v[100:101], v[50:51] op_sel_hi:[0,1]
	v_pk_mul_f32 v[52:53], v[68:69], v[52:53]
	v_rcp_f32_e32 v68, v54
	v_rcp_f32_e32 v69, v55
	v_exp_f32_e32 v54, v50
	v_exp_f32_e32 v55, v51
	v_pk_add_f32 v[40:41], v[40:41], 1.0 op_sel_hi:[1,0]
	ds_read_u16 v64, v66 offset:4896
	ds_read_u16 v65, v66 offset:5168
	v_rcp_f32_e32 v40, v40
	v_rcp_f32_e32 v41, v41
	v_pk_fma_f32 v[50:51], v[54:55], v[54:55], 1.0 op_sel_hi:[1,1,0] neg_lo:[1,0,0] neg_hi:[1,0,0]
	v_pk_add_f32 v[44:45], v[104:105], v[44:45] op_sel_hi:[0,1]
	v_max_f32_e32 v50, 0x2b8cbccc, v50
	v_max_f32_e32 v51, 0x2b8cbccc, v51
	v_pk_mul_f32 v[40:41], v[100:101], v[40:41] op_sel_hi:[0,1]
	v_sqrt_f32_e32 v50, v50
	v_sqrt_f32_e32 v51, v51
	v_exp_f32_e32 v40, v40
	v_exp_f32_e32 v41, v41
	v_pk_add_f32 v[42:43], v[102:103], v[42:43] op_sel_hi:[0,1]
	v_exp_f32_e32 v44, v44
	v_exp_f32_e32 v45, v45
	v_exp_f32_e32 v42, v42
	v_exp_f32_e32 v43, v43
	s_waitcnt lgkmcnt(1)
	v_lshlrev_b32_e32 v64, 16, v64
	s_waitcnt lgkmcnt(0)
	v_lshlrev_b32_e32 v65, 16, v65
	v_pk_mul_f32 v[64:65], v[68:69], v[64:65]
	v_pk_fma_f32 v[68:69], v[40:41], v[40:41], 1.0 op_sel_hi:[1,1,0] neg_lo:[1,0,0] neg_hi:[1,0,0]
	v_pk_mul_f32 v[50:51], v[50:51], v[64:65]
	ds_read_u16 v64, v66 offset:8704
	ds_read_u16 v65, v66 offset:8976
	v_pk_add_f32 v[44:45], v[44:45], 1.0 op_sel_hi:[1,0]
	v_max_f32_e32 v67, 0x2b8cbccc, v68
	v_pk_add_f32 v[46:47], v[104:105], v[46:47] op_sel_hi:[0,1]
	v_pk_add_f32 v[42:43], v[42:43], 1.0 op_sel_hi:[1,0]
	v_rcp_f32_e32 v44, v44
	v_rcp_f32_e32 v45, v45
	v_sqrt_f32_e32 v68, v67
	v_max_f32_e32 v67, 0x2b8cbccc, v69
	v_exp_f32_e32 v46, v46
	v_exp_f32_e32 v47, v47
	v_rcp_f32_e32 v42, v42
	v_rcp_f32_e32 v43, v43
	v_pk_add_f32 v[32:33], v[102:103], v[32:33] op_sel_hi:[0,1]
	v_sqrt_f32_e32 v69, v67
	v_exp_f32_e32 v32, v32
	v_exp_f32_e32 v33, v33
	s_waitcnt lgkmcnt(1)
	v_lshlrev_b32_e32 v64, 16, v64
	s_waitcnt lgkmcnt(0)
	v_lshlrev_b32_e32 v65, 16, v65
	v_pk_mul_f32 v[44:45], v[44:45], v[64:65]
	v_pk_add_f32 v[46:47], v[46:47], 1.0 op_sel_hi:[1,0]
	v_pk_mul_f32 v[42:43], v[100:101], v[42:43] op_sel_hi:[0,1]
	v_pk_mul_f32 v[44:45], v[68:69], v[44:45]
	v_rcp_f32_e32 v68, v46
	v_rcp_f32_e32 v69, v47
	v_exp_f32_e32 v46, v42
	v_exp_f32_e32 v47, v43
	v_pk_add_f32 v[32:33], v[32:33], 1.0 op_sel_hi:[1,0]
	ds_read_u16 v64, v66 offset:9248
	ds_read_u16 v65, v66 offset:9520
	v_rcp_f32_e32 v32, v32
	v_rcp_f32_e32 v33, v33
	v_pk_fma_f32 v[42:43], v[46:47], v[46:47], 1.0 op_sel_hi:[1,1,0] neg_lo:[1,0,0] neg_hi:[1,0,0]
	v_pk_add_f32 v[36:37], v[104:105], v[36:37] op_sel_hi:[0,1]
	v_max_f32_e32 v42, 0x2b8cbccc, v42
	v_max_f32_e32 v43, 0x2b8cbccc, v43
	v_pk_mul_f32 v[32:33], v[100:101], v[32:33] op_sel_hi:[0,1]
	v_sqrt_f32_e32 v42, v42
	v_sqrt_f32_e32 v43, v43
	v_exp_f32_e32 v32, v32
	v_exp_f32_e32 v33, v33
	v_pk_add_f32 v[34:35], v[102:103], v[34:35] op_sel_hi:[0,1]
	v_exp_f32_e32 v36, v36
	v_exp_f32_e32 v37, v37
	v_exp_f32_e32 v34, v34
	v_exp_f32_e32 v35, v35
	s_waitcnt lgkmcnt(1)
	v_lshlrev_b32_e32 v64, 16, v64
	s_waitcnt lgkmcnt(0)
	v_lshlrev_b32_e32 v65, 16, v65
	v_pk_mul_f32 v[64:65], v[68:69], v[64:65]
	v_pk_fma_f32 v[68:69], v[32:33], v[32:33], 1.0 op_sel_hi:[1,1,0] neg_lo:[1,0,0] neg_hi:[1,0,0]
	v_pk_mul_f32 v[42:43], v[42:43], v[64:65]
	ds_read_u16 v64, v66 offset:13056
	ds_read_u16 v65, v66 offset:13328
	v_pk_add_f32 v[36:37], v[36:37], 1.0 op_sel_hi:[1,0]
	v_max_f32_e32 v67, 0x2b8cbccc, v68
	v_pk_add_f32 v[38:39], v[104:105], v[38:39] op_sel_hi:[0,1]
	v_pk_add_f32 v[34:35], v[34:35], 1.0 op_sel_hi:[1,0]
	v_rcp_f32_e32 v36, v36
	v_rcp_f32_e32 v37, v37
	v_sqrt_f32_e32 v68, v67
	v_max_f32_e32 v67, 0x2b8cbccc, v69
	v_exp_f32_e32 v38, v38
	v_exp_f32_e32 v39, v39
	v_rcp_f32_e32 v34, v34
	v_rcp_f32_e32 v35, v35
	v_pk_add_f32 v[24:25], v[102:103], v[24:25] op_sel_hi:[0,1]
	v_sqrt_f32_e32 v69, v67
	v_exp_f32_e32 v24, v24
	v_exp_f32_e32 v25, v25
	s_waitcnt lgkmcnt(1)
	v_lshlrev_b32_e32 v64, 16, v64
	s_waitcnt lgkmcnt(0)
	v_lshlrev_b32_e32 v65, 16, v65
	v_pk_mul_f32 v[36:37], v[36:37], v[64:65]
	v_pk_add_f32 v[38:39], v[38:39], 1.0 op_sel_hi:[1,0]
	v_pk_mul_f32 v[34:35], v[100:101], v[34:35] op_sel_hi:[0,1]
	v_pk_mul_f32 v[36:37], v[68:69], v[36:37]
	v_rcp_f32_e32 v68, v38
	v_rcp_f32_e32 v69, v39
	v_exp_f32_e32 v38, v34
	v_exp_f32_e32 v39, v35
	v_pk_add_f32 v[24:25], v[24:25], 1.0 op_sel_hi:[1,0]
	ds_read_u16 v64, v66 offset:13600
	ds_read_u16 v65, v66 offset:13872
	v_rcp_f32_e32 v24, v24
	v_rcp_f32_e32 v25, v25
	v_pk_fma_f32 v[34:35], v[38:39], v[38:39], 1.0 op_sel_hi:[1,1,0] neg_lo:[1,0,0] neg_hi:[1,0,0]
	v_pk_add_f32 v[28:29], v[104:105], v[28:29] op_sel_hi:[0,1]
	v_max_f32_e32 v34, 0x2b8cbccc, v34
	v_max_f32_e32 v35, 0x2b8cbccc, v35
	v_pk_mul_f32 v[24:25], v[100:101], v[24:25] op_sel_hi:[0,1]
	v_sqrt_f32_e32 v34, v34
	v_sqrt_f32_e32 v35, v35
	v_exp_f32_e32 v24, v24
	v_exp_f32_e32 v25, v25
	v_pk_add_f32 v[26:27], v[102:103], v[26:27] op_sel_hi:[0,1]
	v_exp_f32_e32 v28, v28
	v_exp_f32_e32 v29, v29
	v_exp_f32_e32 v26, v26
	v_exp_f32_e32 v27, v27
	s_waitcnt lgkmcnt(1)
	v_lshlrev_b32_e32 v64, 16, v64
	s_waitcnt lgkmcnt(0)
	v_lshlrev_b32_e32 v65, 16, v65
	v_pk_mul_f32 v[64:65], v[68:69], v[64:65]
	v_pk_fma_f32 v[68:69], v[24:25], v[24:25], 1.0 op_sel_hi:[1,1,0] neg_lo:[1,0,0] neg_hi:[1,0,0]
	v_pk_mul_f32 v[34:35], v[34:35], v[64:65]
	ds_read_u16 v64, v66 offset:17408
	ds_read_u16 v65, v66 offset:17680
	v_pk_add_f32 v[28:29], v[28:29], 1.0 op_sel_hi:[1,0]
	v_max_f32_e32 v67, 0x2b8cbccc, v68
	v_pk_add_f32 v[30:31], v[104:105], v[30:31] op_sel_hi:[0,1]
	v_pk_add_f32 v[26:27], v[26:27], 1.0 op_sel_hi:[1,0]
	v_rcp_f32_e32 v28, v28
	v_rcp_f32_e32 v29, v29
	v_sqrt_f32_e32 v68, v67
	v_max_f32_e32 v67, 0x2b8cbccc, v69
	v_exp_f32_e32 v30, v30
	v_exp_f32_e32 v31, v31
	v_rcp_f32_e32 v26, v26
	v_rcp_f32_e32 v27, v27
	v_sqrt_f32_e32 v69, v67
	s_waitcnt lgkmcnt(1)
	v_lshlrev_b32_e32 v64, 16, v64
	s_waitcnt lgkmcnt(0)
	v_lshlrev_b32_e32 v65, 16, v65
	v_pk_mul_f32 v[28:29], v[28:29], v[64:65]
	v_pk_add_f32 v[30:31], v[30:31], 1.0 op_sel_hi:[1,0]
	v_pk_mul_f32 v[26:27], v[100:101], v[26:27] op_sel_hi:[0,1]
	v_pk_mul_f32 v[28:29], v[68:69], v[28:29]
	v_rcp_f32_e32 v68, v30
	v_rcp_f32_e32 v69, v31
	v_exp_f32_e32 v30, v26
	v_exp_f32_e32 v31, v27
	v_pk_add_f32 v[18:19], v[102:103], v[18:19] op_sel_hi:[0,1]
	ds_read_u16 v64, v66 offset:17952
	ds_read_u16 v65, v66 offset:18224
	v_exp_f32_e32 v18, v18
	v_exp_f32_e32 v19, v19
	v_pk_fma_f32 v[26:27], v[30:31], v[30:31], 1.0 op_sel_hi:[1,1,0] neg_lo:[1,0,0] neg_hi:[1,0,0]
	v_pk_add_f32 v[20:21], v[104:105], v[20:21] op_sel_hi:[0,1]
	v_max_f32_e32 v26, 0x2b8cbccc, v26
	v_max_f32_e32 v27, 0x2b8cbccc, v27
	v_sqrt_f32_e32 v26, v26
	v_sqrt_f32_e32 v27, v27
	v_exp_f32_e32 v20, v20
	v_exp_f32_e32 v21, v21
	v_pk_add_f32 v[18:19], v[18:19], 1.0 op_sel_hi:[1,0]
	s_waitcnt lgkmcnt(1)
	v_lshlrev_b32_e32 v64, 16, v64
	s_waitcnt lgkmcnt(0)
	v_lshlrev_b32_e32 v65, 16, v65
	v_rcp_f32_e32 v18, v18
	v_rcp_f32_e32 v19, v19
	v_pk_mul_f32 v[64:65], v[68:69], v[64:65]
	v_pk_add_f32 v[20:21], v[20:21], 1.0 op_sel_hi:[1,0]
	v_pk_mul_f32 v[26:27], v[26:27], v[64:65]
	ds_read_u16 v64, v66 offset:21760
	ds_read_u16 v65, v66 offset:22032
	v_rcp_f32_e32 v20, v20
	v_rcp_f32_e32 v21, v21
	v_pk_add_f32 v[22:23], v[104:105], v[22:23] op_sel_hi:[0,1]
	v_pk_mul_f32 v[18:19], v[100:101], v[18:19] op_sel_hi:[0,1]
	v_exp_f32_e32 v22, v22
	v_exp_f32_e32 v23, v23
	v_exp_f32_e32 v126, v18
	v_exp_f32_e32 v127, v19
	s_waitcnt lgkmcnt(1)
	v_lshlrev_b32_e32 v64, 16, v64
	s_waitcnt lgkmcnt(0)
	v_lshlrev_b32_e32 v65, 16, v65
	v_pk_add_f32 v[10:11], v[102:103], v[10:11] op_sel_hi:[0,1]
	v_pk_mul_f32 v[20:21], v[20:21], v[64:65]
	ds_read_u16 v64, v66 offset:22304
	ds_read_u16 v65, v66 offset:22576
	v_exp_f32_e32 v10, v10
	v_exp_f32_e32 v11, v11
	v_pk_add_f32 v[22:23], v[22:23], 1.0 op_sel_hi:[1,0]
	v_pk_fma_f32 v[18:19], v[126:127], v[126:127], 1.0 op_sel_hi:[1,1,0] neg_lo:[1,0,0] neg_hi:[1,0,0]
	v_rcp_f32_e32 v22, v22
	v_rcp_f32_e32 v23, v23
	v_max_f32_e32 v18, 0x2b8cbccc, v18
	v_max_f32_e32 v19, 0x2b8cbccc, v19
	v_sqrt_f32_e32 v18, v18
	v_sqrt_f32_e32 v19, v19
	v_pk_add_f32 v[12:13], v[104:105], v[12:13] op_sel_hi:[0,1]
	v_exp_f32_e32 v12, v12
	v_exp_f32_e32 v13, v13
	v_pk_add_f32 v[10:11], v[10:11], 1.0 op_sel_hi:[1,0]
	s_waitcnt lgkmcnt(1)
	v_lshlrev_b32_e32 v64, 16, v64
	s_waitcnt lgkmcnt(0)
	v_lshlrev_b32_e32 v65, 16, v65
	v_rcp_f32_e32 v10, v10
	v_rcp_f32_e32 v11, v11
	v_pk_mul_f32 v[22:23], v[22:23], v[64:65]
	v_pk_add_f32 v[12:13], v[12:13], 1.0 op_sel_hi:[1,0]
	v_pk_mul_f32 v[18:19], v[18:19], v[22:23]
	ds_read_u16 v22, v66 offset:26112
	ds_read_u16 v23, v66 offset:26384
	v_rcp_f32_e32 v12, v12
	v_rcp_f32_e32 v13, v13
	v_pk_add_f32 v[14:15], v[104:105], v[14:15] op_sel_hi:[0,1]
	v_pk_mul_f32 v[10:11], v[100:101], v[10:11] op_sel_hi:[0,1]
	v_exp_f32_e32 v14, v14
	v_exp_f32_e32 v15, v15
	v_exp_f32_e32 v128, v10
	v_exp_f32_e32 v129, v11
	s_waitcnt lgkmcnt(1)
	v_lshlrev_b32_e32 v22, 16, v22
	s_waitcnt lgkmcnt(0)
	v_lshlrev_b32_e32 v23, 16, v23
	v_pk_add_f32 v[2:3], v[102:103], v[2:3] op_sel_hi:[0,1]
	v_pk_add_f32 v[16:17], v[102:103], v[16:17] op_sel_hi:[0,1]
	v_pk_mul_f32 v[12:13], v[12:13], v[22:23]
	ds_read_u16 v22, v66 offset:26656
	ds_read_u16 v23, v66 offset:26928
	v_exp_f32_e32 v2, v2
	v_exp_f32_e32 v3, v3
	v_exp_f32_e32 v16, v16
	v_exp_f32_e32 v17, v17
	v_pk_add_f32 v[8:9], v[102:103], v[8:9] op_sel_hi:[0,1]
	v_pk_add_f32 v[14:15], v[14:15], 1.0 op_sel_hi:[1,0]
	v_pk_fma_f32 v[10:11], v[128:129], v[128:129], 1.0 op_sel_hi:[1,1,0] neg_lo:[1,0,0] neg_hi:[1,0,0]
	v_pk_add_f32 v[0:1], v[102:103], v[0:1] op_sel_hi:[0,1]
	v_exp_f32_e32 v8, v8
	v_exp_f32_e32 v9, v9
	v_rcp_f32_e32 v14, v14
	v_rcp_f32_e32 v15, v15
	v_max_f32_e32 v10, 0x2b8cbccc, v10
	v_max_f32_e32 v11, 0x2b8cbccc, v11
	v_exp_f32_e32 v0, v0
	v_exp_f32_e32 v1, v1
	v_sqrt_f32_e32 v10, v10
	v_sqrt_f32_e32 v11, v11
	v_pk_add_f32 v[4:5], v[104:105], v[4:5] op_sel_hi:[0,1]
	v_exp_f32_e32 v4, v4
	v_exp_f32_e32 v5, v5
	v_pk_add_f32 v[2:3], v[2:3], 1.0 op_sel_hi:[1,0]
	v_pk_add_f32 v[16:17], v[16:17], 1.0 op_sel_hi:[1,0]
	s_waitcnt lgkmcnt(1)
	v_lshlrev_b32_e32 v22, 16, v22
	s_waitcnt lgkmcnt(0)
	v_lshlrev_b32_e32 v23, 16, v23
	v_rcp_f32_e32 v2, v2
	v_rcp_f32_e32 v3, v3
	v_rcp_f32_e32 v16, v16
	v_rcp_f32_e32 v17, v17
	v_pk_add_f32 v[8:9], v[8:9], 1.0 op_sel_hi:[1,0]
	v_pk_mul_f32 v[14:15], v[14:15], v[22:23]
	v_pk_add_f32 v[0:1], v[0:1], 1.0 op_sel_hi:[1,0]
	v_rcp_f32_e32 v8, v8
	v_rcp_f32_e32 v9, v9
	v_pk_mul_f32 v[10:11], v[10:11], v[14:15]
	ds_read_u16 v14, v66 offset:30464
	ds_read_u16 v15, v66 offset:30736
	v_rcp_f32_e32 v0, v0
	v_rcp_f32_e32 v1, v1
	v_pk_add_f32 v[4:5], v[4:5], 1.0 op_sel_hi:[1,0]
	v_pk_add_f32 v[6:7], v[104:105], v[6:7] op_sel_hi:[0,1]
	v_rcp_f32_e32 v4, v4
	v_rcp_f32_e32 v5, v5
	v_pk_mul_f32 v[2:3], v[100:101], v[2:3] op_sel_hi:[0,1]
	v_pk_mul_f32 v[16:17], v[100:101], v[16:17] op_sel_hi:[0,1]
	v_exp_f32_e32 v6, v6
	v_exp_f32_e32 v7, v7
	v_exp_f32_e32 v136, v2
	v_exp_f32_e32 v137, v3
	v_exp_f32_e32 v16, v16
	v_exp_f32_e32 v17, v17
	v_pk_mul_f32 v[8:9], v[100:101], v[8:9] op_sel_hi:[0,1]
	v_pk_mul_f32 v[0:1], v[100:101], v[0:1] op_sel_hi:[0,1]
	v_exp_f32_e32 v8, v8
	v_exp_f32_e32 v9, v9
	s_waitcnt lgkmcnt(1)
	v_lshlrev_b32_e32 v14, 16, v14
	s_waitcnt lgkmcnt(0)
	v_lshlrev_b32_e32 v15, 16, v15
	v_exp_f32_e32 v0, v0
	v_exp_f32_e32 v1, v1
	v_pk_mul_f32 v[4:5], v[4:5], v[14:15]
	ds_read_u16 v14, v66 offset:31008
	ds_read_u16 v15, v66 offset:31280
	v_pk_add_f32 v[6:7], v[6:7], 1.0 op_sel_hi:[1,0]
	v_pk_fma_f32 v[2:3], v[136:137], v[136:137], 1.0 op_sel_hi:[1,1,0] neg_lo:[1,0,0] neg_hi:[1,0,0]
	v_pk_fma_f32 v[68:69], v[16:17], v[16:17], 1.0 op_sel_hi:[1,1,0] neg_lo:[1,0,0] neg_hi:[1,0,0]
	v_rcp_f32_e32 v6, v6
	v_rcp_f32_e32 v7, v7
	v_max_f32_e32 v2, 0x2b8cbccc, v2
	v_max_f32_e32 v3, 0x2b8cbccc, v3
	v_max_f32_e32 v67, 0x2b8cbccc, v68
	v_pk_fma_f32 v[64:65], v[8:9], v[8:9], 1.0 op_sel_hi:[1,1,0] neg_lo:[1,0,0] neg_hi:[1,0,0]
	v_pk_fma_f32 v[22:23], v[0:1], v[0:1], 1.0 op_sel_hi:[1,1,0] neg_lo:[1,0,0] neg_hi:[1,0,0]
	v_sqrt_f32_e32 v2, v2
	v_sqrt_f32_e32 v3, v3
	v_sqrt_f32_e32 v68, v67
	v_max_f32_e32 v67, 0x2b8cbccc, v69
	v_max_f32_e32 v64, 0x2b8cbccc, v64
	v_max_f32_e32 v65, 0x2b8cbccc, v65
	v_max_f32_e32 v22, 0x2b8cbccc, v22
	v_max_f32_e32 v23, 0x2b8cbccc, v23
	v_sqrt_f32_e32 v69, v67
	v_sqrt_f32_e32 v64, v64
	v_sqrt_f32_e32 v65, v65
	v_sqrt_f32_e32 v22, v22
	v_sqrt_f32_e32 v23, v23
	s_waitcnt lgkmcnt(1)
	v_lshlrev_b32_e32 v14, 16, v14
	s_waitcnt lgkmcnt(0)
	v_lshlrev_b32_e32 v15, 16, v15
	v_pk_mul_f32 v[6:7], v[6:7], v[14:15]
	s_lshl_b32 s16, s68, 12
	v_pk_mul_f32 v[2:3], v[2:3], v[6:7]
	v_lshl_add_u32 v6, v103, 14, s16
	v_add_lshl_u32 v6, v160, v6, 1
	v_lshlrev_b32_e32 v67, 2, v101
	v_fma_f32 v60, 0, v56, v60
	v_pk_mul_f32 v[20:21], v[68:69], v[20:21]
	v_pk_mul_f32 v[12:13], v[64:65], v[12:13]
	v_pk_mul_f32 v[4:5], v[22:23], v[4:5]
	v_add_u32_e32 v14, 0x1800, v6
	v_add_u32_e32 v22, 0x3800, v6
	v_add_u32_e32 v64, 0x5800, v6
	v_add_u32_e32 v66, 0x7800, v6
	v_add_u32_e32 v68, 0x21800, v6
	v_add_u32_e32 v70, 0x23800, v6
	v_add_u32_e32 v72, 0x25800, v6
	v_add_u32_e32 v74, 0x27800, v6
	v_add_u32_e32 v76, 0x41800, v6
	v_add_u32_e32 v78, 0x43800, v6
	v_add_u32_e32 v80, 0x45800, v6
	v_add_u32_e32 v82, 0x47800, v6
	v_add_u32_e32 v84, 0x61800, v6
	v_add_u32_e32 v86, 0x63800, v6
	v_add_u32_e32 v88, 0x65800, v6
	v_add_u32_e32 v90, 0x67800, v6
	v_add_u32_e32 v92, 0x81800, v6
	v_add_u32_e32 v94, 0x83800, v6
	v_add_u32_e32 v96, 0x85800, v6
	v_add_u32_e32 v98, 0x87800, v6
	v_add_u32_e32 v102, 0xa1800, v6
	v_add_u32_e32 v104, 0xa3800, v6
	v_add_u32_e32 v106, 0xa5800, v6
	v_add_u32_e32 v108, 0xa7800, v6
	v_add_u32_e32 v110, 0xc1800, v6
	v_add_u32_e32 v112, 0xc3800, v6
	v_add_u32_e32 v114, 0xc5800, v6
	v_add_u32_e32 v116, 0xc7800, v6
	v_add_u32_e32 v118, 0xe1800, v6
	v_add_u32_e32 v120, 0xe3800, v6
	v_add_u32_e32 v122, 0xe5800, v6
	v_add_u32_e32 v124, 0xe7800, v6
	v_add_u32_e32 v6, 64, v67
	v_fmac_f32_e32 v61, v57, v60
	v_mul_f32_e32 v57, v56, v57
	v_and_b32_e32 v23, 0xfc, v6
	v_fma_f32 v58, v62, v61, v58
	v_mul_f32_e32 v6, v62, v57
	v_fmac_f32_e32 v59, v63, v58
	v_mul_f32_e32 v7, v63, v6
	ds_bpermute_b32 v62, v23, v7
	ds_bpermute_b32 v63, v23, v59
	s_movk_i32 s16, 0x80
	v_bfrev_b32_e32 v65, 0.5
	v_bitop3_b32 v65, v67, s16, v65 bitop3:0x6c
	ds_bpermute_b32 v69, v65, v7
	ds_bpermute_b32 v71, v65, v59
	v_cmp_gt_i32_e32 vcc, 3, v103
	s_waitcnt lgkmcnt(2)
	v_fmac_f32_e32 v63, 0, v62
	v_add_u32_e32 v67, 0xc0, v67
	v_cndmask_b32_e64 v63, v63, 0, vcc
	v_cndmask_b32_e64 v62, v62, 1.0, vcc
	s_waitcnt lgkmcnt(0)
	v_fmac_f32_e32 v71, v63, v69
	v_and_b32_e32 v67, 0xfc, v67
	v_mul_f32_e32 v62, v62, v69
	v_cndmask_b32_e64 v63, v71, 0, s[36:37]
	ds_bpermute_b32 v69, v67, v7
	ds_bpermute_b32 v71, v67, v59
	v_cndmask_b32_e64 v62, v62, 1.0, s[36:37]
	v_fma_f32 v52, 0, v48, v52
	v_fmac_f32_e32 v53, v49, v52
	s_waitcnt lgkmcnt(1)
	v_mul_f32_e32 v62, v62, v69
	s_waitcnt lgkmcnt(0)
	v_fmac_f32_e32 v71, v63, v69
	v_mul_f32_e32 v49, v48, v49
	v_cndmask_b32_e64 v100, v62, 1.0, s[34:35]
	v_cndmask_b32_e64 v62, v71, 0, s[34:35]
	v_fma_f32 v50, v54, v53, v50
	v_mul_f32_e32 v54, v54, v49
	v_lshlrev_b32_e32 v15, 2, v105
	v_mul_f32_e32 v63, v7, v100
	v_fma_f32 v69, v7, v62, v59
	v_fmac_f32_e32 v51, v55, v50
	v_mul_f32_e32 v55, v55, v54
	ds_bpermute_b32 v225, v15, v63 offset:192
	ds_bpermute_b32 v63, v15, v69 offset:192
	ds_bpermute_b32 v69, v23, v55
	ds_bpermute_b32 v71, v23, v51
	ds_bpermute_b32 v73, v65, v55
	ds_bpermute_b32 v75, v65, v51
	v_fma_f32 v44, 0, v40, v44
	v_fmac_f32_e32 v45, v41, v44
	s_waitcnt lgkmcnt(2)
	v_fmac_f32_e32 v71, 0, v69
	v_cndmask_b32_e64 v71, v71, 0, vcc
	v_cndmask_b32_e64 v69, v69, 1.0, vcc
	s_waitcnt lgkmcnt(0)
	v_fmac_f32_e32 v75, v71, v73
	v_mul_f32_e32 v69, v69, v73
	v_cndmask_b32_e64 v71, v75, 0, s[36:37]
	ds_bpermute_b32 v73, v67, v55
	ds_bpermute_b32 v75, v67, v51
	v_cndmask_b32_e64 v69, v69, 1.0, s[36:37]
	v_mul_f32_e32 v41, v40, v41
	v_fma_f32 v42, v46, v45, v42
	s_waitcnt lgkmcnt(1)
	v_mul_f32_e32 v69, v69, v73
	s_waitcnt lgkmcnt(0)
	v_fmac_f32_e32 v75, v71, v73
	v_cndmask_b32_e64 v226, v69, 1.0, s[34:35]
	v_cndmask_b32_e64 v130, v75, 0, s[34:35]
	v_mul_f32_e32 v69, v55, v226
	v_fma_f32 v71, v55, v130, v51
	ds_bpermute_b32 v69, v15, v69 offset:192
	ds_bpermute_b32 v156, v15, v71 offset:192
	v_mul_f32_e32 v46, v46, v41
	v_fmac_f32_e32 v63, 0, v225
	v_fmac_f32_e32 v43, v47, v42
	v_mul_f32_e32 v47, v47, v46
	s_waitcnt lgkmcnt(0)
	v_fmac_f32_e32 v156, v63, v69
	v_mul_f32_e32 v157, v225, v69
	ds_bpermute_b32 v69, v23, v47
	ds_bpermute_b32 v71, v23, v43
	ds_bpermute_b32 v73, v65, v47
	ds_bpermute_b32 v75, v65, v43
	v_fma_f32 v36, 0, v32, v36
	v_fmac_f32_e32 v37, v33, v36
	s_waitcnt lgkmcnt(2)
	v_fmac_f32_e32 v71, 0, v69
	v_cndmask_b32_e64 v71, v71, 0, vcc
	v_cndmask_b32_e64 v69, v69, 1.0, vcc
	s_waitcnt lgkmcnt(0)
	v_fmac_f32_e32 v75, v71, v73
	v_mul_f32_e32 v69, v69, v73
	v_cndmask_b32_e64 v71, v75, 0, s[36:37]
	ds_bpermute_b32 v73, v67, v47
	ds_bpermute_b32 v75, v67, v43
	v_cndmask_b32_e64 v69, v69, 1.0, s[36:37]
	v_mul_f32_e32 v33, v32, v33
	v_fma_f32 v34, v38, v37, v34
	s_waitcnt lgkmcnt(1)
	v_mul_f32_e32 v69, v69, v73
	s_waitcnt lgkmcnt(0)
	v_fmac_f32_e32 v75, v71, v73
	v_cndmask_b32_e64 v224, v69, 1.0, s[34:35]
	v_cndmask_b32_e64 v132, v75, 0, s[34:35]
	v_mul_f32_e32 v69, v47, v224
	v_fma_f32 v71, v47, v132, v43
	ds_bpermute_b32 v69, v15, v69 offset:192
	ds_bpermute_b32 v162, v15, v71 offset:192
	v_mul_f32_e32 v38, v38, v33
	v_fmac_f32_e32 v35, v39, v34
	v_mul_f32_e32 v39, v39, v38
	s_waitcnt lgkmcnt(1)
	v_mul_f32_e32 v163, v157, v69
	s_waitcnt lgkmcnt(0)
	v_fmac_f32_e32 v162, v156, v69
	ds_bpermute_b32 v69, v23, v39
	ds_bpermute_b32 v71, v23, v35
	ds_bpermute_b32 v73, v65, v39
	ds_bpermute_b32 v75, v65, v35
	v_fma_f32 v28, 0, v24, v28
	v_fmac_f32_e32 v29, v25, v28
	s_waitcnt lgkmcnt(2)
	v_fmac_f32_e32 v71, 0, v69
	v_cndmask_b32_e64 v71, v71, 0, vcc
	v_cndmask_b32_e64 v69, v69, 1.0, vcc
	s_waitcnt lgkmcnt(0)
	v_fmac_f32_e32 v75, v71, v73
	v_mul_f32_e32 v69, v69, v73
	v_cndmask_b32_e64 v71, v75, 0, s[36:37]
	ds_bpermute_b32 v73, v67, v39
	ds_bpermute_b32 v75, v67, v35
	v_cndmask_b32_e64 v69, v69, 1.0, s[36:37]
	v_mul_f32_e32 v25, v24, v25
	v_fma_f32 v26, v30, v29, v26
	s_waitcnt lgkmcnt(1)
	v_mul_f32_e32 v69, v69, v73
	s_waitcnt lgkmcnt(0)
	v_fmac_f32_e32 v75, v71, v73
	v_cndmask_b32_e64 v164, v69, 1.0, s[34:35]
	v_cndmask_b32_e64 v134, v75, 0, s[34:35]
	v_mul_f32_e32 v69, v39, v164
	v_fma_f32 v71, v39, v134, v35
	ds_bpermute_b32 v69, v15, v69 offset:192
	ds_bpermute_b32 v165, v15, v71 offset:192
	v_mul_f32_e32 v30, v30, v25
	v_fmac_f32_e32 v27, v31, v26
	v_mul_f32_e32 v31, v31, v30
	s_waitcnt lgkmcnt(1)
	v_mul_f32_e32 v166, v163, v69
	s_waitcnt lgkmcnt(0)
	v_fmac_f32_e32 v165, v162, v69
	ds_bpermute_b32 v69, v23, v31
	ds_bpermute_b32 v71, v23, v27
	ds_bpermute_b32 v73, v65, v31
	ds_bpermute_b32 v75, v65, v27
	global_load_ushort v247, v14, s[0:1]
	global_load_ushort v248, v22, s[0:1]
	global_load_ushort v250, v64, s[0:1]
	global_load_ushort v251, v66, s[0:1]
	global_load_ushort v243, v68, s[0:1]
	global_load_ushort v245, v70, s[0:1]
	global_load_ushort v246, v72, s[0:1]
	global_load_ushort v249, v74, s[0:1]
	global_load_ushort v239, v76, s[0:1]
	global_load_ushort v240, v78, s[0:1]
	global_load_ushort v242, v80, s[0:1]
	global_load_ushort v244, v82, s[0:1]
	global_load_ushort v235, v84, s[0:1]
	global_load_ushort v237, v86, s[0:1]
	global_load_ushort v238, v88, s[0:1]
	global_load_ushort v241, v90, s[0:1]
	global_load_ushort v145, v92, s[0:1]
	global_load_ushort v232, v94, s[0:1]
	global_load_ushort v234, v96, s[0:1]
	global_load_ushort v236, v98, s[0:1]
	global_load_ushort v227, v102, s[0:1]
	global_load_ushort v141, v104, s[0:1]
	global_load_ushort v143, v106, s[0:1]
	global_load_ushort v233, v108, s[0:1]
	global_load_ushort v199, v110, s[0:1]
	global_load_ushort v200, v112, s[0:1]
	global_load_ushort v201, v114, s[0:1]
	global_load_ushort v139, v116, s[0:1]
	global_load_ushort v195, v118, s[0:1]
	global_load_ushort v196, v120, s[0:1]
	global_load_ushort v197, v122, s[0:1]
	global_load_ushort v198, v124, s[0:1]
	s_waitcnt lgkmcnt(2)
	v_fmac_f32_e32 v71, 0, v69
	v_cndmask_b32_e64 v71, v71, 0, vcc
	v_cndmask_b32_e64 v69, v69, 1.0, vcc
	s_waitcnt lgkmcnt(0)
	v_fmac_f32_e32 v75, v71, v73
	v_mul_f32_e32 v69, v69, v73
	v_cndmask_b32_e64 v71, v75, 0, s[36:37]
	ds_bpermute_b32 v73, v67, v31
	ds_bpermute_b32 v75, v67, v27
	v_cndmask_b32_e64 v69, v69, 1.0, s[36:37]
	v_fma_f32 v20, 0, v16, v20
	v_fmac_f32_e32 v21, v17, v20
	s_waitcnt lgkmcnt(1)
	v_mul_f32_e32 v69, v69, v73
	s_waitcnt lgkmcnt(0)
	v_fmac_f32_e32 v75, v71, v73
	v_cndmask_b32_e64 v167, v69, 1.0, s[34:35]
	v_cndmask_b32_e64 v138, v75, 0, s[34:35]
	v_mul_f32_e32 v69, v31, v167
	v_fma_f32 v71, v31, v138, v27
	ds_bpermute_b32 v69, v15, v69 offset:192
	ds_bpermute_b32 v168, v15, v71 offset:192
	v_mul_f32_e32 v17, v16, v17
	v_fma_f32 v18, v126, v21, v18
	v_mul_f32_e32 v126, v126, v17
	v_fmac_f32_e32 v19, v127, v18
	v_mul_f32_e32 v127, v127, v126
	s_waitcnt lgkmcnt(0)
	v_fmac_f32_e32 v168, v165, v69
	v_mul_f32_e32 v169, v166, v69
	ds_bpermute_b32 v69, v23, v127
	ds_bpermute_b32 v71, v23, v19
	ds_bpermute_b32 v73, v65, v127
	ds_bpermute_b32 v75, v65, v19
	v_fma_f32 v12, 0, v8, v12
	v_fmac_f32_e32 v13, v9, v12
	s_waitcnt lgkmcnt(2)
	v_fmac_f32_e32 v71, 0, v69
	v_cndmask_b32_e64 v71, v71, 0, vcc
	v_cndmask_b32_e64 v69, v69, 1.0, vcc
	s_waitcnt lgkmcnt(0)
	v_fmac_f32_e32 v75, v71, v73
	v_mul_f32_e32 v69, v69, v73
	v_cndmask_b32_e64 v71, v75, 0, s[36:37]
	ds_bpermute_b32 v73, v67, v127
	ds_bpermute_b32 v75, v67, v19
	v_cndmask_b32_e64 v69, v69, 1.0, s[36:37]
	v_mul_f32_e32 v9, v8, v9
	v_fma_f32 v10, v128, v13, v10
	s_waitcnt lgkmcnt(1)
	v_mul_f32_e32 v69, v69, v73
	s_waitcnt lgkmcnt(0)
	v_fmac_f32_e32 v75, v71, v73
	v_cndmask_b32_e64 v158, v69, 1.0, s[34:35]
	v_cndmask_b32_e64 v140, v75, 0, s[34:35]
	v_mul_f32_e32 v69, v127, v158
	v_fma_f32 v71, v127, v140, v19
	ds_bpermute_b32 v69, v15, v69 offset:192
	ds_bpermute_b32 v159, v15, v71 offset:192
	v_mul_f32_e32 v128, v128, v9
	v_fmac_f32_e32 v11, v129, v10
	v_mul_f32_e32 v129, v129, v128
	s_waitcnt lgkmcnt(1)
	v_mul_f32_e32 v222, v169, v69
	s_waitcnt lgkmcnt(0)
	v_fmac_f32_e32 v159, v168, v69
	ds_bpermute_b32 v69, v23, v129
	ds_bpermute_b32 v71, v23, v11
	ds_bpermute_b32 v73, v65, v129
	ds_bpermute_b32 v75, v65, v11
	v_fma_f32 v4, 0, v0, v4
	v_fmac_f32_e32 v5, v1, v4
	s_waitcnt lgkmcnt(2)
	v_fmac_f32_e32 v71, 0, v69
	v_cndmask_b32_e64 v71, v71, 0, vcc
	v_cndmask_b32_e64 v69, v69, 1.0, vcc
	s_waitcnt lgkmcnt(0)
	v_fmac_f32_e32 v75, v71, v73
	v_mul_f32_e32 v69, v69, v73
	v_cndmask_b32_e64 v71, v75, 0, s[36:37]
	ds_bpermute_b32 v73, v67, v129
	ds_bpermute_b32 v75, v67, v11
	v_cndmask_b32_e64 v69, v69, 1.0, s[36:37]
	v_mul_f32_e32 v1, v0, v1
	v_fma_f32 v2, v136, v5, v2
	s_waitcnt lgkmcnt(1)
	v_mul_f32_e32 v69, v69, v73
	s_waitcnt lgkmcnt(0)
	v_fmac_f32_e32 v75, v71, v73
	v_cndmask_b32_e64 v223, v69, 1.0, s[34:35]
	v_cndmask_b32_e64 v142, v75, 0, s[34:35]
	v_mul_f32_e32 v69, v129, v223
	v_fma_f32 v71, v129, v142, v11
	ds_bpermute_b32 v69, v15, v69 offset:192
	ds_bpermute_b32 v131, v15, v71 offset:192
	v_mul_f32_e32 v136, v136, v1
	v_fmac_f32_e32 v3, v137, v2
	v_mul_f32_e32 v137, v137, v136
	s_waitcnt lgkmcnt(1)
	v_mul_f32_e32 v133, v222, v69
	s_waitcnt lgkmcnt(0)
	v_fmac_f32_e32 v131, v159, v69
	ds_bpermute_b32 v69, v23, v137
	ds_bpermute_b32 v23, v23, v3
	ds_bpermute_b32 v71, v65, v137
	ds_bpermute_b32 v65, v65, v3
	v_readlane_b32 s16, v255, 35
	v_readlane_b32 s17, v255, 36
	s_waitcnt lgkmcnt(2)
	v_fmac_f32_e32 v23, 0, v69
	v_cndmask_b32_e64 v69, v69, 1.0, vcc
	v_cndmask_b32_e64 v23, v23, 0, vcc
	s_waitcnt lgkmcnt(0)
	v_fmac_f32_e32 v65, v23, v71
	v_mul_f32_e32 v23, v69, v71
	ds_bpermute_b32 v69, v67, v137
	ds_bpermute_b32 v67, v67, v3
	v_cndmask_b32_e64 v23, v23, 1.0, s[36:37]
	v_cndmask_b32_e64 v65, v65, 0, s[36:37]
	s_add_u32 s90, s16, s38
	s_waitcnt lgkmcnt(1)
	v_mul_f32_e32 v23, v23, v69
	s_waitcnt lgkmcnt(0)
	v_fmac_f32_e32 v67, v65, v69
	v_cndmask_b32_e64 v135, v23, 1.0, s[34:35]
	v_cndmask_b32_e64 v144, v67, 0, s[34:35]
	v_mul_f32_e32 v23, v137, v135
	v_fma_f32 v65, v137, v144, v3
	s_addc_u32 s91, s17, s39
	ds_bpermute_b32 v23, v15, v23 offset:192
	ds_bpermute_b32 v146, v15, v65 offset:192
	s_lshl_b64 s[16:17], s[90:91], 17
	s_add_u32 s16, s10, s16
	s_addc_u32 s17, s11, s17
	s_cmpk_lt_i32 s27, 0x780
	v_lshl_add_u64 v[148:149], v[160:161], 3, s[16:17]
	v_cmp_gt_u32_e64 s[34:35], 16, v101
	s_cselect_b64 s[16:17], -1, 0
	s_waitcnt lgkmcnt(0)
	v_fmac_f32_e32 v146, v131, v23
	v_mul_f32_e32 v147, v133, v23
	s_and_b64 s[28:29], s[16:17], s[34:35]
	s_and_saveexec_b64 s[16:17], s[28:29]
	s_cbranch_execz .LBB0_305
	s_lshr_b32 s28, s27, 7
	s_bfe_i64 s[28:29], s[28:29], 0x100000
	s_lshl_b64 s[28:29], s[28:29], 13
	v_lshl_add_u64 v[150:151], v[148:149], 0, s[28:29]
	global_store_dwordx2 v[150:151], v[146:147], off sc1

.LBB0_342:
	s_and_b64 vcc, exec, s[16:17]
	s_cbranch_vccz .LBB0_356
	s_add_i32 s16, s61, s25
	s_ashr_i32 s17, s16, 31
	s_lshl_b64 s[16:17], s[16:17], 8
	v_readlane_b32 s27, v254, 51
	s_add_u32 s16, s16, s27
	v_mbcnt_lo_u32_b32 v2, -1, 0
	v_mbcnt_hi_u32_b32 v2, -1, v2
	s_addc_u32 s17, s17, 0
	v_and_or_b32 v0, v2, 15, s16
	v_mov_b32_e32 v1, s17
	v_readlane_b32 s16, v253, 50
	v_ashrrev_i32_e32 v2, 1, v2
	v_lshlrev_b64 v[0:1], 9, v[0:1]
	v_readlane_b32 s17, v253, 51
	v_and_b32_e32 v2, -8, v2
	v_ashrrev_i32_e32 v3, 31, v2
	v_lshl_add_u64 v[0:1], s[16:17], 0, v[0:1]
	v_lshl_add_u64 v[0:1], v[2:3], 1, v[0:1]
	s_movk_i32 s16, 0x2000
	v_add_co_u32_e32 v4, vcc, s16, v0
	s_ashr_i32 s16, s68, 31
	s_nop 0
	v_addc_co_u32_e32 v5, vcc, 0, v1, vcc
	global_load_dwordx4 v[56:59], v[0:1], off
	global_load_dwordx4 v[48:51], v[0:1], off offset:64
	global_load_dwordx4 v[60:63], v[4:5], off
	global_load_dwordx4 v[52:55], v[4:5], off offset:64
	global_load_dwordx4 v[40:43], v[0:1], off offset:128
	global_load_dwordx4 v[32:35], v[0:1], off offset:192
	global_load_dwordx4 v[44:47], v[4:5], off offset:128
	global_load_dwordx4 v[36:39], v[4:5], off offset:192
	global_load_dwordx4 v[24:27], v[0:1], off offset:256
	global_load_dwordx4 v[16:19], v[0:1], off offset:320
	global_load_dwordx4 v[28:31], v[4:5], off offset:256
	global_load_dwordx4 v[20:23], v[4:5], off offset:320
	global_load_dwordx4 v[8:11], v[0:1], off offset:384
	s_nop 0
	global_load_dwordx4 v[0:3], v[0:1], off offset:448
	s_nop 0
	global_load_dwordx4 v[12:15], v[4:5], off offset:384
	s_nop 0
	global_load_dwordx4 v[4:7], v[4:5], off offset:448
	s_lshr_b32 s16, s16, 21
	v_mbcnt_lo_u32_b32 v64, -1, 0
	v_mbcnt_hi_u32_b32 v64, -1, v64
	s_add_i32 s16, s68, s16
	v_add_u32_e32 v65, s3, v64
	v_ashrrev_i32_e32 v178, 2, v65
	s_and_b32 s17, s16, 0xfffff800
	v_and_b32_e32 v180, -8, v178
	s_sub_i32 s17, s68, s17
	s_ashr_i32 s16, s16, 11
	v_add_u32_e32 v179, s17, v180
	s_ashr_i32 s17, s16, 31
	v_lshlrev_b32_e32 v64, 3, v64
	s_lshl_b64 s[42:43], s[16:17], 24
	s_and_b32 s26, s26, 0xff
	v_and_b32_e32 v181, 0xf8, v64
	s_cmp_lt_i32 s26, 1
	s_mov_b64 s[16:17], -1
	s_cbranch_scc1 .LBB0_353
	s_and_b32 s26, 0xffff, s26
	s_cmp_lt_i32 s26, 2
	s_cbranch_scc1 .LBB0_350
	v_max_i32_e32 v64, 7, v179
	v_max_i32_e32 v65, 6, v179
	v_max_i32_e32 v66, 5, v179
	v_max_i32_e32 v67, 4, v179
	s_cmp_lg_u32 s26, 2
	v_cmp_lt_i32_e64 s[38:39], 6, v179
	v_cmp_lt_i32_e64 s[36:37], 5, v179
	v_cmp_lt_i32_e64 s[34:35], 4, v179
	v_cmp_lt_i32_e32 vcc, 3, v179
	v_add_u32_e32 v176, -7, v64
	v_add_u32_e32 v174, -6, v65
	v_add_u32_e32 v172, -5, v66
	v_add_u32_e32 v170, -4, v67
	s_cbranch_scc0 .LBB0_347
	s_add_u32 s16, s10, s42
	s_addc_u32 s17, s11, s43
	s_add_u32 s16, s16, 0x5a00600
	s_addc_u32 s17, s17, 0
	v_lshlrev_b32_e32 v160, 1, v181
	v_add_u32_e32 v162, -15, v179
	v_max_i32_e32 v182, 0, v162
	v_lshl_add_u32 v182, v182, 13, v160
	global_load_dwordx4 v[64:67], v182, s[16:17]
	v_add_u32_e32 v183, 1, v162
	v_max_i32_e32 v183, 0, v183
	v_lshl_add_u32 v183, v183, 13, v160
	global_load_dwordx4 v[68:71], v183, s[16:17]
	v_add_u32_e32 v184, 2, v162
	v_max_i32_e32 v184, 0, v184
	v_lshl_add_u32 v184, v184, 13, v160
	global_load_dwordx4 v[72:75], v184, s[16:17]
	v_add_u32_e32 v185, 3, v162
	v_max_i32_e32 v185, 0, v185
	v_lshl_add_u32 v185, v185, 13, v160
	global_load_dwordx4 v[76:79], v185, s[16:17]
	v_add_u32_e32 v186, 4, v162
	v_max_i32_e32 v186, 0, v186
	v_lshl_add_u32 v186, v186, 13, v160
	global_load_dwordx4 v[80:83], v186, s[16:17]
	v_add_u32_e32 v187, 5, v162
	v_max_i32_e32 v187, 0, v187
	v_lshl_add_u32 v187, v187, 13, v160
	global_load_dwordx4 v[84:87], v187, s[16:17]
	v_add_u32_e32 v188, 6, v162
	v_max_i32_e32 v188, 0, v188
	v_lshl_add_u32 v188, v188, 13, v160
	global_load_dwordx4 v[88:91], v188, s[16:17]
	v_add_u32_e32 v189, 7, v162
	v_max_i32_e32 v189, 0, v189
	v_lshl_add_u32 v189, v189, 13, v160
	global_load_dwordx4 v[92:95], v189, s[16:17]
	v_add_u32_e32 v190, 8, v162
	v_max_i32_e32 v190, 0, v190
	v_lshl_add_u32 v190, v190, 13, v160
	global_load_dwordx4 v[96:99], v190, s[16:17]
	v_add_u32_e32 v191, 9, v162
	v_max_i32_e32 v191, 0, v191
	v_lshl_add_u32 v191, v191, 13, v160
	global_load_dwordx4 v[100:103], v191, s[16:17]
	v_add_u32_e32 v192, 10, v162
	v_max_i32_e32 v192, 0, v192
	v_lshl_add_u32 v192, v192, 13, v160
	global_load_dwordx4 v[104:107], v192, s[16:17]
	v_add_u32_e32 v193, 11, v162
	v_max_i32_e32 v193, 0, v193
	v_lshl_add_u32 v193, v193, 13, v160
	global_load_dwordx4 v[108:111], v193, s[16:17]
	v_add_u32_e32 v194, 12, v162
	v_max_i32_e32 v194, 0, v194
	v_lshl_add_u32 v194, v194, 13, v160
	global_load_dwordx4 v[112:115], v194, s[16:17]
	v_add_u32_e32 v195, 13, v162
	v_max_i32_e32 v195, 0, v195
	v_lshl_add_u32 v195, v195, 13, v160
	global_load_dwordx4 v[116:119], v195, s[16:17]
	v_add_u32_e32 v196, 14, v162
	v_max_i32_e32 v196, 0, v196
	v_lshl_add_u32 v196, v196, 13, v160
	global_load_dwordx4 v[120:123], v196, s[16:17]
	v_lshl_add_u32 v197, v179, 13, v160
	global_load_dwordx4 v[124:127], v197, s[16:17]
	v_add_u32_e32 v198, 1, v179
	v_lshl_add_u32 v198, v198, 13, v160
	global_load_dwordx4 v[128:131], v198, s[16:17]
	v_add_u32_e32 v199, 2, v179
	v_lshl_add_u32 v199, v199, 13, v160
	global_load_dwordx4 v[132:135], v199, s[16:17]
	v_add_u32_e32 v200, 3, v179
	v_lshl_add_u32 v200, v200, 13, v160
	global_load_dwordx4 v[136:139], v200, s[16:17]
	v_add_u32_e32 v201, 4, v179
	v_lshl_add_u32 v201, v201, 13, v160
	global_load_dwordx4 v[140:143], v201, s[16:17]
	v_add_u32_e32 v202, 5, v179
	v_lshl_add_u32 v202, v202, 13, v160
	global_load_dwordx4 v[144:147], v202, s[16:17]
	v_add_u32_e32 v203, 6, v179
	v_lshl_add_u32 v203, v203, 13, v160
	global_load_dwordx4 v[148:151], v203, s[16:17]
	v_add_u32_e32 v204, 7, v179
	v_lshl_add_u32 v204, v204, 13, v160
	global_load_dwordx4 v[152:155], v204, s[16:17]
	s_barrier
	s_mov_b32 s41, 0xffff0000
	v_mul_u32_u24_e32 v208, 0x210, v180
	s_and_b32 s40, s68, 0x780
	v_add_u32_e32 v208, v208, v160
	s_cbranch_scc1 .Lw16p_nz
	s_waitcnt vmcnt(0)
	v_cmp_lt_i32_e32 vcc, 14, v179
	s_nop 1
	v_cndmask_b32_e32 v64, 0, v64, vcc
	v_cndmask_b32_e32 v65, 0, v65, vcc
	v_cndmask_b32_e32 v66, 0, v66, vcc
	v_cndmask_b32_e32 v67, 0, v67, vcc
	v_cmp_lt_i32_e32 vcc, 13, v179
	s_nop 1
	v_cndmask_b32_e32 v68, 0, v68, vcc
	v_cndmask_b32_e32 v69, 0, v69, vcc
	v_cndmask_b32_e32 v70, 0, v70, vcc
	v_cndmask_b32_e32 v71, 0, v71, vcc
	v_cmp_lt_i32_e32 vcc, 12, v179
	s_nop 1
	v_cndmask_b32_e32 v72, 0, v72, vcc
	v_cndmask_b32_e32 v73, 0, v73, vcc
	v_cndmask_b32_e32 v74, 0, v74, vcc
	v_cndmask_b32_e32 v75, 0, v75, vcc
	v_cmp_lt_i32_e32 vcc, 11, v179
	s_nop 1
	v_cndmask_b32_e32 v76, 0, v76, vcc
	v_cndmask_b32_e32 v77, 0, v77, vcc
	v_cndmask_b32_e32 v78, 0, v78, vcc
	v_cndmask_b32_e32 v79, 0, v79, vcc
	v_cmp_lt_i32_e32 vcc, 10, v179
	s_nop 1
	v_cndmask_b32_e32 v80, 0, v80, vcc
	v_cndmask_b32_e32 v81, 0, v81, vcc
	v_cndmask_b32_e32 v82, 0, v82, vcc
	v_cndmask_b32_e32 v83, 0, v83, vcc
	v_cmp_lt_i32_e32 vcc, 9, v179
	s_nop 1
	v_cndmask_b32_e32 v84, 0, v84, vcc
	v_cndmask_b32_e32 v85, 0, v85, vcc
	v_cndmask_b32_e32 v86, 0, v86, vcc
	v_cndmask_b32_e32 v87, 0, v87, vcc
	v_cmp_lt_i32_e32 vcc, 8, v179
	s_nop 1
	v_cndmask_b32_e32 v88, 0, v88, vcc
	v_cndmask_b32_e32 v89, 0, v89, vcc
	v_cndmask_b32_e32 v90, 0, v90, vcc
	v_cndmask_b32_e32 v91, 0, v91, vcc
	v_cmp_lt_i32_e32 vcc, 7, v179
	s_nop 1
	v_cndmask_b32_e32 v92, 0, v92, vcc
	v_cndmask_b32_e32 v93, 0, v93, vcc
	v_cndmask_b32_e32 v94, 0, v94, vcc
	v_cndmask_b32_e32 v95, 0, v95, vcc
	v_cmp_lt_i32_e32 vcc, 6, v179
	s_nop 1
	v_cndmask_b32_e32 v96, 0, v96, vcc
	v_cndmask_b32_e32 v97, 0, v97, vcc
	v_cndmask_b32_e32 v98, 0, v98, vcc
	v_cndmask_b32_e32 v99, 0, v99, vcc
	v_cmp_lt_i32_e32 vcc, 5, v179
	s_nop 1
	v_cndmask_b32_e32 v100, 0, v100, vcc
	v_cndmask_b32_e32 v101, 0, v101, vcc
	v_cndmask_b32_e32 v102, 0, v102, vcc
	v_cndmask_b32_e32 v103, 0, v103, vcc
	v_cmp_lt_i32_e32 vcc, 4, v179
	s_nop 1
	v_cndmask_b32_e32 v104, 0, v104, vcc
	v_cndmask_b32_e32 v105, 0, v105, vcc
	v_cndmask_b32_e32 v106, 0, v106, vcc
	v_cndmask_b32_e32 v107, 0, v107, vcc
	v_cmp_lt_i32_e32 vcc, 3, v179
	s_nop 1
	v_cndmask_b32_e32 v108, 0, v108, vcc
	v_cndmask_b32_e32 v109, 0, v109, vcc
	v_cndmask_b32_e32 v110, 0, v110, vcc
	v_cndmask_b32_e32 v111, 0, v111, vcc
	v_cmp_lt_i32_e32 vcc, 2, v179
	s_nop 1
	v_cndmask_b32_e32 v112, 0, v112, vcc
	v_cndmask_b32_e32 v113, 0, v113, vcc
	v_cndmask_b32_e32 v114, 0, v114, vcc
	v_cndmask_b32_e32 v115, 0, v115, vcc
	v_cmp_lt_i32_e32 vcc, 1, v179
	s_nop 1
	v_cndmask_b32_e32 v116, 0, v116, vcc
	v_cndmask_b32_e32 v117, 0, v117, vcc
	v_cndmask_b32_e32 v118, 0, v118, vcc
	v_cndmask_b32_e32 v119, 0, v119, vcc
	v_cmp_lt_i32_e32 vcc, 0, v179
	s_nop 1
	v_cndmask_b32_e32 v120, 0, v120, vcc
	v_cndmask_b32_e32 v121, 0, v121, vcc
	v_cndmask_b32_e32 v122, 0, v122, vcc
	v_cndmask_b32_e32 v123, 0, v123, vcc

.LBB0_347:
	s_andn2_b64 vcc, exec, s[16:17]
	s_cbranch_vccnz .LBB0_349
	s_add_u32 s16, s10, s42
	s_addc_u32 s17, s11, s43
	v_lshlrev_b32_e32 v160, 1, v181
	v_max_i32_e32 v80, 3, v179
	v_max_i32_e32 v82, 2, v179
	v_max_i32_e32 v88, 1, v179
	v_lshl_add_u64 v[64:65], s[16:17], 0, v[160:161]
	s_mov_b64 s[16:17], 0x5a00400
	v_mov_b32_e32 v177, v161
	v_mov_b32_e32 v175, v161
	v_mov_b32_e32 v173, v161
	v_mov_b32_e32 v171, v161
	v_add_u32_e32 v80, -3, v80
	v_mov_b32_e32 v81, v161
	v_add_u32_e32 v82, -2, v82
	v_mov_b32_e32 v83, v161
	v_add_u32_e32 v88, -1, v88
	v_mov_b32_e32 v89, v161
	v_max_i32_e32 v90, 0, v179
	v_mov_b32_e32 v91, v161
	v_lshl_add_u64 v[124:125], v[64:65], 0, s[16:17]
	v_lshlrev_b64 v[64:65], 13, v[176:177]
	v_lshlrev_b64 v[66:67], 13, v[174:175]
	v_lshlrev_b64 v[72:73], 13, v[172:173]
	v_lshlrev_b64 v[74:75], 13, v[170:171]
	v_lshlrev_b64 v[80:81], 13, v[80:81]
	v_lshlrev_b64 v[82:83], 13, v[82:83]
	v_lshlrev_b64 v[88:89], 13, v[88:89]
	v_lshlrev_b64 v[90:91], 13, v[90:91]
	v_lshl_add_u64 v[64:65], v[124:125], 0, v[64:65]
	v_lshl_add_u64 v[68:69], v[124:125], 0, v[66:67]
	v_lshl_add_u64 v[72:73], v[124:125], 0, v[72:73]
	v_lshl_add_u64 v[76:77], v[124:125], 0, v[74:75]
	v_lshl_add_u64 v[80:81], v[124:125], 0, v[80:81]
	v_lshl_add_u64 v[84:85], v[124:125], 0, v[82:83]
	v_lshl_add_u64 v[88:89], v[124:125], 0, v[88:89]
	v_lshl_add_u64 v[92:93], v[124:125], 0, v[90:91]
	v_or_b32_e32 v156, 1, v179
	v_or_b32_e32 v157, 2, v179
	global_load_dwordx4 v[64:67], v[64:65], off
	s_nop 0
	global_load_dwordx4 v[68:71], v[68:69], off
	s_nop 0
	global_load_dwordx4 v[72:75], v[72:73], off
	s_nop 0
	global_load_dwordx4 v[76:79], v[76:77], off
	s_nop 0
	global_load_dwordx4 v[80:83], v[80:81], off
	s_nop 0
	global_load_dwordx4 v[84:87], v[84:85], off
	s_nop 0
	global_load_dwordx4 v[88:91], v[88:89], off
	s_nop 0
	global_load_dwordx4 v[96:99], v[92:93], off
	v_max_i32_e32 v92, 0, v156
	v_mov_b32_e32 v93, v161
	v_max_i32_e32 v94, 0, v157
	v_mov_b32_e32 v95, v161
	v_lshlrev_b64 v[92:93], 13, v[92:93]
	v_lshlrev_b64 v[94:95], 13, v[94:95]
	v_lshl_add_u64 v[92:93], v[124:125], 0, v[92:93]
	v_lshl_add_u64 v[94:95], v[124:125], 0, v[94:95]
	global_load_dwordx4 v[100:103], v[92:93], off
	global_load_dwordx4 v[104:107], v[94:95], off
	v_or_b32_e32 v95, 3, v179
	v_max_i32_e32 v92, 0, v95
	v_mov_b32_e32 v93, v161
	v_lshlrev_b64 v[92:93], 13, v[92:93]
	v_lshl_add_u64 v[92:93], v[124:125], 0, v[92:93]
	v_or_b32_e32 v158, 4, v179
	global_load_dwordx4 v[108:111], v[92:93], off
	v_max_i32_e32 v92, 0, v158
	v_mov_b32_e32 v93, v161
	v_lshlrev_b64 v[92:93], 13, v[92:93]
	v_lshl_add_u64 v[92:93], v[124:125], 0, v[92:93]
	v_or_b32_e32 v94, 5, v179
	global_load_dwordx4 v[112:115], v[92:93], off
	v_max_i32_e32 v92, 0, v94
	v_mov_b32_e32 v93, v161
	v_lshlrev_b64 v[92:93], 13, v[92:93]
	v_lshl_add_u64 v[92:93], v[124:125], 0, v[92:93]
	global_load_dwordx4 v[116:119], v[92:93], off
	v_or_b32_e32 v93, 6, v179
	v_max_i32_e32 v120, 0, v93
	v_mov_b32_e32 v121, v161
	v_or_b32_e32 v92, 7, v179
	v_lshlrev_b64 v[120:121], 13, v[120:121]
	v_max_i32_e32 v126, 0, v92
	v_mov_b32_e32 v127, v161
	v_lshl_add_u64 v[120:121], v[124:125], 0, v[120:121]
	v_lshlrev_b64 v[126:127], 13, v[126:127]
	global_load_dwordx4 v[120:123], v[120:121], off
	v_lshl_add_u64 v[124:125], v[124:125], 0, v[126:127]
	global_load_dwordx4 v[124:127], v[124:125], off
	v_cmp_lt_i32_e32 vcc, 6, v179
	v_min_i32_e32 v173, 7, v179
	v_add_u32_e32 v173, 1, v173
	v_cvt_f32_i32_e32 v173, v173
	v_min_i32_e32 v156, 7, v156
	v_add_u32_e32 v156, 1, v156
	v_cvt_f32_i32_e32 v156, v156
	v_rcp_iflag_f32_e32 v173, v173
	s_movk_i32 s16, 0x210
	v_min_i32_e32 v95, 7, v95
	v_rcp_iflag_f32_e32 v156, v156
	v_add_u32_e32 v95, 1, v95
	v_cvt_f32_i32_e32 v95, v95
	v_rcp_iflag_f32_e32 v95, v95
	s_barrier
	s_waitcnt vmcnt(14)
	v_cndmask_b32_e32 v131, 0, v67, vcc
	v_cndmask_b32_e32 v130, 0, v66, vcc
	v_cndmask_b32_e32 v129, 0, v65, vcc
	v_cndmask_b32_e32 v128, 0, v64, vcc
	v_cmp_lt_i32_e32 vcc, 5, v179
	s_waitcnt vmcnt(13)
	s_nop 0
	v_cndmask_b32_e32 v135, 0, v71, vcc
	v_cndmask_b32_e32 v134, 0, v70, vcc
	v_cndmask_b32_e32 v133, 0, v69, vcc
	v_cndmask_b32_e32 v132, 0, v68, vcc
	v_cmp_lt_i32_e32 vcc, 4, v179
	s_waitcnt vmcnt(12)
	s_nop 0
	v_cndmask_b32_e32 v139, 0, v75, vcc
	v_cndmask_b32_e32 v138, 0, v74, vcc
	v_cndmask_b32_e32 v137, 0, v73, vcc
	v_cndmask_b32_e32 v136, 0, v72, vcc
	v_cmp_lt_i32_e32 vcc, 3, v179
	s_waitcnt vmcnt(11)
	s_nop 0
	v_cndmask_b32_e32 v143, 0, v79, vcc
	v_cndmask_b32_e32 v142, 0, v78, vcc
	v_cndmask_b32_e32 v141, 0, v77, vcc
	v_cndmask_b32_e32 v140, 0, v76, vcc
	v_cmp_lt_i32_e32 vcc, 2, v179
	s_waitcnt vmcnt(10)
	s_nop 0
	v_cndmask_b32_e32 v147, 0, v83, vcc
	v_cndmask_b32_e32 v146, 0, v82, vcc
	v_cndmask_b32_e32 v145, 0, v81, vcc
	v_cndmask_b32_e32 v144, 0, v80, vcc
	v_cmp_lt_i32_e32 vcc, 1, v179
	s_waitcnt vmcnt(9)
	s_nop 0
	v_cndmask_b32_e32 v151, 0, v87, vcc
	v_cndmask_b32_e32 v150, 0, v86, vcc
	v_cndmask_b32_e32 v149, 0, v85, vcc
	v_cndmask_b32_e32 v148, 0, v84, vcc
	v_cmp_lt_i32_e32 vcc, 0, v179
	s_waitcnt vmcnt(8)
	s_nop 0
	v_cndmask_b32_e32 v155, 0, v91, vcc
	v_cndmask_b32_e32 v154, 0, v90, vcc
	v_cndmask_b32_e32 v153, 0, v89, vcc
	v_cndmask_b32_e32 v152, 0, v88, vcc
	v_cmp_lt_i32_e32 vcc, -1, v179
	s_waitcnt vmcnt(7)
	s_nop 0
	v_cndmask_b32_e32 v99, 0, v99, vcc
	v_cndmask_b32_e32 v98, 0, v98, vcc
	v_cndmask_b32_e32 v97, 0, v97, vcc
	v_cndmask_b32_e32 v96, 0, v96, vcc
	v_cmp_lt_i32_e32 vcc, -2, v179
	s_waitcnt vmcnt(6)
	s_nop 0
	v_cndmask_b32_e32 v91, 0, v103, vcc
	v_cndmask_b32_e32 v90, 0, v102, vcc
	v_cndmask_b32_e32 v89, 0, v101, vcc
	v_cndmask_b32_e32 v88, 0, v100, vcc
	v_cmp_lt_i32_e32 vcc, -3, v179
	s_waitcnt vmcnt(5)
	s_nop 0
	v_cndmask_b32_e32 v87, 0, v107, vcc
	v_cndmask_b32_e32 v86, 0, v106, vcc
	v_cndmask_b32_e32 v85, 0, v105, vcc
	v_cndmask_b32_e32 v84, 0, v104, vcc
	v_cmp_lt_i32_e32 vcc, -4, v179
	s_waitcnt vmcnt(4)
	s_nop 0
	v_cndmask_b32_e32 v83, 0, v111, vcc
	v_cndmask_b32_e32 v82, 0, v110, vcc
	v_cndmask_b32_e32 v81, 0, v109, vcc
	v_cndmask_b32_e32 v80, 0, v108, vcc
	v_cmp_lt_i32_e32 vcc, -5, v179
	s_nop 0
	v_and_b32_e32 v101, 0xffff0000, v128
	s_waitcnt vmcnt(3)
	v_cndmask_b32_e32 v79, 0, v115, vcc
	v_cndmask_b32_e32 v78, 0, v114, vcc
	v_cndmask_b32_e32 v77, 0, v113, vcc
	v_cndmask_b32_e32 v76, 0, v112, vcc
	v_cmp_lt_i32_e32 vcc, -6, v179
	v_and_b32_e32 v103, 0xffff0000, v129
	v_and_b32_e32 v105, 0xffff0000, v130
	v_lshlrev_b32_e32 v106, 16, v131
	v_and_b32_e32 v107, 0xffff0000, v131
	s_waitcnt vmcnt(2)
	v_cndmask_b32_e32 v75, 0, v119, vcc
	v_cndmask_b32_e32 v74, 0, v118, vcc
	v_cndmask_b32_e32 v73, 0, v117, vcc
	v_cndmask_b32_e32 v72, 0, v116, vcc
	v_cmp_lt_i32_e32 vcc, -7, v179
	v_lshlrev_b32_e32 v100, 16, v128
	v_lshlrev_b32_e32 v102, 16, v129
	v_lshlrev_b32_e32 v104, 16, v130
	v_and_b32_e32 v109, 0xffff0000, v132
	v_and_b32_e32 v111, 0xffff0000, v133
	v_and_b32_e32 v113, 0xffff0000, v134
	v_lshlrev_b32_e32 v114, 16, v135
	v_and_b32_e32 v115, 0xffff0000, v135
	v_add_f32_e32 v159, 0, v107
	v_add_f32_e32 v165, 0, v101
	v_add_f32_e32 v168, 0, v103
	v_add_f32_e32 v171, 0, v105
	v_add_f32_e32 v172, 0, v106
	s_waitcnt vmcnt(1)
	v_cndmask_b32_e32 v71, 0, v123, vcc
	v_cndmask_b32_e32 v70, 0, v122, vcc
	v_cndmask_b32_e32 v69, 0, v121, vcc
	v_cndmask_b32_e32 v68, 0, v120, vcc
	v_cmp_lt_i32_e32 vcc, -8, v179
	v_lshlrev_b32_e32 v108, 16, v132
	v_lshlrev_b32_e32 v110, 16, v133
	v_lshlrev_b32_e32 v112, 16, v134
	v_and_b32_e32 v117, 0xffff0000, v136
	v_and_b32_e32 v119, 0xffff0000, v137
	v_and_b32_e32 v121, 0xffff0000, v138
	v_lshlrev_b32_e32 v122, 16, v139
	v_and_b32_e32 v123, 0xffff0000, v139
	v_add_f32_e32 v159, v159, v115
	v_add_f32_e32 v163, 0, v100
	v_add_f32_e32 v165, v165, v109
	v_add_f32_e32 v166, 0, v102
	v_add_f32_e32 v168, v168, v111
	v_add_f32_e32 v169, 0, v104
	v_add_f32_e32 v171, v171, v113
	v_add_f32_e32 v172, v172, v114
	s_waitcnt vmcnt(0)
	v_cndmask_b32_e32 v67, 0, v127, vcc
	v_cndmask_b32_e32 v65, 0, v125, vcc
	v_lshlrev_b32_e32 v116, 16, v136
	v_lshlrev_b32_e32 v118, 16, v137
	v_lshlrev_b32_e32 v120, 16, v138
	v_and_b32_e32 v125, 0xffff0000, v140
	v_and_b32_e32 v127, 0xffff0000, v141
	v_and_b32_e32 v129, 0xffff0000, v142
	v_lshlrev_b32_e32 v130, 16, v143
	v_and_b32_e32 v131, 0xffff0000, v143
	v_add_f32_e32 v159, v159, v123
	v_add_f32_e32 v163, v163, v108
	v_add_f32_e32 v165, v165, v117
	v_add_f32_e32 v166, v166, v110
	v_add_f32_e32 v168, v168, v119
	v_add_f32_e32 v169, v169, v112
	v_add_f32_e32 v171, v171, v121
	v_add_f32_e32 v172, v172, v122
	v_cndmask_b32_e32 v66, 0, v126, vcc
	v_cndmask_b32_e32 v64, 0, v124, vcc
	v_lshlrev_b32_e32 v124, 16, v140
	v_lshlrev_b32_e32 v126, 16, v141
	v_lshlrev_b32_e32 v128, 16, v142
	v_and_b32_e32 v133, 0xffff0000, v144
	v_and_b32_e32 v135, 0xffff0000, v145
	v_and_b32_e32 v137, 0xffff0000, v146
	v_lshlrev_b32_e32 v138, 16, v147
	v_and_b32_e32 v139, 0xffff0000, v147
	v_add_f32_e32 v159, v159, v131
	v_add_f32_e32 v163, v163, v116
	v_add_f32_e32 v165, v165, v125
	v_add_f32_e32 v166, v166, v118
	v_add_f32_e32 v168, v168, v127
	v_add_f32_e32 v169, v169, v120
	v_add_f32_e32 v171, v171, v129
	v_add_f32_e32 v172, v172, v130
	v_lshlrev_b32_e32 v132, 16, v144
	v_lshlrev_b32_e32 v134, 16, v145
	v_lshlrev_b32_e32 v136, 16, v146
	v_and_b32_e32 v141, 0xffff0000, v148
	v_and_b32_e32 v143, 0xffff0000, v149
	v_and_b32_e32 v145, 0xffff0000, v150
	v_lshlrev_b32_e32 v146, 16, v151
	v_and_b32_e32 v147, 0xffff0000, v151
	v_add_f32_e32 v159, v159, v139
	v_add_f32_e32 v163, v163, v124
	v_add_f32_e32 v165, v165, v133
	v_add_f32_e32 v166, v166, v126
	v_add_f32_e32 v168, v168, v135
	v_add_f32_e32 v169, v169, v128
	v_add_f32_e32 v171, v171, v137
	v_add_f32_e32 v172, v172, v138
	v_lshlrev_b32_e32 v140, 16, v148
	v_lshlrev_b32_e32 v142, 16, v149
	v_lshlrev_b32_e32 v144, 16, v150
	v_lshlrev_b32_e32 v148, 16, v152
	v_and_b32_e32 v149, 0xffff0000, v152
	v_lshlrev_b32_e32 v150, 16, v153
	v_and_b32_e32 v151, 0xffff0000, v153
	v_lshlrev_b32_e32 v152, 16, v154
	v_and_b32_e32 v153, 0xffff0000, v154
	v_lshlrev_b32_e32 v154, 16, v155
	v_and_b32_e32 v155, 0xffff0000, v155
	v_add_f32_e32 v159, v159, v147
	v_add_f32_e32 v163, v163, v132
	v_add_f32_e32 v165, v165, v141
	v_add_f32_e32 v166, v166, v134
	v_add_f32_e32 v168, v168, v143
	v_add_f32_e32 v169, v169, v136
	v_add_f32_e32 v171, v171, v145
	v_add_f32_e32 v172, v172, v146
	v_add_f32_e32 v159, v159, v155
	v_and_b32_e32 v162, 0xffff0000, v99
	v_add_f32_e32 v163, v163, v140
	v_lshlrev_b32_e32 v164, 16, v96
	v_add_f32_e32 v165, v165, v149
	v_and_b32_e32 v96, 0xffff0000, v96
	v_add_f32_e32 v166, v166, v142
	v_lshlrev_b32_e32 v167, 16, v97
	v_add_f32_e32 v168, v168, v151
	v_and_b32_e32 v97, 0xffff0000, v97
	v_add_f32_e32 v169, v169, v144
	v_lshlrev_b32_e32 v170, 16, v98
	v_add_f32_e32 v171, v171, v153
	v_and_b32_e32 v98, 0xffff0000, v98
	v_add_f32_e32 v172, v172, v154
	v_lshlrev_b32_e32 v99, 16, v99
	v_add_f32_e32 v159, v159, v162
	v_add_f32_e32 v163, v163, v148
	v_add_f32_e32 v165, v165, v96
	v_add_f32_e32 v166, v166, v150
	v_add_f32_e32 v168, v168, v97
	v_add_f32_e32 v169, v169, v152
	v_add_f32_e32 v171, v171, v98
	v_add_f32_e32 v172, v172, v99
	v_add_f32_e32 v163, v163, v164
	v_add_f32_e32 v166, v166, v167
	v_add_f32_e32 v169, v169, v170
	v_fma_f32 v96, v173, v165, -v96
	v_fma_f32 v97, v173, v168, -v97
	v_fma_f32 v98, v173, v171, -v98
	v_fma_f32 v99, v173, v172, -v99
	v_fma_f32 v162, v173, v159, -v162
	v_fma_f32 v164, v173, v163, -v164
	v_fma_f32 v167, v173, v166, -v167
	v_fma_f32 v170, v173, v169, -v170
	v_cvt_pk_bf16_f32 v96, v164, v96
	v_cvt_pk_bf16_f32 v97, v167, v97
	v_cvt_pk_bf16_f32 v98, v170, v98
	v_cvt_pk_bf16_f32 v99, v99, v162
	v_mul_lo_u32 v162, v180, s16
	v_add3_u32 v160, 0, v160, v162
	ds_write_b128 v160, v[96:99]
	v_sub_f32_e32 v98, v163, v100
	v_lshlrev_b32_e32 v99, 16, v88
	v_sub_f32_e32 v100, v165, v101
	v_and_b32_e32 v88, 0xffff0000, v88
	v_sub_f32_e32 v101, v166, v102
	v_lshlrev_b32_e32 v102, 16, v89
	v_sub_f32_e32 v103, v168, v103
	v_and_b32_e32 v89, 0xffff0000, v89
	v_add_f32_e32 v100, v100, v88
	v_add_f32_e32 v101, v101, v102
	v_add_f32_e32 v103, v103, v89
	v_add_f32_e32 v98, v98, v99
	v_fma_f32 v88, v156, v100, -v88
	v_fma_f32 v102, v156, v101, -v102
	v_fma_f32 v89, v156, v103, -v89
	v_fma_f32 v99, v156, v98, -v99
	v_cvt_pk_bf16_f32 v88, v99, v88
	v_cvt_pk_bf16_f32 v89, v102, v89
	v_min_i32_e32 v102, 7, v157
	v_add_u32_e32 v102, 1, v102
	v_cvt_f32_i32_e32 v102, v102
	v_sub_f32_e32 v96, v159, v107
	v_and_b32_e32 v97, 0xffff0000, v91
	v_lshlrev_b32_e32 v107, 16, v90
	v_sub_f32_e32 v105, v171, v105
	v_and_b32_e32 v90, 0xffff0000, v90
	v_sub_f32_e32 v106, v172, v106
	v_lshlrev_b32_e32 v91, 16, v91
	v_sub_f32_e32 v104, v169, v104
	v_add_f32_e32 v105, v105, v90
	v_add_f32_e32 v106, v106, v91
	v_add_f32_e32 v96, v96, v97
	v_add_f32_e32 v104, v104, v107
	v_fma_f32 v90, v156, v105, -v90
	v_fma_f32 v91, v156, v106, -v91
	v_rcp_iflag_f32_e32 v102, v102
	v_fma_f32 v107, v156, v104, -v107
	v_fma_f32 v97, v156, v96, -v97
	v_cvt_pk_bf16_f32 v90, v107, v90
	v_cvt_pk_bf16_f32 v91, v91, v97
	ds_write_b128 v160, v[88:91] offset:528
	v_sub_f32_e32 v88, v96, v115
	v_and_b32_e32 v89, 0xffff0000, v87
	v_sub_f32_e32 v90, v98, v108
	v_lshlrev_b32_e32 v91, 16, v84
	v_sub_f32_e32 v96, v100, v109
	v_and_b32_e32 v84, 0xffff0000, v84
	v_sub_f32_e32 v97, v101, v110
	v_lshlrev_b32_e32 v98, 16, v85
	v_sub_f32_e32 v99, v103, v111
	v_and_b32_e32 v85, 0xffff0000, v85
	v_sub_f32_e32 v100, v104, v112
	v_lshlrev_b32_e32 v101, 16, v86
	v_sub_f32_e32 v103, v105, v113
	v_and_b32_e32 v86, 0xffff0000, v86
	v_sub_f32_e32 v104, v106, v114
	v_lshlrev_b32_e32 v87, 16, v87
	v_add_f32_e32 v96, v96, v84
	v_add_f32_e32 v99, v99, v85
	v_add_f32_e32 v103, v103, v86
	v_add_f32_e32 v104, v104, v87
	v_add_f32_e32 v88, v88, v89
	v_add_f32_e32 v90, v90, v91
	v_add_f32_e32 v97, v97, v98
	v_add_f32_e32 v100, v100, v101
	v_fma_f32 v84, v102, v96, -v84
	v_fma_f32 v85, v102, v99, -v85
	v_fma_f32 v86, v102, v103, -v86
	v_fma_f32 v87, v102, v104, -v87
	v_fma_f32 v91, v102, v90, -v91
	v_fma_f32 v98, v102, v97, -v98
	v_fma_f32 v101, v102, v100, -v101
	v_fma_f32 v89, v102, v88, -v89
	v_cvt_pk_bf16_f32 v84, v91, v84
	v_cvt_pk_bf16_f32 v85, v98, v85
	v_cvt_pk_bf16_f32 v86, v101, v86
	v_cvt_pk_bf16_f32 v87, v87, v89
	ds_write_b128 v160, v[84:87] offset:1056
	v_sub_f32_e32 v84, v88, v123
	v_sub_f32_e32 v86, v90, v116
	v_lshlrev_b32_e32 v87, 16, v80
	v_sub_f32_e32 v88, v96, v117
	v_and_b32_e32 v80, 0xffff0000, v80
	v_sub_f32_e32 v89, v97, v118
	v_lshlrev_b32_e32 v90, 16, v81
	v_sub_f32_e32 v91, v99, v119
	v_and_b32_e32 v81, 0xffff0000, v81
	v_add_f32_e32 v88, v88, v80
	v_add_f32_e32 v89, v89, v90
	v_add_f32_e32 v91, v91, v81
	v_add_f32_e32 v86, v86, v87
	v_fma_f32 v80, v95, v88, -v80
	v_fma_f32 v90, v95, v89, -v90
	v_fma_f32 v81, v95, v91, -v81
	v_fma_f32 v87, v95, v86, -v87
	v_cvt_pk_bf16_f32 v80, v87, v80
	v_cvt_pk_bf16_f32 v81, v90, v81
	v_min_i32_e32 v90, 7, v158
	v_add_u32_e32 v90, 1, v90
	v_cvt_f32_i32_e32 v90, v90
	v_and_b32_e32 v85, 0xffff0000, v83
	v_lshlrev_b32_e32 v97, 16, v82
	v_sub_f32_e32 v98, v103, v121
	v_and_b32_e32 v82, 0xffff0000, v82
	v_sub_f32_e32 v99, v104, v122
	v_lshlrev_b32_e32 v83, 16, v83
	v_sub_f32_e32 v96, v100, v120
	v_add_f32_e32 v98, v98, v82
	v_add_f32_e32 v99, v99, v83
	v_add_f32_e32 v84, v84, v85
	v_add_f32_e32 v96, v96, v97
	v_fma_f32 v82, v95, v98, -v82
	v_fma_f32 v83, v95, v99, -v83
	v_rcp_iflag_f32_e32 v90, v90
	v_fma_f32 v97, v95, v96, -v97
	v_fma_f32 v85, v95, v84, -v85
	v_cvt_pk_bf16_f32 v82, v97, v82
	v_cvt_pk_bf16_f32 v83, v83, v85
	ds_write_b128 v160, v[80:83] offset:1584
	v_sub_f32_e32 v80, v84, v131
	v_sub_f32_e32 v82, v86, v124
	v_lshlrev_b32_e32 v83, 16, v76
	v_sub_f32_e32 v84, v88, v125
	v_and_b32_e32 v76, 0xffff0000, v76
	v_sub_f32_e32 v85, v89, v126
	v_lshlrev_b32_e32 v86, 16, v77
	v_sub_f32_e32 v87, v91, v127
	v_and_b32_e32 v77, 0xffff0000, v77
	v_add_f32_e32 v84, v84, v76
	v_add_f32_e32 v85, v85, v86
	v_add_f32_e32 v87, v87, v77
	v_add_f32_e32 v82, v82, v83
	v_fma_f32 v76, v90, v84, -v76
	v_fma_f32 v86, v90, v85, -v86
	v_fma_f32 v77, v90, v87, -v77
	v_fma_f32 v83, v90, v82, -v83
	v_cvt_pk_bf16_f32 v76, v83, v76
	v_cvt_pk_bf16_f32 v77, v86, v77
	v_min_i32_e32 v86, 7, v94
	v_add_u32_e32 v86, 1, v86
	v_cvt_f32_i32_e32 v86, v86
	v_and_b32_e32 v81, 0xffff0000, v79
	v_lshlrev_b32_e32 v89, 16, v78
	v_sub_f32_e32 v91, v98, v129
	v_and_b32_e32 v78, 0xffff0000, v78
	v_sub_f32_e32 v95, v99, v130
	v_lshlrev_b32_e32 v79, 16, v79
	v_sub_f32_e32 v88, v96, v128
	v_add_f32_e32 v91, v91, v78
	v_add_f32_e32 v95, v95, v79
	v_add_f32_e32 v80, v80, v81
	v_add_f32_e32 v88, v88, v89
	v_fma_f32 v78, v90, v91, -v78
	v_fma_f32 v79, v90, v95, -v79
	v_rcp_iflag_f32_e32 v86, v86
	v_fma_f32 v89, v90, v88, -v89
	v_fma_f32 v81, v90, v80, -v81
	v_cvt_pk_bf16_f32 v78, v89, v78
	v_cvt_pk_bf16_f32 v79, v79, v81
	ds_write_b128 v160, v[76:79] offset:2112
	v_sub_f32_e32 v76, v80, v139
	v_sub_f32_e32 v78, v82, v132
	v_lshlrev_b32_e32 v79, 16, v72
	v_sub_f32_e32 v80, v84, v133
	v_and_b32_e32 v72, 0xffff0000, v72
	v_sub_f32_e32 v81, v85, v134
	v_lshlrev_b32_e32 v82, 16, v73
	v_sub_f32_e32 v83, v87, v135
	v_and_b32_e32 v73, 0xffff0000, v73
	v_add_f32_e32 v80, v80, v72
	v_add_f32_e32 v81, v81, v82
	v_add_f32_e32 v83, v83, v73
	v_add_f32_e32 v78, v78, v79
	v_fma_f32 v72, v86, v80, -v72
	v_fma_f32 v82, v86, v81, -v82
	v_fma_f32 v73, v86, v83, -v73
	v_fma_f32 v79, v86, v78, -v79
	v_cvt_pk_bf16_f32 v72, v79, v72
	v_cvt_pk_bf16_f32 v73, v82, v73
	v_min_i32_e32 v82, 7, v93
	v_add_u32_e32 v82, 1, v82
	v_cvt_f32_i32_e32 v82, v82
	v_and_b32_e32 v77, 0xffff0000, v75
	v_sub_f32_e32 v84, v88, v136
	v_lshlrev_b32_e32 v85, 16, v74
	v_sub_f32_e32 v87, v91, v137
	v_and_b32_e32 v74, 0xffff0000, v74
	v_sub_f32_e32 v88, v95, v138
	v_lshlrev_b32_e32 v75, 16, v75
	v_add_f32_e32 v87, v87, v74
	v_add_f32_e32 v88, v88, v75
	v_add_f32_e32 v76, v76, v77
	v_add_f32_e32 v84, v84, v85
	v_fma_f32 v74, v86, v87, -v74
	v_fma_f32 v75, v86, v88, -v75
	v_rcp_iflag_f32_e32 v82, v82
	v_fma_f32 v85, v86, v84, -v85
	v_fma_f32 v77, v86, v76, -v77
	v_cvt_pk_bf16_f32 v74, v85, v74
	v_cvt_pk_bf16_f32 v75, v75, v77
	ds_write_b128 v160, v[72:75] offset:2640
	v_sub_f32_e32 v72, v76, v147
	v_sub_f32_e32 v74, v78, v140
	v_lshlrev_b32_e32 v75, 16, v68
	v_sub_f32_e32 v76, v80, v141
	v_and_b32_e32 v68, 0xffff0000, v68
	v_add_f32_e32 v74, v74, v75
	v_add_f32_e32 v76, v76, v68
	v_lshlrev_b32_e32 v78, 16, v69
	v_sub_f32_e32 v79, v83, v143
	v_and_b32_e32 v69, 0xffff0000, v69
	v_add_f32_e32 v79, v79, v69
	v_fma_f32 v75, v82, v74, -v75
	v_fma_f32 v68, v82, v76, -v68
	v_fma_f32 v69, v82, v79, -v69
	v_cvt_pk_bf16_f32 v68, v75, v68
	v_sub_f32_e32 v75, v79, v151
	v_min_i32_e32 v79, 7, v92
	v_add_u32_e32 v79, 1, v79
	v_cvt_f32_i32_e32 v79, v79
	v_sub_f32_e32 v77, v81, v142
	v_lshlrev_b32_e32 v81, 16, v70
	v_sub_f32_e32 v83, v87, v145
	v_and_b32_e32 v70, 0xffff0000, v70
	v_and_b32_e32 v73, 0xffff0000, v71
	v_sub_f32_e32 v80, v84, v144
	v_add_f32_e32 v83, v83, v70
	v_sub_f32_e32 v84, v88, v146
	v_lshlrev_b32_e32 v71, 16, v71
	v_add_f32_e32 v72, v72, v73
	v_add_f32_e32 v77, v77, v78
	v_add_f32_e32 v80, v80, v81
	v_add_f32_e32 v84, v84, v71
	v_fma_f32 v70, v82, v83, -v70
	v_rcp_iflag_f32_e32 v79, v79
	v_fma_f32 v78, v82, v77, -v78
	v_fma_f32 v81, v82, v80, -v81
	v_fma_f32 v71, v82, v84, -v71
	v_fma_f32 v73, v82, v72, -v73
	v_cvt_pk_bf16_f32 v69, v78, v69
	v_cvt_pk_bf16_f32 v70, v81, v70
	v_cvt_pk_bf16_f32 v71, v71, v73
	ds_write_b128 v160, v[68:71] offset:3168
	v_sub_f32_e32 v68, v72, v155
	v_and_b32_e32 v69, 0xffff0000, v67
	v_sub_f32_e32 v70, v84, v154
	v_lshlrev_b32_e32 v67, 16, v67
	v_and_b32_e32 v72, 0xffff0000, v66
	v_sub_f32_e32 v73, v80, v152
	v_lshlrev_b32_e32 v66, 16, v66
	v_and_b32_e32 v78, 0xffff0000, v65
	v_sub_f32_e32 v77, v77, v150
	v_lshlrev_b32_e32 v65, 16, v65
	v_and_b32_e32 v80, 0xffff0000, v64
	v_sub_f32_e32 v74, v74, v148
	v_lshlrev_b32_e32 v64, 16, v64
	v_add_f32_e32 v70, v70, v67
	v_sub_f32_e32 v71, v83, v153
	v_add_f32_e32 v73, v73, v66
	v_add_f32_e32 v77, v77, v65
	v_sub_f32_e32 v76, v76, v149
	v_add_f32_e32 v74, v74, v64
	v_add_f32_e32 v68, v68, v69
	v_add_f32_e32 v71, v71, v72
	v_add_f32_e32 v75, v75, v78
	v_add_f32_e32 v76, v76, v80
	v_fma_f32 v64, v79, v74, -v64
	v_fma_f32 v65, v79, v77, -v65
	v_fma_f32 v66, v79, v73, -v66
	v_fma_f32 v67, v79, v70, -v67
	v_fma_f32 v74, v79, v76, -v80
	v_fma_f32 v75, v79, v75, -v78
	v_fma_f32 v71, v79, v71, -v72
	v_fma_f32 v68, v79, v68, -v69
	v_cvt_pk_bf16_f32 v64, v64, v74
	v_cvt_pk_bf16_f32 v65, v65, v75
	v_cvt_pk_bf16_f32 v66, v66, v71
	v_cvt_pk_bf16_f32 v67, v67, v68

.LBB0_350:
	s_andn2_b64 vcc, exec, s[16:17]
	s_cbranch_vccnz .LBB0_352
	s_add_u32 s16, s10, s42
	s_addc_u32 s17, s11, s43
	v_lshlrev_b32_e32 v160, 1, v181
	v_lshl_add_u64 v[64:65], s[16:17], 0, v[160:161]
	s_mov_b64 s[16:17], 0x5a00200
	v_lshl_add_u64 v[106:107], v[64:65], 0, s[16:17]
	v_max_i32_e32 v64, 3, v179
	v_max_i32_e32 v66, 2, v179
	v_max_i32_e32 v72, 1, v179
	v_or_b32_e32 v130, 1, v179
	v_or_b32_e32 v131, 2, v179
	v_add_u32_e32 v64, -3, v64
	v_mov_b32_e32 v65, v161
	v_add_u32_e32 v66, -2, v66
	v_mov_b32_e32 v67, v161
	v_add_u32_e32 v72, -1, v72
	v_mov_b32_e32 v73, v161
	v_max_i32_e32 v74, 0, v179
	v_mov_b32_e32 v75, v161
	v_max_i32_e32 v80, 0, v130
	v_mov_b32_e32 v81, v161
	v_max_i32_e32 v82, 0, v131
	v_mov_b32_e32 v83, v161
	v_lshlrev_b64 v[64:65], 13, v[64:65]
	v_lshlrev_b64 v[66:67], 13, v[66:67]
	v_lshlrev_b64 v[72:73], 13, v[72:73]
	v_lshlrev_b64 v[74:75], 13, v[74:75]
	v_lshlrev_b64 v[80:81], 13, v[80:81]
	v_lshlrev_b64 v[82:83], 13, v[82:83]
	v_lshl_add_u64 v[64:65], v[106:107], 0, v[64:65]
	v_lshl_add_u64 v[68:69], v[106:107], 0, v[66:67]
	v_lshl_add_u64 v[72:73], v[106:107], 0, v[72:73]
	v_lshl_add_u64 v[76:77], v[106:107], 0, v[74:75]
	v_lshl_add_u64 v[80:81], v[106:107], 0, v[80:81]
	v_lshl_add_u64 v[84:85], v[106:107], 0, v[82:83]
	v_or_b32_e32 v132, 3, v179
	global_load_dwordx4 v[64:67], v[64:65], off
	s_nop 0
	global_load_dwordx4 v[68:71], v[68:69], off
	s_nop 0
	global_load_dwordx4 v[72:75], v[72:73], off
	s_nop 0
	global_load_dwordx4 v[76:79], v[76:77], off
	s_nop 0
	global_load_dwordx4 v[80:83], v[80:81], off
	s_nop 0
	global_load_dwordx4 v[86:89], v[84:85], off
	v_max_i32_e32 v84, 0, v132
	v_mov_b32_e32 v85, v161
	v_lshlrev_b64 v[84:85], 13, v[84:85]
	v_lshl_add_u64 v[84:85], v[106:107], 0, v[84:85]
	v_or_b32_e32 v133, 4, v179
	global_load_dwordx4 v[90:93], v[84:85], off
	v_max_i32_e32 v84, 0, v133
	v_mov_b32_e32 v85, v161
	v_lshlrev_b64 v[84:85], 13, v[84:85]
	v_lshl_add_u64 v[84:85], v[106:107], 0, v[84:85]
	v_or_b32_e32 v134, 5, v179
	global_load_dwordx4 v[94:97], v[84:85], off
	v_max_i32_e32 v84, 0, v134
	v_mov_b32_e32 v85, v161
	v_lshlrev_b64 v[84:85], 13, v[84:85]
	v_lshl_add_u64 v[84:85], v[106:107], 0, v[84:85]
	v_or_b32_e32 v135, 6, v179
	global_load_dwordx4 v[98:101], v[84:85], off
	v_max_i32_e32 v84, 0, v135
	v_mov_b32_e32 v85, v161
	v_lshlrev_b64 v[84:85], 13, v[84:85]
	v_lshl_add_u64 v[84:85], v[106:107], 0, v[84:85]
	global_load_dwordx4 v[102:105], v[84:85], off
	v_or_b32_e32 v84, 7, v179
	v_max_i32_e32 v108, 0, v84
	v_mov_b32_e32 v109, v161
	v_lshlrev_b64 v[108:109], 13, v[108:109]
	v_lshl_add_u64 v[106:107], v[106:107], 0, v[108:109]
	global_load_dwordx4 v[106:109], v[106:107], off
	v_cmp_lt_i32_e32 vcc, 2, v179
	s_movk_i32 s16, 0x210
	s_barrier
	s_waitcnt vmcnt(10)
	v_cndmask_b32_e32 v113, 0, v67, vcc
	v_cndmask_b32_e32 v112, 0, v66, vcc
	v_cndmask_b32_e32 v111, 0, v65, vcc
	v_cndmask_b32_e32 v110, 0, v64, vcc
	v_cmp_lt_i32_e32 vcc, 1, v179
	s_waitcnt vmcnt(9)
	s_nop 0
	v_cndmask_b32_e32 v117, 0, v71, vcc
	v_cndmask_b32_e32 v116, 0, v70, vcc
	v_cndmask_b32_e32 v115, 0, v69, vcc
	v_cndmask_b32_e32 v114, 0, v68, vcc
	v_cmp_lt_i32_e32 vcc, 0, v179
	s_waitcnt vmcnt(8)
	s_nop 0
	v_cndmask_b32_e32 v121, 0, v75, vcc
	v_cndmask_b32_e32 v120, 0, v74, vcc
	v_cndmask_b32_e32 v119, 0, v73, vcc
	v_cndmask_b32_e32 v118, 0, v72, vcc
	v_cmp_lt_i32_e32 vcc, -1, v179
	s_waitcnt vmcnt(7)
	s_nop 0
	v_cndmask_b32_e32 v125, 0, v79, vcc
	v_cndmask_b32_e32 v124, 0, v78, vcc
	v_cndmask_b32_e32 v123, 0, v77, vcc
	v_cndmask_b32_e32 v122, 0, v76, vcc
	v_cmp_lt_i32_e32 vcc, -2, v179
	s_waitcnt vmcnt(6)
	s_nop 0
	v_cndmask_b32_e32 v129, 0, v83, vcc
	v_cndmask_b32_e32 v128, 0, v82, vcc
	v_cndmask_b32_e32 v127, 0, v81, vcc
	v_cndmask_b32_e32 v126, 0, v80, vcc
	v_cmp_lt_i32_e32 vcc, -3, v179
	s_waitcnt vmcnt(5)
	s_nop 0
	v_cndmask_b32_e32 v89, 0, v89, vcc
	v_cndmask_b32_e32 v88, 0, v88, vcc
	v_cndmask_b32_e32 v87, 0, v87, vcc
	v_cndmask_b32_e32 v86, 0, v86, vcc
	v_cmp_lt_i32_e32 vcc, -4, v179
	s_waitcnt vmcnt(4)
	s_nop 0
	v_cndmask_b32_e32 v83, 0, v93, vcc
	v_cndmask_b32_e32 v82, 0, v92, vcc
	v_cndmask_b32_e32 v81, 0, v91, vcc
	v_cndmask_b32_e32 v80, 0, v90, vcc
	v_cmp_lt_i32_e32 vcc, -5, v179
	v_min_i32_e32 v91, 3, v179
	v_add_u32_e32 v91, 1, v91
	s_waitcnt vmcnt(3)
	v_cndmask_b32_e32 v79, 0, v97, vcc
	v_cndmask_b32_e32 v78, 0, v96, vcc
	v_cndmask_b32_e32 v77, 0, v95, vcc
	v_cndmask_b32_e32 v76, 0, v94, vcc
	v_cmp_lt_i32_e32 vcc, -6, v179
	v_cvt_f32_i32_e32 v91, v91
	v_rcp_iflag_f32_e32 v91, v91
	s_waitcnt vmcnt(2)
	v_cndmask_b32_e32 v75, 0, v101, vcc
	v_cndmask_b32_e32 v74, 0, v100, vcc
	v_cndmask_b32_e32 v73, 0, v99, vcc
	v_cndmask_b32_e32 v72, 0, v98, vcc
	v_cmp_lt_i32_e32 vcc, -7, v179
	s_waitcnt vmcnt(1)
	s_nop 0
	v_cndmask_b32_e32 v71, 0, v105, vcc
	v_cndmask_b32_e32 v70, 0, v104, vcc
	v_cndmask_b32_e32 v69, 0, v103, vcc
	v_cndmask_b32_e32 v68, 0, v102, vcc
	v_cmp_lt_i32_e32 vcc, -8, v179
	s_waitcnt vmcnt(0)
	s_nop 0
	v_cndmask_b32_e32 v67, 0, v109, vcc
	v_cndmask_b32_e32 v66, 0, v108, vcc
	v_cndmask_b32_e32 v65, 0, v107, vcc
	v_cndmask_b32_e32 v64, 0, v106, vcc
	s_nop 0
	v_and_b32_e32 v100, 0xffff0000, v113
	v_and_b32_e32 v108, 0xffff0000, v117
	v_add_f32_e32 v90, 0, v100
	v_lshlrev_b32_e32 v105, 16, v116
	v_and_b32_e32 v106, 0xffff0000, v116
	v_and_b32_e32 v116, 0xffff0000, v121
	v_add_f32_e32 v90, v90, v108
	v_lshlrev_b32_e32 v85, 16, v110
	v_and_b32_e32 v94, 0xffff0000, v110
	v_lshlrev_b32_e32 v103, 16, v115
	v_and_b32_e32 v104, 0xffff0000, v115
	v_lshlrev_b32_e32 v107, 16, v117
	v_lshlrev_b32_e32 v109, 16, v118
	v_and_b32_e32 v110, 0xffff0000, v118
	v_lshlrev_b32_e32 v115, 16, v121
	v_lshlrev_b32_e32 v117, 16, v122
	v_and_b32_e32 v118, 0xffff0000, v122
	v_lshlrev_b32_e32 v121, 16, v124
	v_and_b32_e32 v122, 0xffff0000, v124
	v_and_b32_e32 v124, 0xffff0000, v125
	v_add_f32_e32 v90, v90, v116
	v_lshlrev_b32_e32 v95, 16, v111
	v_and_b32_e32 v96, 0xffff0000, v111
	v_lshlrev_b32_e32 v97, 16, v112
	v_and_b32_e32 v98, 0xffff0000, v112
	v_lshlrev_b32_e32 v99, 16, v113
	v_lshlrev_b32_e32 v101, 16, v114
	v_and_b32_e32 v102, 0xffff0000, v114
	v_lshlrev_b32_e32 v111, 16, v119
	v_and_b32_e32 v112, 0xffff0000, v119
	v_lshlrev_b32_e32 v113, 16, v120
	v_and_b32_e32 v114, 0xffff0000, v120
	v_lshlrev_b32_e32 v119, 16, v123
	v_and_b32_e32 v120, 0xffff0000, v123
	v_lshlrev_b32_e32 v123, 16, v125
	v_add_f32_e32 v125, v90, v124
	v_add_f32_e32 v90, 0, v85
	v_add_f32_e32 v90, v90, v101
	v_add_f32_e32 v90, v90, v109
	v_add_f32_e32 v136, v90, v117
	v_add_f32_e32 v90, 0, v94
	v_add_f32_e32 v90, v90, v102
	v_add_f32_e32 v90, v90, v110
	v_add_f32_e32 v137, v90, v118
	v_add_f32_e32 v90, 0, v95
	v_add_f32_e32 v90, v90, v103
	v_add_f32_e32 v90, v90, v111
	v_add_f32_e32 v138, v90, v119
	v_add_f32_e32 v90, 0, v96
	v_add_f32_e32 v90, v90, v104
	v_add_f32_e32 v90, v90, v112
	v_add_f32_e32 v139, v90, v120
	v_add_f32_e32 v90, 0, v97
	v_add_f32_e32 v90, v90, v105
	v_add_f32_e32 v90, v90, v113
	v_add_f32_e32 v140, v90, v121
	v_add_f32_e32 v90, 0, v98
	v_add_f32_e32 v90, v90, v106
	v_add_f32_e32 v90, v90, v114
	v_add_f32_e32 v141, v90, v122
	v_add_f32_e32 v90, 0, v99
	v_add_f32_e32 v90, v90, v107
	v_add_f32_e32 v90, v90, v115
	v_add_f32_e32 v142, v90, v123
	v_fma_f32 v90, v91, v136, -v117
	v_fma_f32 v143, v91, v139, -v120
	v_fma_f32 v92, v91, v137, -v118
	v_fma_f32 v93, v91, v138, -v119
	v_fma_f32 v144, v91, v140, -v121
	v_fma_f32 v145, v91, v141, -v122
	v_fma_f32 v146, v91, v142, -v123
	v_fma_f32 v147, v91, v125, -v124
	v_cvt_pk_bf16_f32 v90, v90, v92
	v_cvt_pk_bf16_f32 v91, v93, v143
	v_mul_lo_u32 v143, v180, s16
	v_add3_u32 v143, 0, v160, v143
	v_cvt_pk_bf16_f32 v92, v144, v145
	v_cvt_pk_bf16_f32 v93, v146, v147
	ds_write_b128 v143, v[90:93]
	v_lshlrev_b32_e32 v147, 16, v129
	v_and_b32_e32 v129, 0xffff0000, v129
	v_sub_f32_e32 v90, v125, v100
	v_lshlrev_b32_e32 v144, 16, v126
	v_and_b32_e32 v126, 0xffff0000, v126
	v_add_f32_e32 v100, v90, v129
	v_sub_f32_e32 v90, v137, v94
	v_lshlrev_b32_e32 v145, 16, v127
	v_add_f32_e32 v94, v90, v126
	v_sub_f32_e32 v90, v138, v95
	v_and_b32_e32 v127, 0xffff0000, v127
	v_add_f32_e32 v95, v90, v145
	v_sub_f32_e32 v90, v139, v96
	v_add_f32_e32 v96, v90, v127
	v_min_i32_e32 v90, 3, v130
	v_add_u32_e32 v90, 1, v90
	v_cvt_f32_i32_e32 v90, v90
	v_lshlrev_b32_e32 v146, 16, v128
	v_sub_f32_e32 v91, v140, v97
	v_and_b32_e32 v128, 0xffff0000, v128
	v_rcp_iflag_f32_e32 v90, v90
	v_sub_f32_e32 v85, v136, v85
	v_add_f32_e32 v97, v91, v146
	v_sub_f32_e32 v91, v141, v98
	v_add_f32_e32 v85, v85, v144
	v_add_f32_e32 v98, v91, v128
	v_sub_f32_e32 v91, v142, v99
	v_add_f32_e32 v99, v91, v147
	v_fma_f32 v91, v90, v85, -v144
	v_fma_f32 v92, v90, v94, -v126
	v_fma_f32 v93, v90, v95, -v145
	v_fma_f32 v125, v90, v96, -v127
	v_fma_f32 v130, v90, v97, -v146
	v_fma_f32 v136, v90, v98, -v128
	v_fma_f32 v137, v90, v99, -v147
	v_fma_f32 v138, v90, v100, -v129
	v_cvt_pk_bf16_f32 v90, v91, v92
	v_cvt_pk_bf16_f32 v91, v93, v125
	v_cvt_pk_bf16_f32 v92, v130, v136
	v_cvt_pk_bf16_f32 v93, v137, v138
	ds_write_b128 v143, v[90:93] offset:528
	v_lshlrev_b32_e32 v90, 16, v86
	v_and_b32_e32 v91, 0xffff0000, v86
	v_and_b32_e32 v137, 0xffff0000, v89
	v_sub_f32_e32 v86, v100, v108
	v_add_f32_e32 v100, v86, v137
	v_sub_f32_e32 v86, v94, v102
	v_lshlrev_b32_e32 v92, 16, v87
	v_add_f32_e32 v94, v86, v91
	v_sub_f32_e32 v86, v95, v103
	v_and_b32_e32 v93, 0xffff0000, v87
	v_add_f32_e32 v95, v86, v92
	v_sub_f32_e32 v86, v96, v104
	v_add_f32_e32 v96, v86, v93
	v_min_i32_e32 v86, 3, v131
	v_add_u32_e32 v86, 1, v86
	v_cvt_f32_i32_e32 v86, v86
	v_lshlrev_b32_e32 v125, 16, v88
	v_sub_f32_e32 v87, v97, v105
	v_and_b32_e32 v130, 0xffff0000, v88
	v_rcp_iflag_f32_e32 v86, v86
	v_sub_f32_e32 v85, v85, v101
	v_add_f32_e32 v97, v87, v125
	v_sub_f32_e32 v87, v98, v106
	v_lshlrev_b32_e32 v136, 16, v89
	v_add_f32_e32 v85, v85, v90
	v_add_f32_e32 v98, v87, v130
	v_sub_f32_e32 v87, v99, v107
	v_add_f32_e32 v99, v87, v136
	v_fma_f32 v87, v86, v85, -v90
	v_fma_f32 v88, v86, v94, -v91
	v_fma_f32 v89, v86, v95, -v92
	v_fma_f32 v101, v86, v96, -v93
	v_fma_f32 v102, v86, v97, -v125
	v_fma_f32 v103, v86, v98, -v130
	v_fma_f32 v104, v86, v99, -v136
	v_fma_f32 v105, v86, v100, -v137
	v_cvt_pk_bf16_f32 v86, v87, v88
	v_cvt_pk_bf16_f32 v87, v89, v101
	v_cvt_pk_bf16_f32 v88, v102, v103
	v_cvt_pk_bf16_f32 v89, v104, v105
	ds_write_b128 v143, v[86:89] offset:1056
	v_lshlrev_b32_e32 v86, 16, v80
	v_and_b32_e32 v87, 0xffff0000, v80
	v_and_b32_e32 v104, 0xffff0000, v83
	v_sub_f32_e32 v80, v100, v116
	v_add_f32_e32 v100, v80, v104
	v_sub_f32_e32 v80, v85, v109
	v_add_f32_e32 v85, v80, v86
	v_sub_f32_e32 v80, v94, v110
	v_lshlrev_b32_e32 v88, 16, v81
	v_add_f32_e32 v94, v80, v87
	v_sub_f32_e32 v80, v95, v111
	v_and_b32_e32 v89, 0xffff0000, v81
	v_add_f32_e32 v95, v80, v88
	v_sub_f32_e32 v80, v96, v112
	v_add_f32_e32 v96, v80, v89
	v_min_i32_e32 v80, 3, v132
	v_add_u32_e32 v80, 1, v80
	v_cvt_f32_i32_e32 v80, v80
	v_lshlrev_b32_e32 v101, 16, v82
	v_sub_f32_e32 v81, v97, v113
	v_and_b32_e32 v102, 0xffff0000, v82
	v_rcp_iflag_f32_e32 v80, v80
	v_add_f32_e32 v97, v81, v101
	v_sub_f32_e32 v81, v98, v114
	v_lshlrev_b32_e32 v103, 16, v83
	v_add_f32_e32 v98, v81, v102
	v_sub_f32_e32 v81, v99, v115
	v_add_f32_e32 v99, v81, v103
	v_fma_f32 v81, v80, v85, -v86
	v_fma_f32 v105, v80, v96, -v89
	v_fma_f32 v82, v80, v94, -v87
	v_fma_f32 v83, v80, v95, -v88
	v_fma_f32 v106, v80, v97, -v101
	v_fma_f32 v107, v80, v98, -v102
	v_fma_f32 v108, v80, v99, -v103
	v_fma_f32 v109, v80, v100, -v104
	v_cvt_pk_bf16_f32 v80, v81, v82
	v_cvt_pk_bf16_f32 v81, v83, v105
	v_min_i32_e32 v105, 3, v133
	v_add_u32_e32 v105, 1, v105
	v_cvt_f32_i32_e32 v105, v105
	v_cvt_pk_bf16_f32 v82, v106, v107
	v_cvt_pk_bf16_f32 v83, v108, v109
	ds_write_b128 v143, v[80:83] offset:1584
	v_rcp_iflag_f32_e32 v105, v105
	v_sub_f32_e32 v82, v85, v117
	v_lshlrev_b32_e32 v83, 16, v76
	v_sub_f32_e32 v85, v94, v118
	v_and_b32_e32 v76, 0xffff0000, v76
	v_sub_f32_e32 v94, v95, v119
	v_lshlrev_b32_e32 v95, 16, v77
	v_sub_f32_e32 v96, v96, v120
	v_and_b32_e32 v77, 0xffff0000, v77
	v_add_f32_e32 v85, v85, v76
	v_add_f32_e32 v94, v94, v95
	v_add_f32_e32 v96, v96, v77
	v_add_f32_e32 v82, v82, v83
	v_fma_f32 v76, v105, v85, -v76
	v_fma_f32 v95, v105, v94, -v95
	v_fma_f32 v77, v105, v96, -v77
	v_fma_f32 v83, v105, v82, -v83
	v_cvt_pk_bf16_f32 v76, v83, v76
	v_cvt_pk_bf16_f32 v77, v95, v77
	v_min_i32_e32 v95, 3, v134
	v_add_u32_e32 v95, 1, v95
	v_cvt_f32_i32_e32 v95, v95
	v_sub_f32_e32 v80, v100, v124
	v_and_b32_e32 v81, 0xffff0000, v79
	v_lshlrev_b32_e32 v100, 16, v78
	v_sub_f32_e32 v98, v98, v122
	v_and_b32_e32 v78, 0xffff0000, v78
	v_sub_f32_e32 v99, v99, v123
	v_lshlrev_b32_e32 v79, 16, v79
	v_sub_f32_e32 v97, v97, v121
	v_add_f32_e32 v98, v98, v78
	v_add_f32_e32 v99, v99, v79
	v_add_f32_e32 v80, v80, v81
	v_add_f32_e32 v97, v97, v100
	v_fma_f32 v78, v105, v98, -v78
	v_fma_f32 v79, v105, v99, -v79
	v_rcp_iflag_f32_e32 v95, v95
	v_fma_f32 v100, v105, v97, -v100
	v_fma_f32 v81, v105, v80, -v81
	v_cvt_pk_bf16_f32 v78, v100, v78
	v_cvt_pk_bf16_f32 v79, v79, v81
	ds_write_b128 v143, v[76:79] offset:2112
	v_sub_f32_e32 v76, v80, v129
	v_sub_f32_e32 v78, v82, v144
	v_lshlrev_b32_e32 v79, 16, v72
	v_sub_f32_e32 v80, v85, v126
	v_and_b32_e32 v72, 0xffff0000, v72
	v_sub_f32_e32 v81, v94, v145
	v_lshlrev_b32_e32 v82, 16, v73
	v_sub_f32_e32 v83, v96, v127
	v_and_b32_e32 v73, 0xffff0000, v73
	v_add_f32_e32 v80, v80, v72
	v_add_f32_e32 v81, v81, v82
	v_add_f32_e32 v83, v83, v73
	v_add_f32_e32 v78, v78, v79
	v_fma_f32 v72, v95, v80, -v72
	v_fma_f32 v82, v95, v81, -v82
	v_fma_f32 v73, v95, v83, -v73
	v_fma_f32 v79, v95, v78, -v79
	v_cvt_pk_bf16_f32 v72, v79, v72
	v_cvt_pk_bf16_f32 v73, v82, v73
	v_min_i32_e32 v82, 3, v135
	v_add_u32_e32 v82, 1, v82
	v_cvt_f32_i32_e32 v82, v82
	v_and_b32_e32 v77, 0xffff0000, v75
	v_sub_f32_e32 v85, v97, v146
	v_lshlrev_b32_e32 v94, 16, v74
	v_sub_f32_e32 v96, v98, v128
	v_and_b32_e32 v74, 0xffff0000, v74
	v_sub_f32_e32 v97, v99, v147
	v_lshlrev_b32_e32 v75, 16, v75
	v_add_f32_e32 v96, v96, v74
	v_add_f32_e32 v97, v97, v75
	v_add_f32_e32 v76, v76, v77
	v_add_f32_e32 v85, v85, v94
	v_fma_f32 v74, v95, v96, -v74
	v_fma_f32 v75, v95, v97, -v75
	v_rcp_iflag_f32_e32 v82, v82
	v_fma_f32 v94, v95, v85, -v94
	v_fma_f32 v77, v95, v76, -v77
	v_cvt_pk_bf16_f32 v74, v94, v74
	v_cvt_pk_bf16_f32 v75, v75, v77
	ds_write_b128 v143, v[72:75] offset:2640
	v_sub_f32_e32 v72, v76, v137
	v_sub_f32_e32 v74, v78, v90
	v_lshlrev_b32_e32 v75, 16, v68
	v_sub_f32_e32 v76, v80, v91
	v_and_b32_e32 v68, 0xffff0000, v68
	v_add_f32_e32 v74, v74, v75
	v_add_f32_e32 v76, v76, v68
	v_lshlrev_b32_e32 v78, 16, v69
	v_sub_f32_e32 v79, v83, v93
	v_and_b32_e32 v69, 0xffff0000, v69
	v_add_f32_e32 v79, v79, v69
	v_fma_f32 v75, v82, v74, -v75
	v_fma_f32 v68, v82, v76, -v68
	v_fma_f32 v69, v82, v79, -v69
	v_cvt_pk_bf16_f32 v68, v75, v68
	v_sub_f32_e32 v75, v79, v89
	v_min_i32_e32 v79, 3, v84
	v_add_u32_e32 v79, 1, v79
	v_cvt_f32_i32_e32 v79, v79
	v_sub_f32_e32 v77, v81, v92
	v_lshlrev_b32_e32 v81, 16, v70
	v_sub_f32_e32 v83, v96, v130
	v_and_b32_e32 v70, 0xffff0000, v70
	v_and_b32_e32 v73, 0xffff0000, v71
	v_sub_f32_e32 v80, v85, v125
	v_add_f32_e32 v83, v83, v70
	v_sub_f32_e32 v85, v97, v136
	v_lshlrev_b32_e32 v71, 16, v71
	v_add_f32_e32 v72, v72, v73
	v_add_f32_e32 v77, v77, v78
	v_add_f32_e32 v80, v80, v81
	v_add_f32_e32 v85, v85, v71
	v_fma_f32 v70, v82, v83, -v70
	v_rcp_iflag_f32_e32 v79, v79
	v_fma_f32 v78, v82, v77, -v78
	v_fma_f32 v81, v82, v80, -v81
	v_fma_f32 v71, v82, v85, -v71
	v_fma_f32 v73, v82, v72, -v73
	v_cvt_pk_bf16_f32 v69, v78, v69
	v_cvt_pk_bf16_f32 v70, v81, v70
	v_cvt_pk_bf16_f32 v71, v71, v73
	ds_write_b128 v143, v[68:71] offset:3168
	v_sub_f32_e32 v68, v72, v104
	v_and_b32_e32 v69, 0xffff0000, v67
	v_sub_f32_e32 v70, v85, v103
	v_lshlrev_b32_e32 v67, 16, v67
	v_and_b32_e32 v72, 0xffff0000, v66
	v_sub_f32_e32 v73, v80, v101
	v_lshlrev_b32_e32 v66, 16, v66
	v_and_b32_e32 v78, 0xffff0000, v65
	v_sub_f32_e32 v77, v77, v88
	v_lshlrev_b32_e32 v65, 16, v65
	v_and_b32_e32 v80, 0xffff0000, v64
	v_sub_f32_e32 v74, v74, v86
	v_lshlrev_b32_e32 v64, 16, v64
	v_add_f32_e32 v70, v70, v67
	v_sub_f32_e32 v71, v83, v102
	v_add_f32_e32 v73, v73, v66
	v_add_f32_e32 v77, v77, v65
	v_sub_f32_e32 v76, v76, v87
	v_add_f32_e32 v74, v74, v64
	v_add_f32_e32 v68, v68, v69
	v_add_f32_e32 v71, v71, v72
	v_add_f32_e32 v75, v75, v78
	v_add_f32_e32 v76, v76, v80
	v_fma_f32 v64, v79, v74, -v64
	v_fma_f32 v65, v79, v77, -v65
	v_fma_f32 v66, v79, v73, -v66
	v_fma_f32 v67, v79, v70, -v67
	v_fma_f32 v74, v79, v76, -v80
	v_fma_f32 v75, v79, v75, -v78
	v_fma_f32 v71, v79, v71, -v72
	v_fma_f32 v68, v79, v68, -v69
	v_cvt_pk_bf16_f32 v64, v64, v74
	v_cvt_pk_bf16_f32 v65, v65, v75
	v_cvt_pk_bf16_f32 v66, v66, v71
	v_cvt_pk_bf16_f32 v67, v67, v68

.LBB0_353:
	s_andn2_b64 vcc, exec, s[16:17]
	v_lshlrev_b32_e32 v160, 1, v181
	s_cbranch_vccnz .LBB0_355
	s_add_u32 s16, s0, s42
	v_max_i32_e32 v64, 1, v179
	s_addc_u32 s17, s1, s43
	v_add_u32_e32 v64, -1, v64
	v_mov_b32_e32 v65, v161
	v_max_i32_e32 v66, 0, v179
	v_mov_b32_e32 v67, v161
	v_lshl_add_u64 v[96:97], s[16:17], 0, v[160:161]
	v_lshlrev_b64 v[64:65], 13, v[64:65]
	v_lshlrev_b64 v[66:67], 13, v[66:67]
	v_or_b32_e32 v116, 1, v179
	v_or_b32_e32 v117, 2, v179
	v_lshl_add_u64 v[64:65], v[96:97], 0, v[64:65]
	v_lshl_add_u64 v[68:69], v[96:97], 0, v[66:67]
	v_max_i32_e32 v72, 0, v116
	v_mov_b32_e32 v73, v161
	v_max_i32_e32 v74, 0, v117
	v_mov_b32_e32 v75, v161
	v_or_b32_e32 v118, 3, v179
	global_load_dwordx4 v[64:67], v[64:65], off
	s_nop 0
	global_load_dwordx4 v[68:71], v[68:69], off
	v_lshlrev_b64 v[72:73], 13, v[72:73]
	v_lshlrev_b64 v[74:75], 13, v[74:75]
	v_max_i32_e32 v80, 0, v118
	v_mov_b32_e32 v81, v161
	v_or_b32_e32 v119, 4, v179
	v_lshl_add_u64 v[72:73], v[96:97], 0, v[72:73]
	v_lshl_add_u64 v[76:77], v[96:97], 0, v[74:75]
	v_lshlrev_b64 v[80:81], 13, v[80:81]
	v_max_i32_e32 v84, 0, v119
	v_mov_b32_e32 v85, v161
	v_or_b32_e32 v120, 5, v179
	global_load_dwordx4 v[72:75], v[72:73], off
	s_nop 0
	global_load_dwordx4 v[76:79], v[76:77], off
	v_lshl_add_u64 v[80:81], v[96:97], 0, v[80:81]
	v_lshlrev_b64 v[84:85], 13, v[84:85]
	v_max_i32_e32 v88, 0, v120
	v_mov_b32_e32 v89, v161
	v_or_b32_e32 v121, 6, v179
	global_load_dwordx4 v[80:83], v[80:81], off
	v_lshl_add_u64 v[84:85], v[96:97], 0, v[84:85]
	v_lshlrev_b64 v[88:89], 13, v[88:89]
	v_max_i32_e32 v92, 0, v121
	v_mov_b32_e32 v93, v161
	v_or_b32_e32 v122, 7, v179
	global_load_dwordx4 v[84:87], v[84:85], off
	v_lshl_add_u64 v[88:89], v[96:97], 0, v[88:89]
	v_lshlrev_b64 v[92:93], 13, v[92:93]
	v_max_i32_e32 v98, 0, v122
	v_mov_b32_e32 v99, v161
	global_load_dwordx4 v[88:91], v[88:89], off
	v_lshl_add_u64 v[92:93], v[96:97], 0, v[92:93]
	v_lshlrev_b64 v[98:99], 13, v[98:99]
	global_load_dwordx4 v[92:95], v[92:93], off
	v_lshl_add_u64 v[96:97], v[96:97], 0, v[98:99]
	global_load_dwordx4 v[96:99], v[96:97], off
	v_cmp_lt_i32_e32 vcc, 0, v179
	s_movk_i32 s16, 0x210
	s_barrier
	s_waitcnt vmcnt(8)
	v_cndmask_b32_e32 v103, 0, v67, vcc
	v_cndmask_b32_e32 v102, 0, v66, vcc
	v_cndmask_b32_e32 v101, 0, v65, vcc
	v_cndmask_b32_e32 v100, 0, v64, vcc
	v_cmp_lt_i32_e32 vcc, -1, v179
	s_waitcnt vmcnt(7)
	s_nop 0
	v_cndmask_b32_e32 v107, 0, v71, vcc
	v_cndmask_b32_e32 v106, 0, v70, vcc
	v_cndmask_b32_e32 v105, 0, v69, vcc
	v_cndmask_b32_e32 v104, 0, v68, vcc
	v_cmp_lt_i32_e32 vcc, -2, v179
	s_waitcnt vmcnt(6)
	s_nop 0
	v_cndmask_b32_e32 v111, 0, v75, vcc
	v_cndmask_b32_e32 v110, 0, v74, vcc
	v_cndmask_b32_e32 v109, 0, v73, vcc
	v_cndmask_b32_e32 v108, 0, v72, vcc
	v_cmp_lt_i32_e32 vcc, -3, v179
	s_waitcnt vmcnt(5)
	s_nop 0
	v_cndmask_b32_e32 v115, 0, v79, vcc
	v_cndmask_b32_e32 v114, 0, v78, vcc
	v_cndmask_b32_e32 v113, 0, v77, vcc
	v_cndmask_b32_e32 v112, 0, v76, vcc
	v_cmp_lt_i32_e32 vcc, -4, v179
	s_waitcnt vmcnt(4)
	s_nop 0
	v_cndmask_b32_e32 v83, 0, v83, vcc
	v_cndmask_b32_e32 v82, 0, v82, vcc
	v_cndmask_b32_e32 v81, 0, v81, vcc
	v_cndmask_b32_e32 v80, 0, v80, vcc
	v_cmp_lt_i32_e32 vcc, -5, v179
	s_waitcnt vmcnt(3)
	s_nop 0
	v_cndmask_b32_e32 v79, 0, v87, vcc
	v_cndmask_b32_e32 v78, 0, v86, vcc
	v_cndmask_b32_e32 v77, 0, v85, vcc
	v_cndmask_b32_e32 v76, 0, v84, vcc
	v_cmp_lt_i32_e32 vcc, -6, v179
	s_waitcnt vmcnt(2)
	s_nop 0
	v_cndmask_b32_e32 v75, 0, v91, vcc
	v_cndmask_b32_e32 v74, 0, v90, vcc
	v_cndmask_b32_e32 v73, 0, v89, vcc
	v_cndmask_b32_e32 v72, 0, v88, vcc
	v_cmp_lt_i32_e32 vcc, -7, v179
	s_waitcnt vmcnt(1)
	s_nop 0
	v_cndmask_b32_e32 v71, 0, v95, vcc
	v_cndmask_b32_e32 v70, 0, v94, vcc
	v_cndmask_b32_e32 v69, 0, v93, vcc
	v_cndmask_b32_e32 v68, 0, v92, vcc
	v_cmp_lt_i32_e32 vcc, -8, v179
	s_waitcnt vmcnt(0)
	s_nop 0
	v_cndmask_b32_e32 v67, 0, v99, vcc
	v_cndmask_b32_e32 v66, 0, v98, vcc
	v_cndmask_b32_e32 v65, 0, v97, vcc
	v_cndmask_b32_e32 v64, 0, v96, vcc
	s_nop 0
	v_and_b32_e32 v95, 0xffff0000, v103
	v_lshlrev_b32_e32 v88, 16, v100
	v_lshlrev_b32_e32 v94, 16, v103
	v_and_b32_e32 v103, 0xffff0000, v107
	v_add_f32_e32 v84, 0, v95
	v_and_b32_e32 v89, 0xffff0000, v100
	v_lshlrev_b32_e32 v96, 16, v104
	v_and_b32_e32 v97, 0xffff0000, v104
	v_add_f32_e32 v104, v84, v103
	v_add_f32_e32 v84, 0, v88
	v_lshlrev_b32_e32 v90, 16, v101
	v_lshlrev_b32_e32 v98, 16, v105
	v_and_b32_e32 v99, 0xffff0000, v105
	v_add_f32_e32 v105, v84, v96
	v_add_f32_e32 v84, 0, v89
	v_and_b32_e32 v91, 0xffff0000, v101
	v_lshlrev_b32_e32 v100, 16, v106
	v_and_b32_e32 v101, 0xffff0000, v106
	v_add_f32_e32 v106, v84, v97
	v_add_f32_e32 v84, 0, v90
	v_lshlrev_b32_e32 v92, 16, v102
	v_and_b32_e32 v93, 0xffff0000, v102
	v_lshlrev_b32_e32 v102, 16, v107
	v_add_f32_e32 v107, v84, v98
	v_add_f32_e32 v84, 0, v91
	v_add_f32_e32 v123, v84, v99
	v_min_i32_e32 v84, 2, v116
	v_cvt_f32_i32_e32 v84, v84
	v_add_f32_e32 v85, 0, v92
	v_add_f32_e32 v116, v85, v100
	v_add_f32_e32 v85, 0, v93
	v_rcp_iflag_f32_e32 v84, v84
	v_add_f32_e32 v124, v85, v101
	v_add_f32_e32 v85, 0, v94
	v_add_f32_e32 v125, v85, v102
	v_fma_f32 v85, v84, v105, -v96
	v_fma_f32 v126, v84, v123, -v99
	v_fma_f32 v86, v84, v106, -v97
	v_fma_f32 v87, v84, v107, -v98
	v_fma_f32 v127, v84, v116, -v100
	v_fma_f32 v128, v84, v124, -v101
	v_fma_f32 v129, v84, v125, -v102
	v_fma_f32 v130, v84, v104, -v103
	v_cvt_pk_bf16_f32 v84, v85, v86
	v_cvt_pk_bf16_f32 v85, v87, v126
	v_mul_lo_u32 v126, v180, s16
	v_add3_u32 v126, 0, v160, v126
	v_cvt_pk_bf16_f32 v86, v127, v128
	v_cvt_pk_bf16_f32 v87, v129, v130
	ds_write_b128 v126, v[84:87]
	v_lshlrev_b32_e32 v130, 16, v111
	v_and_b32_e32 v111, 0xffff0000, v111
	v_sub_f32_e32 v84, v104, v95
	v_lshlrev_b32_e32 v127, 16, v108
	v_add_f32_e32 v95, v84, v111
	v_sub_f32_e32 v84, v105, v88
	v_and_b32_e32 v108, 0xffff0000, v108
	v_add_f32_e32 v88, v84, v127
	v_sub_f32_e32 v84, v106, v89
	v_lshlrev_b32_e32 v128, 16, v109
	v_add_f32_e32 v89, v84, v108
	v_sub_f32_e32 v84, v107, v90
	v_and_b32_e32 v109, 0xffff0000, v109
	v_add_f32_e32 v90, v84, v128
	v_sub_f32_e32 v84, v123, v91
	v_add_f32_e32 v91, v84, v109
	v_min_i32_e32 v84, 2, v117
	v_cvt_f32_i32_e32 v84, v84
	v_lshlrev_b32_e32 v129, 16, v110
	v_sub_f32_e32 v85, v116, v92
	v_and_b32_e32 v110, 0xffff0000, v110
	v_rcp_iflag_f32_e32 v84, v84
	v_add_f32_e32 v92, v85, v129
	v_sub_f32_e32 v85, v124, v93
	v_add_f32_e32 v93, v85, v110
	v_sub_f32_e32 v85, v125, v94
	v_add_f32_e32 v94, v85, v130
	v_fma_f32 v85, v84, v88, -v127
	v_fma_f32 v86, v84, v89, -v108
	v_fma_f32 v87, v84, v90, -v128
	v_fma_f32 v104, v84, v91, -v109
	v_fma_f32 v105, v84, v92, -v129
	v_fma_f32 v106, v84, v93, -v110
	v_fma_f32 v107, v84, v94, -v130
	v_fma_f32 v116, v84, v95, -v111
	v_cvt_pk_bf16_f32 v84, v85, v86
	v_cvt_pk_bf16_f32 v85, v87, v104
	v_cvt_pk_bf16_f32 v86, v105, v106
	v_cvt_pk_bf16_f32 v87, v107, v116
	ds_write_b128 v126, v[84:87] offset:528
	v_lshlrev_b32_e32 v104, 16, v112
	v_and_b32_e32 v105, 0xffff0000, v112
	v_lshlrev_b32_e32 v106, 16, v113
	v_and_b32_e32 v107, 0xffff0000, v113
	v_lshlrev_b32_e32 v112, 16, v114
	v_and_b32_e32 v113, 0xffff0000, v114
	v_lshlrev_b32_e32 v114, 16, v115
	v_and_b32_e32 v115, 0xffff0000, v115
	v_sub_f32_e32 v84, v95, v103
	v_add_f32_e32 v95, v84, v115
	v_sub_f32_e32 v84, v88, v96
	v_add_f32_e32 v88, v84, v104
	v_sub_f32_e32 v84, v89, v97
	v_add_f32_e32 v89, v84, v105
	v_sub_f32_e32 v84, v90, v98
	v_add_f32_e32 v90, v84, v106
	v_sub_f32_e32 v84, v91, v99
	v_add_f32_e32 v91, v84, v107
	v_min_i32_e32 v84, 2, v118
	v_cvt_f32_i32_e32 v84, v84
	v_sub_f32_e32 v85, v92, v100
	v_add_f32_e32 v92, v85, v112
	v_sub_f32_e32 v85, v93, v101
	v_rcp_iflag_f32_e32 v84, v84
	v_add_f32_e32 v93, v85, v113
	v_sub_f32_e32 v85, v94, v102
	v_add_f32_e32 v94, v85, v114
	v_fma_f32 v85, v84, v88, -v104
	v_fma_f32 v86, v84, v89, -v105
	v_fma_f32 v87, v84, v90, -v106
	v_fma_f32 v96, v84, v91, -v107
	v_fma_f32 v97, v84, v92, -v112
	v_fma_f32 v98, v84, v93, -v113
	v_fma_f32 v99, v84, v94, -v114
	v_fma_f32 v100, v84, v95, -v115
	v_cvt_pk_bf16_f32 v84, v85, v86
	v_cvt_pk_bf16_f32 v85, v87, v96
	v_cvt_pk_bf16_f32 v86, v97, v98
	v_cvt_pk_bf16_f32 v87, v99, v100
	ds_write_b128 v126, v[84:87] offset:1056
	v_lshlrev_b32_e32 v84, 16, v80
	v_and_b32_e32 v85, 0xffff0000, v80
	v_and_b32_e32 v99, 0xffff0000, v83
	v_sub_f32_e32 v80, v95, v111
	v_add_f32_e32 v95, v80, v99
	v_sub_f32_e32 v80, v88, v127
	v_add_f32_e32 v88, v80, v84
	v_sub_f32_e32 v80, v89, v108
	v_lshlrev_b32_e32 v86, 16, v81
	v_add_f32_e32 v89, v80, v85
	v_sub_f32_e32 v80, v90, v128
	v_and_b32_e32 v87, 0xffff0000, v81
	v_add_f32_e32 v90, v80, v86
	v_sub_f32_e32 v80, v91, v109
	v_add_f32_e32 v91, v80, v87
	v_min_i32_e32 v80, 2, v119
	v_cvt_f32_i32_e32 v80, v80
	v_lshlrev_b32_e32 v96, 16, v82
	v_sub_f32_e32 v81, v92, v129
	v_and_b32_e32 v97, 0xffff0000, v82
	v_rcp_iflag_f32_e32 v80, v80
	v_add_f32_e32 v92, v81, v96
	v_sub_f32_e32 v81, v93, v110
	v_lshlrev_b32_e32 v98, 16, v83
	v_add_f32_e32 v93, v81, v97
	v_sub_f32_e32 v81, v94, v130
	v_add_f32_e32 v94, v81, v98
	v_fma_f32 v81, v80, v88, -v84
	v_fma_f32 v82, v80, v89, -v85
	v_fma_f32 v83, v80, v90, -v86
	v_fma_f32 v100, v80, v91, -v87
	v_fma_f32 v101, v80, v92, -v96
	v_fma_f32 v102, v80, v93, -v97
	v_fma_f32 v103, v80, v94, -v98
	v_fma_f32 v108, v80, v95, -v99
	v_cvt_pk_bf16_f32 v80, v81, v82
	v_cvt_pk_bf16_f32 v81, v83, v100
	v_cvt_pk_bf16_f32 v82, v101, v102
	v_cvt_pk_bf16_f32 v83, v103, v108
	ds_write_b128 v126, v[80:83] offset:1584
	v_lshlrev_b32_e32 v80, 16, v76
	v_and_b32_e32 v81, 0xffff0000, v76
	v_and_b32_e32 v103, 0xffff0000, v79
	v_sub_f32_e32 v76, v95, v115
	v_add_f32_e32 v95, v76, v103
	v_sub_f32_e32 v76, v88, v104
	v_add_f32_e32 v88, v76, v80
	v_sub_f32_e32 v76, v89, v105
	v_lshlrev_b32_e32 v82, 16, v77
	v_add_f32_e32 v89, v76, v81
	v_sub_f32_e32 v76, v90, v106
	v_and_b32_e32 v83, 0xffff0000, v77
	v_add_f32_e32 v90, v76, v82
	v_sub_f32_e32 v76, v91, v107
	v_add_f32_e32 v91, v76, v83
	v_min_i32_e32 v76, 2, v120
	v_cvt_f32_i32_e32 v76, v76
	v_lshlrev_b32_e32 v100, 16, v78
	v_sub_f32_e32 v77, v92, v112
	v_and_b32_e32 v101, 0xffff0000, v78
	v_rcp_iflag_f32_e32 v76, v76
	v_add_f32_e32 v92, v77, v100
	v_sub_f32_e32 v77, v93, v113
	v_lshlrev_b32_e32 v102, 16, v79
	v_add_f32_e32 v93, v77, v101
	v_sub_f32_e32 v77, v94, v114
	v_add_f32_e32 v94, v77, v102
	v_fma_f32 v77, v76, v88, -v80
	v_fma_f32 v78, v76, v89, -v81
	v_fma_f32 v79, v76, v90, -v82
	v_fma_f32 v104, v76, v91, -v83
	v_fma_f32 v105, v76, v92, -v100
	v_fma_f32 v106, v76, v93, -v101
	v_fma_f32 v107, v76, v94, -v102
	v_fma_f32 v108, v76, v95, -v103
	v_cvt_pk_bf16_f32 v76, v77, v78
	v_cvt_pk_bf16_f32 v77, v79, v104
	v_cvt_pk_bf16_f32 v78, v105, v106
	v_cvt_pk_bf16_f32 v79, v107, v108
	ds_write_b128 v126, v[76:79] offset:2112
	v_lshlrev_b32_e32 v76, 16, v72
	v_and_b32_e32 v77, 0xffff0000, v72
	v_and_b32_e32 v107, 0xffff0000, v75
	v_sub_f32_e32 v72, v95, v99
	v_add_f32_e32 v95, v72, v107
	v_sub_f32_e32 v72, v88, v84
	v_add_f32_e32 v84, v72, v76
	v_sub_f32_e32 v72, v89, v85
	v_lshlrev_b32_e32 v78, 16, v73
	v_add_f32_e32 v85, v72, v77
	v_sub_f32_e32 v72, v90, v86
	v_and_b32_e32 v79, 0xffff0000, v73
	v_add_f32_e32 v86, v72, v78
	v_sub_f32_e32 v72, v91, v87
	v_add_f32_e32 v87, v72, v79
	v_min_i32_e32 v72, 2, v121
	v_cvt_f32_i32_e32 v72, v72
	v_lshlrev_b32_e32 v104, 16, v74
	v_sub_f32_e32 v73, v92, v96
	v_and_b32_e32 v105, 0xffff0000, v74
	v_rcp_iflag_f32_e32 v72, v72
	v_add_f32_e32 v88, v73, v104
	v_sub_f32_e32 v73, v93, v97
	v_lshlrev_b32_e32 v106, 16, v75
	v_add_f32_e32 v89, v73, v105
	v_sub_f32_e32 v73, v94, v98
	v_add_f32_e32 v90, v73, v106
	v_fma_f32 v73, v72, v84, -v76
	v_fma_f32 v74, v72, v85, -v77
	v_fma_f32 v75, v72, v86, -v78
	v_fma_f32 v91, v72, v87, -v79
	v_fma_f32 v92, v72, v88, -v104
	v_fma_f32 v93, v72, v89, -v105
	v_fma_f32 v94, v72, v90, -v106
	v_fma_f32 v96, v72, v95, -v107
	v_cvt_pk_bf16_f32 v72, v73, v74
	v_cvt_pk_bf16_f32 v73, v75, v91
	v_cvt_pk_bf16_f32 v74, v92, v93
	v_cvt_pk_bf16_f32 v75, v94, v96
	ds_write_b128 v126, v[72:75] offset:2640
	v_sub_f32_e32 v74, v84, v80
	v_sub_f32_e32 v80, v85, v81
	v_sub_f32_e32 v81, v86, v82
	v_min_i32_e32 v86, 2, v122
	v_cvt_f32_i32_e32 v86, v86
	v_lshlrev_b32_e32 v82, 16, v69
	v_add_f32_e32 v81, v81, v82
	v_sub_f32_e32 v78, v81, v78
	v_rcp_iflag_f32_e32 v86, v86
	v_lshlrev_b32_e32 v75, 16, v68
	v_and_b32_e32 v68, 0xffff0000, v68
	v_sub_f32_e32 v83, v87, v83
	v_fma_f32 v82, v86, v81, -v82
	v_min_i32_e32 v81, -6, v179
	v_add_u32_e32 v81, 8, v81
	v_cvt_f32_i32_e32 v81, v81
	v_and_b32_e32 v69, 0xffff0000, v69
	v_lshlrev_b32_e32 v85, 16, v70
	v_sub_f32_e32 v87, v89, v101
	v_and_b32_e32 v70, 0xffff0000, v70
	v_sub_f32_e32 v72, v95, v103
	v_and_b32_e32 v73, 0xffff0000, v71
	v_add_f32_e32 v80, v80, v68
	v_add_f32_e32 v83, v83, v69
	v_sub_f32_e32 v84, v88, v100
	v_add_f32_e32 v87, v87, v70
	v_sub_f32_e32 v88, v90, v102
	v_lshlrev_b32_e32 v71, 16, v71
	v_add_f32_e32 v72, v72, v73
	v_add_f32_e32 v74, v74, v75
	v_add_f32_e32 v84, v84, v85
	v_add_f32_e32 v88, v88, v71
	v_fma_f32 v68, v86, v80, -v68
	v_fma_f32 v69, v86, v83, -v69
	v_fma_f32 v70, v86, v87, -v70
	v_rcp_iflag_f32_e32 v81, v81
	v_fma_f32 v75, v86, v74, -v75
	v_fma_f32 v85, v86, v84, -v85
	v_fma_f32 v71, v86, v88, -v71
	v_fma_f32 v73, v86, v72, -v73
	v_cvt_pk_bf16_f32 v68, v75, v68
	v_cvt_pk_bf16_f32 v69, v82, v69
	v_cvt_pk_bf16_f32 v70, v85, v70
	v_cvt_pk_bf16_f32 v71, v71, v73
	ds_write_b128 v126, v[68:71] offset:3168
	v_sub_f32_e32 v68, v72, v107
	v_and_b32_e32 v69, 0xffff0000, v67
	v_sub_f32_e32 v70, v88, v106
	v_lshlrev_b32_e32 v67, 16, v67
	v_and_b32_e32 v72, 0xffff0000, v66
	v_sub_f32_e32 v73, v84, v104
	v_lshlrev_b32_e32 v66, 16, v66
	v_sub_f32_e32 v75, v83, v79
	v_and_b32_e32 v79, 0xffff0000, v65
	v_lshlrev_b32_e32 v65, 16, v65
	v_sub_f32_e32 v77, v80, v77
	v_and_b32_e32 v80, 0xffff0000, v64
	v_sub_f32_e32 v74, v74, v76
	v_lshlrev_b32_e32 v64, 16, v64
	v_add_f32_e32 v70, v70, v67
	v_sub_f32_e32 v71, v87, v105
	v_add_f32_e32 v73, v73, v66
	v_add_f32_e32 v78, v78, v65
	v_add_f32_e32 v74, v74, v64
	v_add_f32_e32 v68, v68, v69
	v_add_f32_e32 v71, v71, v72
	v_add_f32_e32 v75, v75, v79
	v_add_f32_e32 v77, v77, v80
	v_fma_f32 v64, v81, v74, -v64
	v_fma_f32 v65, v81, v78, -v65
	v_fma_f32 v66, v81, v73, -v66
	v_fma_f32 v67, v81, v70, -v67
	v_fma_f32 v74, v81, v77, -v80
	v_fma_f32 v75, v81, v75, -v79
	v_fma_f32 v71, v81, v71, -v72
	v_fma_f32 v68, v81, v68, -v69
	v_cvt_pk_bf16_f32 v64, v64, v74
	v_cvt_pk_bf16_f32 v65, v65, v75
	v_cvt_pk_bf16_f32 v66, v66, v71
	v_cvt_pk_bf16_f32 v67, v67, v68
.LBB0_355:
	v_or_b32_e32 v68, 7, v178
	s_movk_i32 s16, 0x210
	v_mul_lo_u32 v68, v68, s16
	v_add3_u32 v68, 0, v160, v68
	ds_write_b128 v68, v[64:67]
	s_waitcnt lgkmcnt(0)
	s_barrier
	v_mbcnt_lo_u32_b32 v64, -1, 0
	v_mbcnt_hi_u32_b32 v64, -1, v64
	s_lshl_b32 s16, s25, 9
	v_and_b32_e32 v65, 15, v64
	v_or_b32_e32 v66, s68, v65
	v_ashrrev_i32_e32 v67, 1, v64
	v_readlane_b32 s17, v253, 45
	v_and_b32_e32 v67, -8, v67
	v_lshlrev_b32_e32 v66, 13, v66
	s_add_i32 s16, s16, s17
	v_add3_u32 v200, s16, v67, v66
	global_load_dwordx2 v[128:129], v200, s[0:1]
	v_add_u32_e32 v199, 32, v200
	v_add_u32_e32 v198, 0x20000, v200
	global_load_dwordx2 v[130:131], v199, s[0:1]
	global_load_dwordx2 v[136:137], v198, s[0:1]
	v_add_u32_e32 v197, 0x20020, v200
	global_load_dwordx2 v[140:141], v197, s[0:1]
	v_and_b32_e32 v64, -16, v64
	v_mul_u32_u24_e32 v65, 0x210, v65
	v_add3_u32 v201, 0, v64, v65
	ds_read_b128 v[68:71], v201
	ds_read_b128 v[154:157], v201 offset:64
	s_waitcnt vmcnt(19) lgkmcnt(1)
	v_mfma_f32_16x16x32_bf16 v[64:67], v[56:59], v[68:71], 0
	ds_read_b128 v[76:79], v201 offset:8448
	ds_read_b128 v[84:87], v201 offset:16896
	ds_read_b128 v[92:95], v201 offset:25344
	s_waitcnt vmcnt(17)
	v_mfma_f32_16x16x32_bf16 v[68:71], v[60:63], v[68:71], 0
	v_add_u32_e32 v196, 0x40000, v200
	global_load_dwordx2 v[148:149], v196, s[0:1]
	ds_read_b128 v[100:103], v201 offset:33792
	s_waitcnt lgkmcnt(4)
	v_mfma_f32_16x16x32_bf16 v[64:67], v[48:51], v[154:157], v[64:67]
	ds_read_b128 v[108:111], v201 offset:42240
	v_add_u32_e32 v195, 0x40020, v200
	global_load_dwordx2 v[152:153], v195, s[0:1]
	s_waitcnt vmcnt(18)
	v_mfma_f32_16x16x32_bf16 v[68:71], v[52:55], v[154:157], v[68:71]
	ds_read_b128 v[154:157], v201 offset:8512
	ds_read_b128 v[116:119], v201 offset:50688
	ds_read_b128 v[124:127], v201 offset:59136
	s_waitcnt lgkmcnt(7)
	v_mfma_f32_16x16x32_bf16 v[72:75], v[56:59], v[76:79], 0
	v_add_u32_e32 v194, 0x60000, v200
	global_load_dwordx2 v[174:175], v194, s[0:1]
	v_add_u32_e32 v193, 0x60020, v200
	v_mfma_f32_16x16x32_bf16 v[76:79], v[60:63], v[76:79], 0
	global_load_dwordx2 v[178:179], v193, s[0:1]
	v_add_u32_e32 v192, 0x80000, v200
	global_load_dwordx2 v[172:173], v192, s[0:1]
	s_waitcnt lgkmcnt(2)
	v_mfma_f32_16x16x32_bf16 v[72:75], v[48:51], v[154:157], v[72:75]
	v_add_u32_e32 v191, 0x80020, v200
	global_load_dwordx2 v[170:171], v191, s[0:1]
	v_add_u32_e32 v190, 0xa0000, v200
	v_mfma_f32_16x16x32_bf16 v[76:79], v[52:55], v[154:157], v[76:79]
	ds_read_b128 v[154:157], v201 offset:16960
	global_load_dwordx2 v[146:147], v190, s[0:1]
	v_add_u32_e32 v189, 0xa0020, v200
	v_mfma_f32_16x16x32_bf16 v[80:83], v[56:59], v[84:87], 0
	global_load_dwordx2 v[144:145], v189, s[0:1]
	v_add_u32_e32 v188, 0xc0000, v200
	global_load_dwordx2 v[134:135], v188, s[0:1]
	v_mfma_f32_16x16x32_bf16 v[84:87], v[60:63], v[84:87], 0
	v_add_u32_e32 v187, 0xc0020, v200
	global_load_dwordx2 v[132:133], v187, s[0:1]
	v_add_u32_e32 v186, 0xe0000, v200
	s_waitcnt lgkmcnt(0)
	v_mfma_f32_16x16x32_bf16 v[80:83], v[48:51], v[154:157], v[80:83]
	global_load_dwordx2 v[122:123], v186, s[0:1]
	v_add_u32_e32 v160, 0xe0020, v200
	global_load_dwordx2 v[120:121], v160, s[0:1]
	v_mfma_f32_16x16x32_bf16 v[84:87], v[52:55], v[154:157], v[84:87]
	ds_read_b128 v[154:157], v201 offset:25408
	s_mov_b64 s[34:35], 0
	v_mfma_f32_16x16x32_bf16 v[88:91], v[56:59], v[92:95], 0
	v_mfma_f32_16x16x32_bf16 v[92:95], v[60:63], v[92:95], 0
	s_waitcnt lgkmcnt(0)
	v_mfma_f32_16x16x32_bf16 v[88:91], v[48:51], v[154:157], v[88:91]
	v_mfma_f32_16x16x32_bf16 v[92:95], v[52:55], v[154:157], v[92:95]
	ds_read_b128 v[154:157], v201 offset:33856
	v_mfma_f32_16x16x32_bf16 v[96:99], v[56:59], v[100:103], 0
	v_mfma_f32_16x16x32_bf16 v[100:103], v[60:63], v[100:103], 0
	s_waitcnt lgkmcnt(0)
	v_mfma_f32_16x16x32_bf16 v[96:99], v[48:51], v[154:157], v[96:99]
	v_mfma_f32_16x16x32_bf16 v[100:103], v[52:55], v[154:157], v[100:103]
	ds_read_b128 v[154:157], v201 offset:42304
	v_mfma_f32_16x16x32_bf16 v[104:107], v[56:59], v[108:111], 0
	v_mfma_f32_16x16x32_bf16 v[108:111], v[60:63], v[108:111], 0
	s_waitcnt lgkmcnt(0)
	v_mfma_f32_16x16x32_bf16 v[104:107], v[48:51], v[154:157], v[104:107]
	v_mfma_f32_16x16x32_bf16 v[108:111], v[52:55], v[154:157], v[108:111]
	ds_read_b128 v[154:157], v201 offset:50752
	v_mfma_f32_16x16x32_bf16 v[112:115], v[56:59], v[116:119], 0
	v_mfma_f32_16x16x32_bf16 v[116:119], v[60:63], v[116:119], 0
	s_waitcnt lgkmcnt(0)
	v_mfma_f32_16x16x32_bf16 v[112:115], v[48:51], v[154:157], v[112:115]
	v_mfma_f32_16x16x32_bf16 v[116:119], v[52:55], v[154:157], v[116:119]
	ds_read_b128 v[154:157], v201 offset:59200
	v_mfma_f32_16x16x32_bf16 v[56:59], v[56:59], v[124:127], 0
	v_mfma_f32_16x16x32_bf16 v[60:63], v[60:63], v[124:127], 0
	s_waitcnt vmcnt(15)
	v_lshlrev_b32_e32 v126, 16, v129
	v_and_b32_e32 v127, 0xffff0000, v129
	v_lshlrev_b32_e32 v124, 16, v128
	v_and_b32_e32 v125, 0xffff0000, v128
	v_pk_mul_f32 v[128:129], v[126:127], s[12:13] op_sel_hi:[1,0]
	v_pk_mul_f32 v[138:139], v[124:125], s[12:13] op_sel_hi:[1,0]
	v_exp_f32_e32 v128, v128
	v_exp_f32_e32 v129, v129
	v_exp_f32_e32 v138, v138
	v_exp_f32_e32 v139, v139
	s_waitcnt lgkmcnt(0)
	v_mfma_f32_16x16x32_bf16 v[162:165], v[48:51], v[154:157], v[56:59]
	v_add_f32_e64 v128, v128, 1.0
	v_add_f32_e64 v129, v129, 1.0
	s_waitcnt vmcnt(13)
	v_lshlrev_b32_e32 v48, 16, v136
	v_pk_add_f32 v[138:139], v[138:139], 1.0 op_sel_hi:[1,0]
	v_rcp_f32_e32 v128, v128
	v_rcp_f32_e32 v129, v129
	v_rcp_f32_e32 v138, v138
	v_rcp_f32_e32 v139, v139
	v_and_b32_e32 v49, 0xffff0000, v136
	v_pk_mul_f32 v[126:127], v[128:129], v[126:127]
	v_lshlrev_b32_e32 v128, 16, v130
	v_and_b32_e32 v129, 0xffff0000, v130
	v_lshlrev_b32_e32 v130, 16, v131
	v_and_b32_e32 v131, 0xffff0000, v131
	v_lshlrev_b32_e32 v50, 16, v137
	v_and_b32_e32 v51, 0xffff0000, v137
	v_pk_mul_f32 v[124:125], v[138:139], v[124:125]
	v_pk_mul_f32 v[138:139], v[130:131], s[12:13] op_sel_hi:[1,0]
	v_mfma_f32_16x16x32_bf16 v[154:157], v[52:55], v[154:157], v[60:63]
	v_mul_f32_e64 v52, v50, s12
	v_mul_f32_e64 v53, v51, s12
	v_pk_mul_f32 v[54:55], v[48:49], s[12:13] op_sel_hi:[1,0]
	v_exp_f32_e32 v138, v138
	v_exp_f32_e32 v139, v139
	v_exp_f32_e32 v54, v54
	v_exp_f32_e32 v55, v55
	v_exp_f32_e32 v52, v52
	v_exp_f32_e32 v53, v53
	v_pk_add_f32 v[138:139], v[138:139], 1.0 op_sel_hi:[1,0]
	v_pk_add_f32 v[54:55], v[54:55], 1.0 op_sel_hi:[1,0]
	v_rcp_f32_e32 v138, v138
	v_pk_add_f32 v[52:53], v[52:53], 1.0 op_sel_hi:[1,0]
	v_rcp_f32_e32 v139, v139
	v_rcp_f32_e32 v54, v54
	v_rcp_f32_e32 v55, v55
	v_rcp_f32_e32 v52, v52
	v_rcp_f32_e32 v53, v53
	v_pk_mul_f32 v[130:131], v[138:139], v[130:131]
	v_pk_mul_f32 v[136:137], v[54:55], v[48:49]
	s_waitcnt vmcnt(12)
	v_lshlrev_b32_e32 v48, 16, v140
	v_pk_mul_f32 v[138:139], v[52:53], v[50:51]
	v_and_b32_e32 v49, 0xffff0000, v140
	v_lshlrev_b32_e32 v50, 16, v141
	v_and_b32_e32 v51, 0xffff0000, v141
	v_pk_mul_f32 v[142:143], v[128:129], s[12:13] op_sel_hi:[1,0]
	v_pk_mul_f32 v[52:53], v[50:51], s[12:13] op_sel_hi:[1,0]
	v_pk_mul_f32 v[54:55], v[48:49], s[12:13] op_sel_hi:[1,0]
	v_exp_f32_e32 v142, v142
	v_exp_f32_e32 v143, v143
	v_exp_f32_e32 v54, v54
	v_exp_f32_e32 v55, v55
	v_exp_f32_e32 v52, v52
	v_exp_f32_e32 v53, v53
	v_pk_add_f32 v[142:143], v[142:143], 1.0 op_sel_hi:[1,0]
	v_pk_add_f32 v[54:55], v[54:55], 1.0 op_sel_hi:[1,0]
	v_rcp_f32_e32 v142, v142
	v_pk_add_f32 v[52:53], v[52:53], 1.0 op_sel_hi:[1,0]
	v_rcp_f32_e32 v143, v143
	v_rcp_f32_e32 v54, v54
	v_rcp_f32_e32 v55, v55
	v_rcp_f32_e32 v52, v52
	v_rcp_f32_e32 v53, v53
	v_pk_mul_f32 v[128:129], v[142:143], v[128:129]
	v_pk_mul_f32 v[140:141], v[54:55], v[48:49]
	ds_read_b128 v[60:63], v201 offset:8576
	v_pk_mul_f32 v[142:143], v[52:53], v[50:51]
	ds_read_b128 v[52:55], v201 offset:128
	s_waitcnt lgkmcnt(0)
	v_mfma_f32_16x16x32_bf16 v[48:51], v[40:43], v[52:55], v[64:67]
	v_mfma_f32_16x16x32_bf16 v[52:55], v[44:47], v[52:55], v[68:71]
	s_nop 2
	ds_read_b128 v[68:71], v201 offset:17024
	v_mfma_f32_16x16x32_bf16 v[56:59], v[40:43], v[60:63], v[72:75]
	v_mfma_f32_16x16x32_bf16 v[60:63], v[44:47], v[60:63], v[76:79]
	s_nop 2
	ds_read_b128 v[76:79], v201 offset:25472
	s_waitcnt lgkmcnt(1)
	v_mfma_f32_16x16x32_bf16 v[64:67], v[40:43], v[68:71], v[80:83]
	s_nop 2
	ds_read_b128 v[80:83], v201 offset:33920
	v_mfma_f32_16x16x32_bf16 v[68:71], v[44:47], v[68:71], v[84:87]
	s_waitcnt lgkmcnt(1)
	v_mfma_f32_16x16x32_bf16 v[72:75], v[40:43], v[76:79], v[88:91]
	s_nop 0
	ds_read_b128 v[84:87], v201 offset:50816
	v_mfma_f32_16x16x32_bf16 v[76:79], v[44:47], v[76:79], v[92:95]
	s_waitcnt lgkmcnt(1)
	v_mfma_f32_16x16x32_bf16 v[88:91], v[40:43], v[80:83], v[96:99]
	v_mfma_f32_16x16x32_bf16 v[92:95], v[44:47], v[80:83], v[100:103]
	ds_read_b128 v[80:83], v201 offset:42368
	s_waitcnt lgkmcnt(0)
	v_mfma_f32_16x16x32_bf16 v[96:99], v[40:43], v[80:83], v[104:107]
	s_nop 2
	ds_read_b128 v[104:107], v201 offset:59264
	v_mfma_f32_16x16x32_bf16 v[100:103], v[44:47], v[80:83], v[108:111]
	v_mfma_f32_16x16x32_bf16 v[80:83], v[40:43], v[84:87], v[112:115]
	v_mfma_f32_16x16x32_bf16 v[84:87], v[44:47], v[84:87], v[116:119]
	s_waitcnt lgkmcnt(0)
	v_mfma_f32_16x16x32_bf16 v[40:43], v[40:43], v[104:107], v[162:165]
	v_mfma_f32_16x16x32_bf16 v[44:47], v[44:47], v[104:107], v[154:157]
	s_waitcnt vmcnt(11)
	v_lshlrev_b32_e32 v104, 16, v148
	v_and_b32_e32 v105, 0xffff0000, v148
	v_lshlrev_b32_e32 v106, 16, v149
	v_and_b32_e32 v107, 0xffff0000, v149
	v_pk_mul_f32 v[108:109], v[106:107], s[12:13] op_sel_hi:[1,0]
	v_pk_mul_f32 v[110:111], v[104:105], s[12:13] op_sel_hi:[1,0]
	v_exp_f32_e32 v108, v108
	v_exp_f32_e32 v110, v110
	v_exp_f32_e32 v111, v111
	v_exp_f32_e32 v109, v109
	v_pk_add_f32 v[110:111], v[110:111], 1.0 op_sel_hi:[1,0]
	v_pk_add_f32 v[108:109], v[108:109], 1.0 op_sel_hi:[1,0]
	v_rcp_f32_e32 v110, v110
	v_rcp_f32_e32 v111, v111
	v_rcp_f32_e32 v108, v108
	v_rcp_f32_e32 v109, v109
	v_pk_mul_f32 v[148:149], v[110:111], v[104:105]
	s_waitcnt vmcnt(10)
	v_lshlrev_b32_e32 v104, 16, v152
	v_pk_mul_f32 v[150:151], v[108:109], v[106:107]
	v_and_b32_e32 v105, 0xffff0000, v152
	v_lshlrev_b32_e32 v106, 16, v153
	v_and_b32_e32 v107, 0xffff0000, v153
	v_pk_mul_f32 v[108:109], v[106:107], s[12:13] op_sel_hi:[1,0]
	v_pk_mul_f32 v[110:111], v[104:105], s[12:13] op_sel_hi:[1,0]
	v_exp_f32_e32 v108, v108
	v_exp_f32_e32 v110, v110
	v_exp_f32_e32 v111, v111
	v_exp_f32_e32 v109, v109
	v_pk_add_f32 v[110:111], v[110:111], 1.0 op_sel_hi:[1,0]
	v_pk_add_f32 v[108:109], v[108:109], 1.0 op_sel_hi:[1,0]
	v_rcp_f32_e32 v110, v110
	v_rcp_f32_e32 v111, v111
	v_rcp_f32_e32 v108, v108
	v_rcp_f32_e32 v109, v109
	v_pk_mul_f32 v[152:153], v[110:111], v[104:105]
	v_pk_mul_f32 v[154:155], v[108:109], v[106:107]
	ds_read_b128 v[104:107], v201 offset:192
	s_waitcnt lgkmcnt(0)
	v_mfma_f32_16x16x32_bf16 v[48:51], v[32:35], v[104:107], v[48:51]
	ds_read_b128 v[108:111], v201 offset:50880
	v_mfma_f32_16x16x32_bf16 v[52:55], v[36:39], v[104:107], v[52:55]
	ds_read_b128 v[104:107], v201 offset:8640
	s_waitcnt lgkmcnt(0)
	v_mfma_f32_16x16x32_bf16 v[56:59], v[32:35], v[104:107], v[56:59]
	v_mfma_f32_16x16x32_bf16 v[60:63], v[36:39], v[104:107], v[60:63]
	ds_read_b128 v[104:107], v201 offset:17088
	s_waitcnt lgkmcnt(0)
	v_mfma_f32_16x16x32_bf16 v[64:67], v[32:35], v[104:107], v[64:67]
	v_mfma_f32_16x16x32_bf16 v[68:71], v[36:39], v[104:107], v[68:71]
	ds_read_b128 v[104:107], v201 offset:25536
	s_waitcnt lgkmcnt(0)
	v_mfma_f32_16x16x32_bf16 v[72:75], v[32:35], v[104:107], v[72:75]
	v_mfma_f32_16x16x32_bf16 v[76:79], v[36:39], v[104:107], v[76:79]
	ds_read_b128 v[104:107], v201 offset:33984
	s_waitcnt lgkmcnt(0)
	v_mfma_f32_16x16x32_bf16 v[88:91], v[32:35], v[104:107], v[88:91]
	v_mfma_f32_16x16x32_bf16 v[92:95], v[36:39], v[104:107], v[92:95]
	ds_read_b128 v[104:107], v201 offset:42432
	s_waitcnt lgkmcnt(0)
	v_mfma_f32_16x16x32_bf16 v[96:99], v[32:35], v[104:107], v[96:99]
	v_mfma_f32_16x16x32_bf16 v[100:103], v[36:39], v[104:107], v[100:103]
	v_mfma_f32_16x16x32_bf16 v[104:107], v[32:35], v[108:111], v[80:83]
	s_nop 2
	ds_read_b128 v[80:83], v201 offset:59328
	s_waitcnt lgkmcnt(0)
	v_mfma_f32_16x16x32_bf16 v[32:35], v[32:35], v[80:83], v[40:43]
	s_waitcnt vmcnt(9)
	s_nop 1
	v_lshlrev_b32_e32 v40, 16, v174
	v_and_b32_e32 v41, 0xffff0000, v174
	v_lshlrev_b32_e32 v42, 16, v175
	v_and_b32_e32 v43, 0xffff0000, v175
	v_mfma_f32_16x16x32_bf16 v[108:111], v[36:39], v[108:111], v[84:87]
	v_mfma_f32_16x16x32_bf16 v[36:39], v[36:39], v[80:83], v[44:47]
	s_nop 2
	v_mul_f32_e64 v44, v42, s12
	v_mul_f32_e64 v45, v43, s12
	v_pk_mul_f32 v[46:47], v[40:41], s[12:13] op_sel_hi:[1,0]
	v_exp_f32_e32 v44, v44
	v_exp_f32_e32 v46, v46
	v_exp_f32_e32 v47, v47
	v_exp_f32_e32 v45, v45
	v_pk_add_f32 v[46:47], v[46:47], 1.0 op_sel_hi:[1,0]
	v_pk_add_f32 v[44:45], v[44:45], 1.0 op_sel_hi:[1,0]
	v_rcp_f32_e32 v46, v46
	v_rcp_f32_e32 v47, v47
	v_rcp_f32_e32 v44, v44
	v_rcp_f32_e32 v45, v45
	v_pk_mul_f32 v[174:175], v[46:47], v[40:41]
	s_waitcnt vmcnt(8)
	v_lshlrev_b32_e32 v40, 16, v178
	v_pk_mul_f32 v[176:177], v[44:45], v[42:43]
	v_and_b32_e32 v41, 0xffff0000, v178
	v_lshlrev_b32_e32 v42, 16, v179
	v_and_b32_e32 v43, 0xffff0000, v179
	v_pk_mul_f32 v[44:45], v[42:43], s[12:13] op_sel_hi:[1,0]
	v_pk_mul_f32 v[46:47], v[40:41], s[12:13] op_sel_hi:[1,0]
	v_exp_f32_e32 v44, v44
	v_exp_f32_e32 v46, v46
	v_exp_f32_e32 v47, v47
	v_exp_f32_e32 v45, v45
	v_pk_add_f32 v[46:47], v[46:47], 1.0 op_sel_hi:[1,0]
	v_pk_add_f32 v[44:45], v[44:45], 1.0 op_sel_hi:[1,0]
	v_rcp_f32_e32 v46, v46
	v_rcp_f32_e32 v47, v47
	v_rcp_f32_e32 v44, v44
	v_rcp_f32_e32 v45, v45
	v_pk_mul_f32 v[178:179], v[46:47], v[40:41]
	v_pk_mul_f32 v[180:181], v[44:45], v[42:43]
	ds_read_b128 v[40:43], v201 offset:256
	ds_read_b128 v[44:47], v201 offset:8704
	s_waitcnt lgkmcnt(1)
	v_mfma_f32_16x16x32_bf16 v[112:115], v[24:27], v[40:43], v[48:51]
	s_nop 2
	ds_read_b128 v[48:51], v201 offset:17152
	v_mfma_f32_16x16x32_bf16 v[116:119], v[28:31], v[40:43], v[52:55]
	s_waitcnt lgkmcnt(1)
	v_mfma_f32_16x16x32_bf16 v[40:43], v[24:27], v[44:47], v[56:59]
	s_nop 0
	ds_read_b128 v[52:55], v201 offset:50944
	v_mfma_f32_16x16x32_bf16 v[44:47], v[28:31], v[44:47], v[60:63]
	s_waitcnt lgkmcnt(1)
	v_mfma_f32_16x16x32_bf16 v[56:59], v[24:27], v[48:51], v[64:67]
	v_mfma_f32_16x16x32_bf16 v[60:63], v[28:31], v[48:51], v[68:71]
	ds_read_b128 v[48:51], v201 offset:25600
	s_waitcnt lgkmcnt(0)
	v_mfma_f32_16x16x32_bf16 v[72:75], v[24:27], v[48:51], v[72:75]
	v_mfma_f32_16x16x32_bf16 v[76:79], v[28:31], v[48:51], v[76:79]
	ds_read_b128 v[48:51], v201 offset:34048
	s_waitcnt lgkmcnt(0)
	v_mfma_f32_16x16x32_bf16 v[80:83], v[24:27], v[48:51], v[88:91]
	s_nop 2
	ds_read_b128 v[88:91], v201 offset:59392
	s_waitcnt lgkmcnt(0)
	v_mfma_f32_16x16x32_bf16 v[32:35], v[24:27], v[88:91], v[32:35]
	v_mfma_f32_16x16x32_bf16 v[36:39], v[28:31], v[88:91], v[36:39]
	ds_read_b128 v[88:91], v201 offset:8768
	s_waitcnt lgkmcnt(0)
	v_mfma_f32_16x16x32_bf16 v[40:43], v[16:19], v[88:91], v[40:43]
	v_mfma_f32_16x16x32_bf16 v[44:47], v[20:23], v[88:91], v[44:47]
	ds_read_b128 v[88:91], v201 offset:17216
	v_mfma_f32_16x16x32_bf16 v[84:87], v[28:31], v[48:51], v[92:95]
	ds_read_b128 v[48:51], v201 offset:42496
	s_waitcnt lgkmcnt(1)
	v_mfma_f32_16x16x32_bf16 v[56:59], v[16:19], v[88:91], v[56:59]
	v_mfma_f32_16x16x32_bf16 v[60:63], v[20:23], v[88:91], v[60:63]
	ds_read_b128 v[88:91], v201 offset:25664
	s_waitcnt lgkmcnt(0)
	v_mfma_f32_16x16x32_bf16 v[72:75], v[16:19], v[88:91], v[72:75]
	v_mfma_f32_16x16x32_bf16 v[76:79], v[20:23], v[88:91], v[76:79]
	ds_read_b128 v[88:91], v201 offset:34112
	v_mfma_f32_16x16x32_bf16 v[64:67], v[24:27], v[48:51], v[96:99]
	v_mfma_f32_16x16x32_bf16 v[68:71], v[28:31], v[48:51], v[100:103]
	v_mfma_f32_16x16x32_bf16 v[48:51], v[24:27], v[52:55], v[104:107]
	s_waitcnt vmcnt(7)
	v_lshlrev_b32_e32 v24, 16, v172
	v_and_b32_e32 v25, 0xffff0000, v172
	v_lshlrev_b32_e32 v26, 16, v173
	v_and_b32_e32 v27, 0xffff0000, v173
	v_mfma_f32_16x16x32_bf16 v[52:55], v[28:31], v[52:55], v[108:111]
	v_mul_f32_e64 v28, v26, s12
	v_mul_f32_e64 v29, v27, s12
	v_pk_mul_f32 v[30:31], v[24:25], s[12:13] op_sel_hi:[1,0]
	v_exp_f32_e32 v28, v28
	v_exp_f32_e32 v30, v30
	v_exp_f32_e32 v31, v31
	v_exp_f32_e32 v29, v29
	s_waitcnt lgkmcnt(0)
	v_mfma_f32_16x16x32_bf16 v[80:83], v[16:19], v[88:91], v[80:83]
	v_add_f32_e64 v30, v30, 1.0
	v_add_f32_e64 v31, v31, 1.0
	v_pk_add_f32 v[28:29], v[28:29], 1.0 op_sel_hi:[1,0]
	v_rcp_f32_e32 v30, v30
	v_rcp_f32_e32 v31, v31
	v_rcp_f32_e32 v28, v28
	v_rcp_f32_e32 v29, v29
	v_mfma_f32_16x16x32_bf16 v[84:87], v[20:23], v[88:91], v[84:87]
	v_mul_f32_e64 v172, v30, v24
	v_mul_f32_e64 v173, v31, v25
	s_waitcnt vmcnt(6)
	v_lshlrev_b32_e32 v24, 16, v170
	v_pk_mul_f32 v[182:183], v[28:29], v[26:27]
	v_and_b32_e32 v25, 0xffff0000, v170
	v_lshlrev_b32_e32 v26, 16, v171
	v_and_b32_e32 v27, 0xffff0000, v171
	v_pk_mul_f32 v[28:29], v[26:27], s[12:13] op_sel_hi:[1,0]
	v_pk_mul_f32 v[30:31], v[24:25], s[12:13] op_sel_hi:[1,0]
	v_exp_f32_e32 v28, v28
	v_exp_f32_e32 v30, v30
	v_exp_f32_e32 v31, v31
	v_exp_f32_e32 v29, v29
	ds_read_b128 v[88:91], v201 offset:42560
	s_waitcnt lgkmcnt(0)
	v_mfma_f32_16x16x32_bf16 v[64:67], v[16:19], v[88:91], v[64:67]
	v_add_f32_e64 v28, v28, 1.0
	v_add_f32_e64 v29, v29, 1.0
	v_pk_add_f32 v[30:31], v[30:31], 1.0 op_sel_hi:[1,0]
	v_rcp_f32_e32 v28, v28
	v_rcp_f32_e32 v30, v30
	v_rcp_f32_e32 v31, v31
	v_rcp_f32_e32 v29, v29
	v_mfma_f32_16x16x32_bf16 v[88:91], v[20:23], v[88:91], v[68:71]
	v_mul_f32_e64 v170, v30, v24
	v_mul_f32_e64 v171, v31, v25
	v_pk_mul_f32 v[184:185], v[28:29], v[26:27]
	ds_read_b128 v[28:31], v201 offset:320
	ds_read_b128 v[68:71], v201 offset:51008
	s_waitcnt lgkmcnt(0)
	v_mfma_f32_16x16x32_bf16 v[96:99], v[16:19], v[68:71], v[48:51]
	s_nop 2
	ds_read_b128 v[48:51], v201 offset:59456
	v_mfma_f32_16x16x32_bf16 v[24:27], v[16:19], v[28:31], v[112:115]
	v_mfma_f32_16x16x32_bf16 v[28:31], v[20:23], v[28:31], v[116:119]
	v_mfma_f32_16x16x32_bf16 v[100:103], v[20:23], v[68:71], v[52:55]
	s_waitcnt lgkmcnt(0)
	v_mfma_f32_16x16x32_bf16 v[16:19], v[16:19], v[48:51], v[32:35]
	v_mfma_f32_16x16x32_bf16 v[32:35], v[20:23], v[48:51], v[36:39]
	s_waitcnt vmcnt(5)
	v_lshlrev_b32_e32 v20, 16, v146
	v_and_b32_e32 v21, 0xffff0000, v146
	v_lshlrev_b32_e32 v22, 16, v147
	v_and_b32_e32 v23, 0xffff0000, v147
	v_pk_mul_f32 v[36:37], v[22:23], s[12:13] op_sel_hi:[1,0]
	v_pk_mul_f32 v[38:39], v[20:21], s[12:13] op_sel_hi:[1,0]
	v_exp_f32_e32 v36, v36
	v_exp_f32_e32 v38, v38
	v_exp_f32_e32 v39, v39
	v_exp_f32_e32 v37, v37
	v_pk_add_f32 v[38:39], v[38:39], 1.0 op_sel_hi:[1,0]
	v_pk_add_f32 v[36:37], v[36:37], 1.0 op_sel_hi:[1,0]
	v_rcp_f32_e32 v38, v38
	v_rcp_f32_e32 v39, v39
	v_rcp_f32_e32 v36, v36
	v_rcp_f32_e32 v37, v37
	v_pk_mul_f32 v[116:117], v[38:39], v[20:21]
	s_waitcnt vmcnt(4)
	v_lshlrev_b32_e32 v20, 16, v144
	v_pk_mul_f32 v[118:119], v[36:37], v[22:23]
	v_and_b32_e32 v21, 0xffff0000, v144
	v_lshlrev_b32_e32 v22, 16, v145
	v_and_b32_e32 v23, 0xffff0000, v145
	v_pk_mul_f32 v[36:37], v[22:23], s[12:13] op_sel_hi:[1,0]
	v_pk_mul_f32 v[38:39], v[20:21], s[12:13] op_sel_hi:[1,0]
	v_exp_f32_e32 v36, v36
	v_exp_f32_e32 v38, v38
	v_exp_f32_e32 v39, v39
	v_exp_f32_e32 v37, v37
	v_pk_add_f32 v[38:39], v[38:39], 1.0 op_sel_hi:[1,0]
	v_pk_add_f32 v[36:37], v[36:37], 1.0 op_sel_hi:[1,0]
	v_rcp_f32_e32 v38, v38
	v_rcp_f32_e32 v39, v39
	v_rcp_f32_e32 v36, v36
	v_rcp_f32_e32 v37, v37
	v_pk_mul_f32 v[144:145], v[38:39], v[20:21]
	v_pk_mul_f32 v[146:147], v[36:37], v[22:23]
	ds_read_b128 v[20:23], v201 offset:384
	s_waitcnt lgkmcnt(0)
	v_mfma_f32_16x16x32_bf16 v[108:111], v[8:11], v[20:23], v[24:27]
	s_nop 2
	ds_read_b128 v[24:27], v201 offset:51072
	v_mfma_f32_16x16x32_bf16 v[112:115], v[12:15], v[20:23], v[28:31]
	ds_read_b128 v[20:23], v201 offset:8832
	s_waitcnt lgkmcnt(0)
	v_mfma_f32_16x16x32_bf16 v[28:31], v[8:11], v[20:23], v[40:43]
	s_nop 2
	ds_read_b128 v[40:43], v201 offset:59520
	v_mfma_f32_16x16x32_bf16 v[104:107], v[12:15], v[20:23], v[44:47]
	ds_read_b128 v[20:23], v201 offset:17280
	s_waitcnt lgkmcnt(0)
	v_mfma_f32_16x16x32_bf16 v[36:39], v[8:11], v[20:23], v[56:59]
	s_nop 2
	ds_read_b128 v[56:59], v201 offset:8896
	v_mfma_f32_16x16x32_bf16 v[92:95], v[12:15], v[20:23], v[60:63]
	ds_read_b128 v[20:23], v201 offset:25728
	s_waitcnt lgkmcnt(0)
	v_mfma_f32_16x16x32_bf16 v[52:55], v[8:11], v[20:23], v[72:75]
	v_mfma_f32_16x16x32_bf16 v[68:71], v[12:15], v[20:23], v[76:79]
	ds_read_b128 v[20:23], v201 offset:34176
	s_waitcnt lgkmcnt(0)
	v_mfma_f32_16x16x32_bf16 v[60:63], v[8:11], v[20:23], v[80:83]
	v_mfma_f32_16x16x32_bf16 v[72:75], v[12:15], v[20:23], v[84:87]
	ds_read_b128 v[20:23], v201 offset:42624
	s_waitcnt lgkmcnt(0)
	v_mfma_f32_16x16x32_bf16 v[44:47], v[8:11], v[20:23], v[64:67]
	ds_read_b128 v[84:87], v201 offset:25792
	s_nop 1
	ds_read_b128 v[64:67], v201 offset:17344
	v_mfma_f32_16x16x32_bf16 v[48:51], v[12:15], v[20:23], v[88:91]
	v_mfma_f32_16x16x32_bf16 v[20:23], v[8:11], v[24:27], v[96:99]
	v_mfma_f32_16x16x32_bf16 v[8:11], v[8:11], v[40:43], v[16:19]
	s_waitcnt vmcnt(3)
	s_nop 1
	v_lshlrev_b32_e32 v16, 16, v134
	v_and_b32_e32 v17, 0xffff0000, v134
	v_lshlrev_b32_e32 v18, 16, v135
	v_and_b32_e32 v19, 0xffff0000, v135
	v_mfma_f32_16x16x32_bf16 v[24:27], v[12:15], v[24:27], v[100:103]
	v_mfma_f32_16x16x32_bf16 v[12:15], v[12:15], v[40:43], v[32:35]
	s_nop 2
	v_mul_f32_e64 v32, v18, s12
	v_mul_f32_e64 v33, v19, s12
	v_pk_mul_f32 v[34:35], v[16:17], s[12:13] op_sel_hi:[1,0]
	v_exp_f32_e32 v32, v32
	v_exp_f32_e32 v34, v34
	v_exp_f32_e32 v35, v35
	v_exp_f32_e32 v33, v33
	v_mfma_f32_16x16x32_bf16 v[40:43], v[0:3], v[56:59], v[28:31]
	v_add_f32_e64 v34, v34, 1.0
	v_add_f32_e64 v35, v35, 1.0
	v_pk_add_f32 v[32:33], v[32:33], 1.0 op_sel_hi:[1,0]
	v_rcp_f32_e32 v34, v34
	v_rcp_f32_e32 v35, v35
	v_rcp_f32_e32 v32, v32
	v_rcp_f32_e32 v33, v33
	v_mfma_f32_16x16x32_bf16 v[28:31], v[4:7], v[56:59], v[104:107]
	v_mul_f32_e64 v76, v34, v16
	v_mul_f32_e64 v77, v35, v17
	s_waitcnt vmcnt(2)
	v_lshlrev_b32_e32 v16, 16, v132
	v_pk_mul_f32 v[78:79], v[32:33], v[18:19]
	v_and_b32_e32 v17, 0xffff0000, v132
	v_lshlrev_b32_e32 v18, 16, v133
	v_and_b32_e32 v19, 0xffff0000, v133
	v_pk_mul_f32 v[32:33], v[18:19], s[12:13] op_sel_hi:[1,0]
	v_pk_mul_f32 v[34:35], v[16:17], s[12:13] op_sel_hi:[1,0]
	v_exp_f32_e32 v32, v32
	v_exp_f32_e32 v34, v34
	v_exp_f32_e32 v35, v35
	v_exp_f32_e32 v33, v33
	s_waitcnt lgkmcnt(0)
	v_mfma_f32_16x16x32_bf16 v[56:59], v[0:3], v[64:67], v[36:39]
	v_add_f32_e64 v34, v34, 1.0
	v_add_f32_e64 v35, v35, 1.0
	v_pk_add_f32 v[32:33], v[32:33], 1.0 op_sel_hi:[1,0]
	v_rcp_f32_e32 v34, v34
	v_rcp_f32_e32 v35, v35
	v_rcp_f32_e32 v32, v32
	v_rcp_f32_e32 v33, v33
	v_mfma_f32_16x16x32_bf16 v[36:39], v[4:7], v[64:67], v[92:95]
	v_mul_f32_e64 v80, v34, v16
	v_mul_f32_e64 v81, v35, v17
	v_pk_mul_f32 v[82:83], v[32:33], v[18:19]
	ds_read_b128 v[16:19], v201 offset:448
	v_mfma_f32_16x16x32_bf16 v[64:67], v[0:3], v[84:87], v[52:55]
	v_mfma_f32_16x16x32_bf16 v[52:55], v[4:7], v[84:87], v[68:71]
	ds_read_b128 v[84:87], v201 offset:34240
	s_waitcnt lgkmcnt(0)
	v_mfma_f32_16x16x32_bf16 v[68:71], v[0:3], v[84:87], v[60:63]
	v_mfma_f32_16x16x32_bf16 v[60:63], v[4:7], v[84:87], v[72:75]
	ds_read_b128 v[84:87], v201 offset:42688
	s_waitcnt lgkmcnt(0)
	v_mfma_f32_16x16x32_bf16 v[72:75], v[0:3], v[84:87], v[44:47]
	v_mfma_f32_16x16x32_bf16 v[44:47], v[4:7], v[84:87], v[48:51]
	ds_read_b128 v[84:87], v201 offset:51136
	s_waitcnt lgkmcnt(0)
	v_mfma_f32_16x16x32_bf16 v[48:51], v[0:3], v[84:87], v[20:23]
	v_mfma_f32_16x16x32_bf16 v[20:23], v[4:7], v[84:87], v[24:27]
	s_nop 2
	ds_read_b128 v[24:27], v201 offset:59584
	v_mfma_f32_16x16x32_bf16 v[32:35], v[0:3], v[16:19], v[108:111]
	v_mfma_f32_16x16x32_bf16 v[16:19], v[4:7], v[16:19], v[112:115]
	s_waitcnt lgkmcnt(0)
	v_mfma_f32_16x16x32_bf16 v[8:11], v[0:3], v[24:27], v[8:11]
	v_mfma_f32_16x16x32_bf16 v[0:3], v[4:7], v[24:27], v[12:15]
	s_waitcnt vmcnt(1)
	v_lshlrev_b32_e32 v6, 16, v123
	v_and_b32_e32 v7, 0xffff0000, v123
	v_lshlrev_b32_e32 v4, 16, v122
	v_and_b32_e32 v5, 0xffff0000, v122
	v_pk_mul_f32 v[12:13], v[6:7], s[12:13] op_sel_hi:[1,0]
	v_pk_mul_f32 v[14:15], v[4:5], s[12:13] op_sel_hi:[1,0]
	v_exp_f32_e32 v12, v12
	v_exp_f32_e32 v13, v13
	v_exp_f32_e32 v14, v14
	v_exp_f32_e32 v15, v15
	v_pk_mul_f32 v[18:19], v[130:131], v[18:19]
	v_pk_add_f32 v[12:13], v[12:13], 1.0 op_sel_hi:[1,0]
	v_pk_mul_f32 v[16:17], v[128:129], v[16:17]
	v_pk_add_f32 v[14:15], v[14:15], 1.0 op_sel_hi:[1,0]
	v_rcp_f32_e32 v12, v12
	v_rcp_f32_e32 v13, v13
	v_rcp_f32_e32 v14, v14
	v_rcp_f32_e32 v15, v15
	v_pk_mul_f32 v[6:7], v[12:13], v[6:7]
	s_waitcnt vmcnt(0)
	v_lshlrev_b32_e32 v12, 16, v120
	v_and_b32_e32 v13, 0xffff0000, v120
	v_pk_mul_f32 v[4:5], v[14:15], v[4:5]
	v_lshlrev_b32_e32 v14, 16, v121
	v_and_b32_e32 v15, 0xffff0000, v121
	v_pk_mul_f32 v[26:27], v[12:13], s[12:13] op_sel_hi:[1,0]
	v_pk_mul_f32 v[24:25], v[14:15], s[12:13] op_sel_hi:[1,0]
	v_exp_f32_e32 v26, v26
	v_exp_f32_e32 v27, v27
	v_exp_f32_e32 v24, v24
	v_exp_f32_e32 v25, v25
	v_pk_mul_f32 v[4:5], v[4:5], v[8:9]
	v_pk_add_f32 v[26:27], v[26:27], 1.0 op_sel_hi:[1,0]
	v_pk_mul_f32 v[6:7], v[6:7], v[10:11]
	v_pk_add_f32 v[24:25], v[24:25], 1.0 op_sel_hi:[1,0]
	v_rcp_f32_e32 v26, v26
	v_rcp_f32_e32 v27, v27
	v_rcp_f32_e32 v24, v24
	v_rcp_f32_e32 v25, v25
	v_pk_mul_f32 v[12:13], v[26:27], v[12:13]
	v_pk_mul_f32 v[26:27], v[124:125], v[32:33]
	v_pk_mul_f32 v[14:15], v[24:25], v[14:15]
	v_pk_mul_f32 v[24:25], v[126:127], v[34:35]
	v_cvt_pk_bf16_f32 v26, v26, v27
	v_pk_mul_f32 v[0:1], v[12:13], v[0:1]
	v_cvt_pk_bf16_f32 v27, v24, v25
	global_store_dwordx2 v200, v[26:27], s[0:1]
	v_cvt_pk_bf16_f32 v16, v16, v17
	v_cvt_pk_bf16_f32 v17, v18, v19
	v_pk_mul_f32 v[18:19], v[136:137], v[40:41]
	global_store_dwordx2 v199, v[16:17], s[0:1]
	v_pk_mul_f32 v[16:17], v[138:139], v[42:43]
	v_cvt_pk_bf16_f32 v18, v18, v19
	v_pk_mul_f32 v[2:3], v[14:15], v[2:3]
	v_cvt_pk_bf16_f32 v19, v16, v17
	global_store_dwordx2 v198, v[18:19], s[0:1]
	v_pk_mul_f32 v[18:19], v[140:141], v[28:29]
	v_pk_mul_f32 v[16:17], v[142:143], v[30:31]
	v_cvt_pk_bf16_f32 v18, v18, v19
	s_nop 0
	v_cvt_pk_bf16_f32 v19, v16, v17
	global_store_dwordx2 v197, v[18:19], s[0:1]
	v_pk_mul_f32 v[18:19], v[148:149], v[56:57]
	v_pk_mul_f32 v[16:17], v[150:151], v[58:59]
	v_cvt_pk_bf16_f32 v18, v18, v19
	s_nop 0
	v_cvt_pk_bf16_f32 v19, v16, v17
	global_store_dwordx2 v196, v[18:19], s[0:1]
	v_pk_mul_f32 v[18:19], v[152:153], v[36:37]
	v_pk_mul_f32 v[16:17], v[154:155], v[38:39]
	v_cvt_pk_bf16_f32 v18, v18, v19
	s_nop 0
	v_cvt_pk_bf16_f32 v19, v16, v17
	global_store_dwordx2 v195, v[18:19], s[0:1]
	v_pk_mul_f32 v[18:19], v[174:175], v[64:65]
	v_pk_mul_f32 v[16:17], v[176:177], v[66:67]
	v_cvt_pk_bf16_f32 v18, v18, v19
	s_nop 0
	v_cvt_pk_bf16_f32 v19, v16, v17
	global_store_dwordx2 v194, v[18:19], s[0:1]
	v_pk_mul_f32 v[18:19], v[178:179], v[52:53]
	v_pk_mul_f32 v[16:17], v[180:181], v[54:55]
	v_cvt_pk_bf16_f32 v18, v18, v19
	s_nop 0
	v_cvt_pk_bf16_f32 v19, v16, v17
	global_store_dwordx2 v193, v[18:19], s[0:1]
	v_pk_mul_f32 v[18:19], v[172:173], v[68:69]
	v_pk_mul_f32 v[16:17], v[182:183], v[70:71]
	v_cvt_pk_bf16_f32 v18, v18, v19
	s_nop 0
	v_cvt_pk_bf16_f32 v19, v16, v17
	global_store_dwordx2 v192, v[18:19], s[0:1]
	v_pk_mul_f32 v[18:19], v[170:171], v[60:61]
	v_pk_mul_f32 v[16:17], v[184:185], v[62:63]
	v_cvt_pk_bf16_f32 v18, v18, v19
	s_nop 0
	v_cvt_pk_bf16_f32 v19, v16, v17
	global_store_dwordx2 v191, v[18:19], s[0:1]
	v_pk_mul_f32 v[18:19], v[116:117], v[72:73]
	v_pk_mul_f32 v[16:17], v[118:119], v[74:75]
	v_cvt_pk_bf16_f32 v18, v18, v19
	s_nop 0
	v_cvt_pk_bf16_f32 v19, v16, v17
	global_store_dwordx2 v190, v[18:19], s[0:1]
	v_pk_mul_f32 v[18:19], v[144:145], v[44:45]
	v_pk_mul_f32 v[16:17], v[146:147], v[46:47]
	v_cvt_pk_bf16_f32 v18, v18, v19
	s_nop 0
	v_cvt_pk_bf16_f32 v19, v16, v17
	global_store_dwordx2 v189, v[18:19], s[0:1]
	v_pk_mul_f32 v[18:19], v[76:77], v[48:49]
	v_pk_mul_f32 v[16:17], v[78:79], v[50:51]
	v_cvt_pk_bf16_f32 v18, v18, v19
	s_nop 0
	v_cvt_pk_bf16_f32 v19, v16, v17
	global_store_dwordx2 v188, v[18:19], s[0:1]
	v_pk_mul_f32 v[18:19], v[80:81], v[20:21]
	v_pk_mul_f32 v[16:17], v[82:83], v[22:23]
	v_cvt_pk_bf16_f32 v18, v18, v19
	s_nop 0
	v_cvt_pk_bf16_f32 v19, v16, v17
	global_store_dwordx2 v187, v[18:19], s[0:1]
	v_cvt_pk_bf16_f32 v4, v4, v5
	v_cvt_pk_bf16_f32 v5, v6, v7
	global_store_dwordx2 v186, v[4:5], s[0:1]
	v_cvt_pk_bf16_f32 v0, v0, v1
	v_cvt_pk_bf16_f32 v1, v2, v3
	global_store_dwordx2 v160, v[0:1], s[0:1]
	s_branch .LBB0_357
